# FF2 owner-epilogue output stores (out, XG, XG8) carry the nt hint so the lines leave L2 early and the barrier's L2 write-back is shorter
# speedup vs baseline: 1.0045x; 1.0045x over previous
.Lfq_LBB0_1423:
	v_lshlrev_b32_e32 v203, 12, v204
	v_lshl_add_u32 v203, v200, 2, v203
	v_lshlrev_b32_e32 v205, 2, v194
	s_cmp_eq_u32 s30, 1
	s_cbranch_scc1 .Lfq_np1
	s_cmp_eq_u32 s30, 2
	s_cbranch_scc1 .Lfq_np2
	s_add_u32 s42, s62, 0x0
	s_addc_u32 s43, s63, 0
	global_load_dwordx4 v[160:163], v205, s[42:43] sc0 sc1
	s_add_u32 s98, s62, 0x1000
	s_addc_u32 s99, s63, 0
	global_load_dwordx4 v[164:167], v205, s[98:99] sc0 sc1
	s_add_u32 s42, s62, 0x400
	s_addc_u32 s43, s63, 0
	global_load_dwordx4 v[168:171], v205, s[42:43] sc0 sc1
	s_add_u32 s98, s62, 0x1400
	s_addc_u32 s99, s63, 0
	global_load_dwordx4 v[172:175], v205, s[98:99] sc0 sc1
	s_add_u32 s42, s62, 0x800
	s_addc_u32 s43, s63, 0
	global_load_dwordx4 v[176:179], v205, s[42:43] sc0 sc1
	s_add_u32 s98, s62, 0x1800
	s_addc_u32 s99, s63, 0
	global_load_dwordx4 v[180:183], v205, s[98:99] sc0 sc1
	s_add_u32 s42, s62, 0xc00
	s_addc_u32 s43, s63, 0
	global_load_dwordx4 v[206:209], v205, s[42:43] sc0 sc1
	s_add_u32 s98, s62, 0x1c00
	s_addc_u32 s99, s63, 0
	global_load_dwordx4 v[210:213], v205, s[98:99] sc0 sc1
	s_add_u32 s42, s62, 0x2000
	s_addc_u32 s43, s63, 0
	global_load_dwordx4 v[236:239], v205, s[42:43] sc0 sc1
	s_waitcnt vmcnt(8)
	v_lshlrev_b32_e32 v240, 16, v160
	v_and_b32_e32 v241, 0xffff0000, v160
	v_pk_add_f32 v[124:125], v[124:125], v[240:241]
	v_lshlrev_b32_e32 v240, 16, v161
	v_and_b32_e32 v241, 0xffff0000, v161
	v_pk_add_f32 v[126:127], v[126:127], v[240:241]
	v_lshlrev_b32_e32 v240, 16, v162
	v_and_b32_e32 v241, 0xffff0000, v162
	v_pk_add_f32 v[120:121], v[120:121], v[240:241]
	v_lshlrev_b32_e32 v240, 16, v163
	v_and_b32_e32 v241, 0xffff0000, v163
	v_pk_add_f32 v[122:123], v[122:123], v[240:241]
	s_add_u32 s98, s62, 0x3000
	s_addc_u32 s99, s63, 0
	global_load_dwordx4 v[160:163], v205, s[98:99] sc0 sc1
	s_waitcnt vmcnt(8)
	v_lshlrev_b32_e32 v240, 16, v164
	v_and_b32_e32 v241, 0xffff0000, v164
	v_pk_add_f32 v[92:93], v[92:93], v[240:241]
	v_lshlrev_b32_e32 v240, 16, v165
	v_and_b32_e32 v241, 0xffff0000, v165
	v_pk_add_f32 v[94:95], v[94:95], v[240:241]
	v_lshlrev_b32_e32 v240, 16, v166
	v_and_b32_e32 v241, 0xffff0000, v166
	v_pk_add_f32 v[88:89], v[88:89], v[240:241]
	v_lshlrev_b32_e32 v240, 16, v167
	v_and_b32_e32 v241, 0xffff0000, v167
	v_pk_add_f32 v[90:91], v[90:91], v[240:241]
	s_add_u32 s42, s62, 0x2400
	s_addc_u32 s43, s63, 0
	global_load_dwordx4 v[164:167], v205, s[42:43] sc0 sc1
	s_waitcnt vmcnt(8)
	v_lshlrev_b32_e32 v240, 16, v168
	v_and_b32_e32 v241, 0xffff0000, v168
	v_pk_add_f32 v[116:117], v[116:117], v[240:241]
	v_lshlrev_b32_e32 v240, 16, v169
	v_and_b32_e32 v241, 0xffff0000, v169
	v_pk_add_f32 v[118:119], v[118:119], v[240:241]
	v_lshlrev_b32_e32 v240, 16, v170
	v_and_b32_e32 v241, 0xffff0000, v170
	v_pk_add_f32 v[112:113], v[112:113], v[240:241]
	v_lshlrev_b32_e32 v240, 16, v171
	v_and_b32_e32 v241, 0xffff0000, v171
	v_pk_add_f32 v[114:115], v[114:115], v[240:241]
	s_add_u32 s98, s62, 0x3400
	s_addc_u32 s99, s63, 0
	global_load_dwordx4 v[168:171], v205, s[98:99] sc0 sc1
	s_waitcnt vmcnt(8)
	v_lshlrev_b32_e32 v240, 16, v172
	v_and_b32_e32 v241, 0xffff0000, v172
	v_pk_add_f32 v[84:85], v[84:85], v[240:241]
	v_lshlrev_b32_e32 v240, 16, v173
	v_and_b32_e32 v241, 0xffff0000, v173
	v_pk_add_f32 v[86:87], v[86:87], v[240:241]
	v_lshlrev_b32_e32 v240, 16, v174
	v_and_b32_e32 v241, 0xffff0000, v174
	v_pk_add_f32 v[80:81], v[80:81], v[240:241]
	v_lshlrev_b32_e32 v240, 16, v175
	v_and_b32_e32 v241, 0xffff0000, v175
	v_pk_add_f32 v[82:83], v[82:83], v[240:241]
	s_add_u32 s42, s62, 0x2800
	s_addc_u32 s43, s63, 0
	global_load_dwordx4 v[172:175], v205, s[42:43] sc0 sc1
	s_waitcnt vmcnt(8)
	v_lshlrev_b32_e32 v240, 16, v176
	v_and_b32_e32 v241, 0xffff0000, v176
	v_pk_add_f32 v[108:109], v[108:109], v[240:241]
	v_lshlrev_b32_e32 v240, 16, v177
	v_and_b32_e32 v241, 0xffff0000, v177
	v_pk_add_f32 v[110:111], v[110:111], v[240:241]
	v_lshlrev_b32_e32 v240, 16, v178
	v_and_b32_e32 v241, 0xffff0000, v178
	v_pk_add_f32 v[104:105], v[104:105], v[240:241]
	v_lshlrev_b32_e32 v240, 16, v179
	v_and_b32_e32 v241, 0xffff0000, v179
	v_pk_add_f32 v[106:107], v[106:107], v[240:241]
	s_add_u32 s98, s62, 0x3800
	s_addc_u32 s99, s63, 0
	global_load_dwordx4 v[176:179], v205, s[98:99] sc0 sc1
	s_waitcnt vmcnt(8)
	v_lshlrev_b32_e32 v240, 16, v180
	v_and_b32_e32 v241, 0xffff0000, v180
	v_pk_add_f32 v[76:77], v[76:77], v[240:241]
	v_lshlrev_b32_e32 v240, 16, v181
	v_and_b32_e32 v241, 0xffff0000, v181
	v_pk_add_f32 v[78:79], v[78:79], v[240:241]
	v_lshlrev_b32_e32 v240, 16, v182
	v_and_b32_e32 v241, 0xffff0000, v182
	v_pk_add_f32 v[72:73], v[72:73], v[240:241]
	v_lshlrev_b32_e32 v240, 16, v183
	v_and_b32_e32 v241, 0xffff0000, v183
	v_pk_add_f32 v[74:75], v[74:75], v[240:241]
	s_add_u32 s42, s62, 0x2c00
	s_addc_u32 s43, s63, 0
	global_load_dwordx4 v[180:183], v205, s[42:43] sc0 sc1
	s_waitcnt vmcnt(8)
	v_lshlrev_b32_e32 v240, 16, v206
	v_and_b32_e32 v241, 0xffff0000, v206
	v_pk_add_f32 v[100:101], v[100:101], v[240:241]
	v_lshlrev_b32_e32 v240, 16, v207
	v_and_b32_e32 v241, 0xffff0000, v207
	v_pk_add_f32 v[102:103], v[102:103], v[240:241]
	v_lshlrev_b32_e32 v240, 16, v208
	v_and_b32_e32 v241, 0xffff0000, v208
	v_pk_add_f32 v[96:97], v[96:97], v[240:241]
	v_lshlrev_b32_e32 v240, 16, v209
	v_and_b32_e32 v241, 0xffff0000, v209
	v_pk_add_f32 v[98:99], v[98:99], v[240:241]
	s_add_u32 s98, s62, 0x3c00
	s_addc_u32 s99, s63, 0
	global_load_dwordx4 v[206:209], v205, s[98:99] sc0 sc1
	s_waitcnt vmcnt(8)
	v_lshlrev_b32_e32 v240, 16, v210
	v_and_b32_e32 v241, 0xffff0000, v210
	v_pk_add_f32 v[68:69], v[68:69], v[240:241]
	v_lshlrev_b32_e32 v240, 16, v211
	v_and_b32_e32 v241, 0xffff0000, v211
	v_pk_add_f32 v[70:71], v[70:71], v[240:241]
	v_lshlrev_b32_e32 v240, 16, v212
	v_and_b32_e32 v241, 0xffff0000, v212
	v_pk_add_f32 v[64:65], v[64:65], v[240:241]
	v_lshlrev_b32_e32 v240, 16, v213
	v_and_b32_e32 v241, 0xffff0000, v213
	v_pk_add_f32 v[66:67], v[66:67], v[240:241]
	s_add_u32 s42, s62, 0x20000
	s_addc_u32 s43, s63, 0
	global_load_dwordx4 v[210:213], v205, s[42:43] sc0 sc1
	s_waitcnt vmcnt(8)
	v_lshlrev_b32_e32 v240, 16, v236
	v_and_b32_e32 v241, 0xffff0000, v236
	v_pk_add_f32 v[60:61], v[60:61], v[240:241]
	v_lshlrev_b32_e32 v240, 16, v237
	v_and_b32_e32 v241, 0xffff0000, v237
	v_pk_add_f32 v[62:63], v[62:63], v[240:241]
	v_lshlrev_b32_e32 v240, 16, v238
	v_and_b32_e32 v241, 0xffff0000, v238
	v_pk_add_f32 v[56:57], v[56:57], v[240:241]
	v_lshlrev_b32_e32 v240, 16, v239
	v_and_b32_e32 v241, 0xffff0000, v239
	v_pk_add_f32 v[58:59], v[58:59], v[240:241]
	s_add_u32 s98, s62, 0x21000
	s_addc_u32 s99, s63, 0
	global_load_dwordx4 v[236:239], v205, s[98:99] sc0 sc1
	s_waitcnt vmcnt(8)
	v_lshlrev_b32_e32 v240, 16, v160
	v_and_b32_e32 v241, 0xffff0000, v160
	v_pk_add_f32 v[28:29], v[28:29], v[240:241]
	v_lshlrev_b32_e32 v240, 16, v161
	v_and_b32_e32 v241, 0xffff0000, v161
	v_pk_add_f32 v[30:31], v[30:31], v[240:241]
	v_lshlrev_b32_e32 v240, 16, v162
	v_and_b32_e32 v241, 0xffff0000, v162
	v_pk_add_f32 v[24:25], v[24:25], v[240:241]
	v_lshlrev_b32_e32 v240, 16, v163
	v_and_b32_e32 v241, 0xffff0000, v163
	v_pk_add_f32 v[26:27], v[26:27], v[240:241]
	s_add_u32 s42, s62, 0x20400
	s_addc_u32 s43, s63, 0
	global_load_dwordx4 v[160:163], v205, s[42:43] sc0 sc1
	s_waitcnt vmcnt(8)
	v_lshlrev_b32_e32 v240, 16, v164
	v_and_b32_e32 v241, 0xffff0000, v164
	v_pk_add_f32 v[52:53], v[52:53], v[240:241]
	v_lshlrev_b32_e32 v240, 16, v165
	v_and_b32_e32 v241, 0xffff0000, v165
	v_pk_add_f32 v[54:55], v[54:55], v[240:241]
	v_lshlrev_b32_e32 v240, 16, v166
	v_and_b32_e32 v241, 0xffff0000, v166
	v_pk_add_f32 v[48:49], v[48:49], v[240:241]
	v_lshlrev_b32_e32 v240, 16, v167
	v_and_b32_e32 v241, 0xffff0000, v167
	v_pk_add_f32 v[50:51], v[50:51], v[240:241]
	s_add_u32 s98, s62, 0x21400
	s_addc_u32 s99, s63, 0
	global_load_dwordx4 v[164:167], v205, s[98:99] sc0 sc1
	s_waitcnt vmcnt(8)
	v_lshlrev_b32_e32 v240, 16, v168
	v_and_b32_e32 v241, 0xffff0000, v168
	v_pk_add_f32 v[20:21], v[20:21], v[240:241]
	v_lshlrev_b32_e32 v240, 16, v169
	v_and_b32_e32 v241, 0xffff0000, v169
	v_pk_add_f32 v[22:23], v[22:23], v[240:241]
	v_lshlrev_b32_e32 v240, 16, v170
	v_and_b32_e32 v241, 0xffff0000, v170
	v_pk_add_f32 v[16:17], v[16:17], v[240:241]
	v_lshlrev_b32_e32 v240, 16, v171
	v_and_b32_e32 v241, 0xffff0000, v171
	v_pk_add_f32 v[18:19], v[18:19], v[240:241]
	s_add_u32 s42, s62, 0x20800
	s_addc_u32 s43, s63, 0
	global_load_dwordx4 v[168:171], v205, s[42:43] sc0 sc1
	s_waitcnt vmcnt(8)
	v_lshlrev_b32_e32 v240, 16, v172
	v_and_b32_e32 v241, 0xffff0000, v172
	v_pk_add_f32 v[44:45], v[44:45], v[240:241]
	v_lshlrev_b32_e32 v240, 16, v173
	v_and_b32_e32 v241, 0xffff0000, v173
	v_pk_add_f32 v[46:47], v[46:47], v[240:241]
	v_lshlrev_b32_e32 v240, 16, v174
	v_and_b32_e32 v241, 0xffff0000, v174
	v_pk_add_f32 v[40:41], v[40:41], v[240:241]
	v_lshlrev_b32_e32 v240, 16, v175
	v_and_b32_e32 v241, 0xffff0000, v175
	v_pk_add_f32 v[42:43], v[42:43], v[240:241]
	s_add_u32 s98, s62, 0x21800
	s_addc_u32 s99, s63, 0
	global_load_dwordx4 v[172:175], v205, s[98:99] sc0 sc1
	s_waitcnt vmcnt(8)
	v_lshlrev_b32_e32 v240, 16, v176
	v_and_b32_e32 v241, 0xffff0000, v176
	v_pk_add_f32 v[12:13], v[12:13], v[240:241]
	v_lshlrev_b32_e32 v240, 16, v177
	v_and_b32_e32 v241, 0xffff0000, v177
	v_pk_add_f32 v[14:15], v[14:15], v[240:241]
	v_lshlrev_b32_e32 v240, 16, v178
	v_and_b32_e32 v241, 0xffff0000, v178
	v_pk_add_f32 v[8:9], v[8:9], v[240:241]
	v_lshlrev_b32_e32 v240, 16, v179
	v_and_b32_e32 v241, 0xffff0000, v179
	v_pk_add_f32 v[10:11], v[10:11], v[240:241]
	s_add_u32 s42, s62, 0x20c00
	s_addc_u32 s43, s63, 0
	global_load_dwordx4 v[176:179], v205, s[42:43] sc0 sc1
	s_waitcnt vmcnt(8)
	v_lshlrev_b32_e32 v240, 16, v180
	v_and_b32_e32 v241, 0xffff0000, v180
	v_pk_add_f32 v[36:37], v[36:37], v[240:241]
	v_lshlrev_b32_e32 v240, 16, v181
	v_and_b32_e32 v241, 0xffff0000, v181
	v_pk_add_f32 v[38:39], v[38:39], v[240:241]
	v_lshlrev_b32_e32 v240, 16, v182
	v_and_b32_e32 v241, 0xffff0000, v182
	v_pk_add_f32 v[32:33], v[32:33], v[240:241]
	v_lshlrev_b32_e32 v240, 16, v183
	v_and_b32_e32 v241, 0xffff0000, v183
	v_pk_add_f32 v[34:35], v[34:35], v[240:241]
	s_add_u32 s98, s62, 0x21c00
	s_addc_u32 s99, s63, 0
	global_load_dwordx4 v[180:183], v205, s[98:99] sc0 sc1
	s_waitcnt vmcnt(8)
	v_lshlrev_b32_e32 v240, 16, v206
	v_and_b32_e32 v241, 0xffff0000, v206
	v_pk_add_f32 v[4:5], v[4:5], v[240:241]
	v_lshlrev_b32_e32 v240, 16, v207
	v_and_b32_e32 v241, 0xffff0000, v207
	v_pk_add_f32 v[6:7], v[6:7], v[240:241]
	v_lshlrev_b32_e32 v240, 16, v208
	v_and_b32_e32 v241, 0xffff0000, v208
	v_pk_add_f32 v[0:1], v[0:1], v[240:241]
	v_lshlrev_b32_e32 v240, 16, v209
	v_and_b32_e32 v241, 0xffff0000, v209
	v_pk_add_f32 v[2:3], v[2:3], v[240:241]
	s_add_u32 s42, s62, 0x22000
	s_addc_u32 s43, s63, 0
	global_load_dwordx4 v[206:209], v205, s[42:43] sc0 sc1
	s_waitcnt vmcnt(8)
	v_lshlrev_b32_e32 v240, 16, v210
	v_and_b32_e32 v241, 0xffff0000, v210
	v_pk_add_f32 v[124:125], v[124:125], v[240:241]
	v_lshlrev_b32_e32 v240, 16, v211
	v_and_b32_e32 v241, 0xffff0000, v211
	v_pk_add_f32 v[126:127], v[126:127], v[240:241]
	v_lshlrev_b32_e32 v240, 16, v212
	v_and_b32_e32 v241, 0xffff0000, v212
	v_pk_add_f32 v[120:121], v[120:121], v[240:241]
	v_lshlrev_b32_e32 v240, 16, v213
	v_and_b32_e32 v241, 0xffff0000, v213
	v_pk_add_f32 v[122:123], v[122:123], v[240:241]
	s_add_u32 s98, s62, 0x23000
	s_addc_u32 s99, s63, 0
	global_load_dwordx4 v[210:213], v205, s[98:99] sc0 sc1
	s_waitcnt vmcnt(8)
	v_lshlrev_b32_e32 v240, 16, v236
	v_and_b32_e32 v241, 0xffff0000, v236
	v_pk_add_f32 v[92:93], v[92:93], v[240:241]
	v_lshlrev_b32_e32 v240, 16, v237
	v_and_b32_e32 v241, 0xffff0000, v237
	v_pk_add_f32 v[94:95], v[94:95], v[240:241]
	v_lshlrev_b32_e32 v240, 16, v238
	v_and_b32_e32 v241, 0xffff0000, v238
	v_pk_add_f32 v[88:89], v[88:89], v[240:241]
	v_lshlrev_b32_e32 v240, 16, v239
	v_and_b32_e32 v241, 0xffff0000, v239
	v_pk_add_f32 v[90:91], v[90:91], v[240:241]
	s_add_u32 s42, s62, 0x22400
	s_addc_u32 s43, s63, 0
	global_load_dwordx4 v[236:239], v205, s[42:43] sc0 sc1
	s_waitcnt vmcnt(8)
	v_lshlrev_b32_e32 v240, 16, v160
	v_and_b32_e32 v241, 0xffff0000, v160
	v_pk_add_f32 v[116:117], v[116:117], v[240:241]
	v_lshlrev_b32_e32 v240, 16, v161
	v_and_b32_e32 v241, 0xffff0000, v161
	v_pk_add_f32 v[118:119], v[118:119], v[240:241]
	v_lshlrev_b32_e32 v240, 16, v162
	v_and_b32_e32 v241, 0xffff0000, v162
	v_pk_add_f32 v[112:113], v[112:113], v[240:241]
	v_lshlrev_b32_e32 v240, 16, v163
	v_and_b32_e32 v241, 0xffff0000, v163
	v_pk_add_f32 v[114:115], v[114:115], v[240:241]
	s_add_u32 s98, s62, 0x23400
	s_addc_u32 s99, s63, 0
	global_load_dwordx4 v[160:163], v205, s[98:99] sc0 sc1
	s_waitcnt vmcnt(8)
	v_lshlrev_b32_e32 v240, 16, v164
	v_and_b32_e32 v241, 0xffff0000, v164
	v_pk_add_f32 v[84:85], v[84:85], v[240:241]
	v_lshlrev_b32_e32 v240, 16, v165
	v_and_b32_e32 v241, 0xffff0000, v165
	v_pk_add_f32 v[86:87], v[86:87], v[240:241]
	v_lshlrev_b32_e32 v240, 16, v166
	v_and_b32_e32 v241, 0xffff0000, v166
	v_pk_add_f32 v[80:81], v[80:81], v[240:241]
	v_lshlrev_b32_e32 v240, 16, v167
	v_and_b32_e32 v241, 0xffff0000, v167
	v_pk_add_f32 v[82:83], v[82:83], v[240:241]
	s_add_u32 s42, s62, 0x22800
	s_addc_u32 s43, s63, 0
	global_load_dwordx4 v[164:167], v205, s[42:43] sc0 sc1
	s_waitcnt vmcnt(8)
	v_lshlrev_b32_e32 v240, 16, v168
	v_and_b32_e32 v241, 0xffff0000, v168
	v_pk_add_f32 v[108:109], v[108:109], v[240:241]
	v_lshlrev_b32_e32 v240, 16, v169
	v_and_b32_e32 v241, 0xffff0000, v169
	v_pk_add_f32 v[110:111], v[110:111], v[240:241]
	v_lshlrev_b32_e32 v240, 16, v170
	v_and_b32_e32 v241, 0xffff0000, v170
	v_pk_add_f32 v[104:105], v[104:105], v[240:241]
	v_lshlrev_b32_e32 v240, 16, v171
	v_and_b32_e32 v241, 0xffff0000, v171
	v_pk_add_f32 v[106:107], v[106:107], v[240:241]
	s_add_u32 s98, s62, 0x23800
	s_addc_u32 s99, s63, 0
	global_load_dwordx4 v[168:171], v205, s[98:99] sc0 sc1
	s_waitcnt vmcnt(8)
	v_lshlrev_b32_e32 v240, 16, v172
	v_and_b32_e32 v241, 0xffff0000, v172
	v_pk_add_f32 v[76:77], v[76:77], v[240:241]
	v_lshlrev_b32_e32 v240, 16, v173
	v_and_b32_e32 v241, 0xffff0000, v173
	v_pk_add_f32 v[78:79], v[78:79], v[240:241]
	v_lshlrev_b32_e32 v240, 16, v174
	v_and_b32_e32 v241, 0xffff0000, v174
	v_pk_add_f32 v[72:73], v[72:73], v[240:241]
	v_lshlrev_b32_e32 v240, 16, v175
	v_and_b32_e32 v241, 0xffff0000, v175
	v_pk_add_f32 v[74:75], v[74:75], v[240:241]
	s_add_u32 s42, s62, 0x22c00
	s_addc_u32 s43, s63, 0
	global_load_dwordx4 v[172:175], v205, s[42:43] sc0 sc1
	s_waitcnt vmcnt(8)
	v_lshlrev_b32_e32 v240, 16, v176
	v_and_b32_e32 v241, 0xffff0000, v176
	v_pk_add_f32 v[100:101], v[100:101], v[240:241]
	v_lshlrev_b32_e32 v240, 16, v177
	v_and_b32_e32 v241, 0xffff0000, v177
	v_pk_add_f32 v[102:103], v[102:103], v[240:241]
	v_lshlrev_b32_e32 v240, 16, v178
	v_and_b32_e32 v241, 0xffff0000, v178
	v_pk_add_f32 v[96:97], v[96:97], v[240:241]
	v_lshlrev_b32_e32 v240, 16, v179
	v_and_b32_e32 v241, 0xffff0000, v179
	v_pk_add_f32 v[98:99], v[98:99], v[240:241]
	s_add_u32 s98, s62, 0x23c00
	s_addc_u32 s99, s63, 0
	global_load_dwordx4 v[176:179], v205, s[98:99] sc0 sc1
	s_waitcnt vmcnt(8)
	v_lshlrev_b32_e32 v240, 16, v180
	v_and_b32_e32 v241, 0xffff0000, v180
	v_pk_add_f32 v[68:69], v[68:69], v[240:241]
	v_lshlrev_b32_e32 v240, 16, v181
	v_and_b32_e32 v241, 0xffff0000, v181
	v_pk_add_f32 v[70:71], v[70:71], v[240:241]
	v_lshlrev_b32_e32 v240, 16, v182
	v_and_b32_e32 v241, 0xffff0000, v182
	v_pk_add_f32 v[64:65], v[64:65], v[240:241]
	v_lshlrev_b32_e32 v240, 16, v183
	v_and_b32_e32 v241, 0xffff0000, v183
	v_pk_add_f32 v[66:67], v[66:67], v[240:241]
	s_add_u32 s42, s62, 0x40000
	s_addc_u32 s43, s63, 0
	global_load_dwordx4 v[180:183], v205, s[42:43] sc0 sc1
	s_waitcnt vmcnt(8)
	v_lshlrev_b32_e32 v240, 16, v206
	v_and_b32_e32 v241, 0xffff0000, v206
	v_pk_add_f32 v[60:61], v[60:61], v[240:241]
	v_lshlrev_b32_e32 v240, 16, v207
	v_and_b32_e32 v241, 0xffff0000, v207
	v_pk_add_f32 v[62:63], v[62:63], v[240:241]
	v_lshlrev_b32_e32 v240, 16, v208
	v_and_b32_e32 v241, 0xffff0000, v208
	v_pk_add_f32 v[56:57], v[56:57], v[240:241]
	v_lshlrev_b32_e32 v240, 16, v209
	v_and_b32_e32 v241, 0xffff0000, v209
	v_pk_add_f32 v[58:59], v[58:59], v[240:241]
	s_add_u32 s98, s62, 0x41000
	s_addc_u32 s99, s63, 0
	global_load_dwordx4 v[206:209], v205, s[98:99] sc0 sc1
	s_waitcnt vmcnt(8)
	v_lshlrev_b32_e32 v240, 16, v210
	v_and_b32_e32 v241, 0xffff0000, v210
	v_pk_add_f32 v[28:29], v[28:29], v[240:241]
	v_lshlrev_b32_e32 v240, 16, v211
	v_and_b32_e32 v241, 0xffff0000, v211
	v_pk_add_f32 v[30:31], v[30:31], v[240:241]
	v_lshlrev_b32_e32 v240, 16, v212
	v_and_b32_e32 v241, 0xffff0000, v212
	v_pk_add_f32 v[24:25], v[24:25], v[240:241]
	v_lshlrev_b32_e32 v240, 16, v213
	v_and_b32_e32 v241, 0xffff0000, v213
	v_pk_add_f32 v[26:27], v[26:27], v[240:241]
	s_add_u32 s42, s62, 0x40400
	s_addc_u32 s43, s63, 0
	global_load_dwordx4 v[210:213], v205, s[42:43] sc0 sc1
	s_waitcnt vmcnt(8)
	v_lshlrev_b32_e32 v240, 16, v236
	v_and_b32_e32 v241, 0xffff0000, v236
	v_pk_add_f32 v[52:53], v[52:53], v[240:241]
	v_lshlrev_b32_e32 v240, 16, v237
	v_and_b32_e32 v241, 0xffff0000, v237
	v_pk_add_f32 v[54:55], v[54:55], v[240:241]
	v_lshlrev_b32_e32 v240, 16, v238
	v_and_b32_e32 v241, 0xffff0000, v238
	v_pk_add_f32 v[48:49], v[48:49], v[240:241]
	v_lshlrev_b32_e32 v240, 16, v239
	v_and_b32_e32 v241, 0xffff0000, v239
	v_pk_add_f32 v[50:51], v[50:51], v[240:241]
	s_add_u32 s98, s62, 0x41400
	s_addc_u32 s99, s63, 0
	global_load_dwordx4 v[236:239], v205, s[98:99] sc0 sc1
	s_waitcnt vmcnt(8)
	v_lshlrev_b32_e32 v240, 16, v160
	v_and_b32_e32 v241, 0xffff0000, v160
	v_pk_add_f32 v[20:21], v[20:21], v[240:241]
	v_lshlrev_b32_e32 v240, 16, v161
	v_and_b32_e32 v241, 0xffff0000, v161
	v_pk_add_f32 v[22:23], v[22:23], v[240:241]
	v_lshlrev_b32_e32 v240, 16, v162
	v_and_b32_e32 v241, 0xffff0000, v162
	v_pk_add_f32 v[16:17], v[16:17], v[240:241]
	v_lshlrev_b32_e32 v240, 16, v163
	v_and_b32_e32 v241, 0xffff0000, v163
	v_pk_add_f32 v[18:19], v[18:19], v[240:241]
	s_add_u32 s42, s62, 0x40800
	s_addc_u32 s43, s63, 0
	global_load_dwordx4 v[160:163], v205, s[42:43] sc0 sc1
	s_waitcnt vmcnt(8)
	v_lshlrev_b32_e32 v240, 16, v164
	v_and_b32_e32 v241, 0xffff0000, v164
	v_pk_add_f32 v[44:45], v[44:45], v[240:241]
	v_lshlrev_b32_e32 v240, 16, v165
	v_and_b32_e32 v241, 0xffff0000, v165
	v_pk_add_f32 v[46:47], v[46:47], v[240:241]
	v_lshlrev_b32_e32 v240, 16, v166
	v_and_b32_e32 v241, 0xffff0000, v166
	v_pk_add_f32 v[40:41], v[40:41], v[240:241]
	v_lshlrev_b32_e32 v240, 16, v167
	v_and_b32_e32 v241, 0xffff0000, v167
	v_pk_add_f32 v[42:43], v[42:43], v[240:241]
	s_add_u32 s98, s62, 0x41800
	s_addc_u32 s99, s63, 0
	global_load_dwordx4 v[164:167], v205, s[98:99] sc0 sc1
	s_waitcnt vmcnt(8)
	v_lshlrev_b32_e32 v240, 16, v168
	v_and_b32_e32 v241, 0xffff0000, v168
	v_pk_add_f32 v[12:13], v[12:13], v[240:241]
	v_lshlrev_b32_e32 v240, 16, v169
	v_and_b32_e32 v241, 0xffff0000, v169
	v_pk_add_f32 v[14:15], v[14:15], v[240:241]
	v_lshlrev_b32_e32 v240, 16, v170
	v_and_b32_e32 v241, 0xffff0000, v170
	v_pk_add_f32 v[8:9], v[8:9], v[240:241]
	v_lshlrev_b32_e32 v240, 16, v171
	v_and_b32_e32 v241, 0xffff0000, v171
	v_pk_add_f32 v[10:11], v[10:11], v[240:241]
	s_add_u32 s42, s62, 0x40c00
	s_addc_u32 s43, s63, 0
	global_load_dwordx4 v[168:171], v205, s[42:43] sc0 sc1
	s_waitcnt vmcnt(8)
	v_lshlrev_b32_e32 v240, 16, v172
	v_and_b32_e32 v241, 0xffff0000, v172
	v_pk_add_f32 v[36:37], v[36:37], v[240:241]
	v_lshlrev_b32_e32 v240, 16, v173
	v_and_b32_e32 v241, 0xffff0000, v173
	v_pk_add_f32 v[38:39], v[38:39], v[240:241]
	v_lshlrev_b32_e32 v240, 16, v174
	v_and_b32_e32 v241, 0xffff0000, v174
	v_pk_add_f32 v[32:33], v[32:33], v[240:241]
	v_lshlrev_b32_e32 v240, 16, v175
	v_and_b32_e32 v241, 0xffff0000, v175
	v_pk_add_f32 v[34:35], v[34:35], v[240:241]
	s_add_u32 s98, s62, 0x41c00
	s_addc_u32 s99, s63, 0
	global_load_dwordx4 v[172:175], v205, s[98:99] sc0 sc1
	s_waitcnt vmcnt(8)
	v_lshlrev_b32_e32 v240, 16, v176
	v_and_b32_e32 v241, 0xffff0000, v176
	v_pk_add_f32 v[4:5], v[4:5], v[240:241]
	v_lshlrev_b32_e32 v240, 16, v177
	v_and_b32_e32 v241, 0xffff0000, v177
	v_pk_add_f32 v[6:7], v[6:7], v[240:241]
	v_lshlrev_b32_e32 v240, 16, v178
	v_and_b32_e32 v241, 0xffff0000, v178
	v_pk_add_f32 v[0:1], v[0:1], v[240:241]
	v_lshlrev_b32_e32 v240, 16, v179
	v_and_b32_e32 v241, 0xffff0000, v179
	v_pk_add_f32 v[2:3], v[2:3], v[240:241]
	s_add_u32 s42, s62, 0x42000
	s_addc_u32 s43, s63, 0
	global_load_dwordx4 v[176:179], v205, s[42:43] sc0 sc1
	s_waitcnt vmcnt(8)
	v_lshlrev_b32_e32 v240, 16, v180
	v_and_b32_e32 v241, 0xffff0000, v180
	v_pk_add_f32 v[124:125], v[124:125], v[240:241]
	v_lshlrev_b32_e32 v240, 16, v181
	v_and_b32_e32 v241, 0xffff0000, v181
	v_pk_add_f32 v[126:127], v[126:127], v[240:241]
	v_lshlrev_b32_e32 v240, 16, v182
	v_and_b32_e32 v241, 0xffff0000, v182
	v_pk_add_f32 v[120:121], v[120:121], v[240:241]
	v_lshlrev_b32_e32 v240, 16, v183
	v_and_b32_e32 v241, 0xffff0000, v183
	v_pk_add_f32 v[122:123], v[122:123], v[240:241]
	s_add_u32 s98, s62, 0x43000
	s_addc_u32 s99, s63, 0
	global_load_dwordx4 v[180:183], v205, s[98:99] sc0 sc1
	s_waitcnt vmcnt(8)
	v_lshlrev_b32_e32 v240, 16, v206
	v_and_b32_e32 v241, 0xffff0000, v206
	v_pk_add_f32 v[92:93], v[92:93], v[240:241]
	v_lshlrev_b32_e32 v240, 16, v207
	v_and_b32_e32 v241, 0xffff0000, v207
	v_pk_add_f32 v[94:95], v[94:95], v[240:241]
	v_lshlrev_b32_e32 v240, 16, v208
	v_and_b32_e32 v241, 0xffff0000, v208
	v_pk_add_f32 v[88:89], v[88:89], v[240:241]
	v_lshlrev_b32_e32 v240, 16, v209
	v_and_b32_e32 v241, 0xffff0000, v209
	v_pk_add_f32 v[90:91], v[90:91], v[240:241]
	s_add_u32 s42, s62, 0x42400
	s_addc_u32 s43, s63, 0
	global_load_dwordx4 v[206:209], v205, s[42:43] sc0 sc1
	s_waitcnt vmcnt(8)
	v_lshlrev_b32_e32 v240, 16, v210
	v_and_b32_e32 v241, 0xffff0000, v210
	v_pk_add_f32 v[116:117], v[116:117], v[240:241]
	v_lshlrev_b32_e32 v240, 16, v211
	v_and_b32_e32 v241, 0xffff0000, v211
	v_pk_add_f32 v[118:119], v[118:119], v[240:241]
	v_lshlrev_b32_e32 v240, 16, v212
	v_and_b32_e32 v241, 0xffff0000, v212
	v_pk_add_f32 v[112:113], v[112:113], v[240:241]
	v_lshlrev_b32_e32 v240, 16, v213
	v_and_b32_e32 v241, 0xffff0000, v213
	v_pk_add_f32 v[114:115], v[114:115], v[240:241]
	s_add_u32 s98, s62, 0x43400
	s_addc_u32 s99, s63, 0
	global_load_dwordx4 v[210:213], v205, s[98:99] sc0 sc1
	s_waitcnt vmcnt(8)
	v_lshlrev_b32_e32 v240, 16, v236
	v_and_b32_e32 v241, 0xffff0000, v236
	v_pk_add_f32 v[84:85], v[84:85], v[240:241]
	v_lshlrev_b32_e32 v240, 16, v237
	v_and_b32_e32 v241, 0xffff0000, v237
	v_pk_add_f32 v[86:87], v[86:87], v[240:241]
	v_lshlrev_b32_e32 v240, 16, v238
	v_and_b32_e32 v241, 0xffff0000, v238
	v_pk_add_f32 v[80:81], v[80:81], v[240:241]
	v_lshlrev_b32_e32 v240, 16, v239
	v_and_b32_e32 v241, 0xffff0000, v239
	v_pk_add_f32 v[82:83], v[82:83], v[240:241]
	s_add_u32 s42, s62, 0x42800
	s_addc_u32 s43, s63, 0
	global_load_dwordx4 v[236:239], v205, s[42:43] sc0 sc1
	s_waitcnt vmcnt(8)
	v_lshlrev_b32_e32 v240, 16, v160
	v_and_b32_e32 v241, 0xffff0000, v160
	v_pk_add_f32 v[108:109], v[108:109], v[240:241]
	v_lshlrev_b32_e32 v240, 16, v161
	v_and_b32_e32 v241, 0xffff0000, v161
	v_pk_add_f32 v[110:111], v[110:111], v[240:241]
	v_lshlrev_b32_e32 v240, 16, v162
	v_and_b32_e32 v241, 0xffff0000, v162
	v_pk_add_f32 v[104:105], v[104:105], v[240:241]
	v_lshlrev_b32_e32 v240, 16, v163
	v_and_b32_e32 v241, 0xffff0000, v163
	v_pk_add_f32 v[106:107], v[106:107], v[240:241]
	s_add_u32 s98, s62, 0x43800
	s_addc_u32 s99, s63, 0
	global_load_dwordx4 v[160:163], v205, s[98:99] sc0 sc1
	s_waitcnt vmcnt(8)
	v_lshlrev_b32_e32 v240, 16, v164
	v_and_b32_e32 v241, 0xffff0000, v164
	v_pk_add_f32 v[76:77], v[76:77], v[240:241]
	v_lshlrev_b32_e32 v240, 16, v165
	v_and_b32_e32 v241, 0xffff0000, v165
	v_pk_add_f32 v[78:79], v[78:79], v[240:241]
	v_lshlrev_b32_e32 v240, 16, v166
	v_and_b32_e32 v241, 0xffff0000, v166
	v_pk_add_f32 v[72:73], v[72:73], v[240:241]
	v_lshlrev_b32_e32 v240, 16, v167
	v_and_b32_e32 v241, 0xffff0000, v167
	v_pk_add_f32 v[74:75], v[74:75], v[240:241]
	s_add_u32 s42, s62, 0x42c00
	s_addc_u32 s43, s63, 0
	global_load_dwordx4 v[164:167], v205, s[42:43] sc0 sc1
	s_waitcnt vmcnt(8)
	v_lshlrev_b32_e32 v240, 16, v168
	v_and_b32_e32 v241, 0xffff0000, v168
	v_pk_add_f32 v[100:101], v[100:101], v[240:241]
	v_lshlrev_b32_e32 v240, 16, v169
	v_and_b32_e32 v241, 0xffff0000, v169
	v_pk_add_f32 v[102:103], v[102:103], v[240:241]
	v_lshlrev_b32_e32 v240, 16, v170
	v_and_b32_e32 v241, 0xffff0000, v170
	v_pk_add_f32 v[96:97], v[96:97], v[240:241]
	v_lshlrev_b32_e32 v240, 16, v171
	v_and_b32_e32 v241, 0xffff0000, v171
	v_pk_add_f32 v[98:99], v[98:99], v[240:241]
	s_add_u32 s98, s62, 0x43c00
	s_addc_u32 s99, s63, 0
	global_load_dwordx4 v[168:171], v205, s[98:99] sc0 sc1
	s_waitcnt vmcnt(8)
	v_lshlrev_b32_e32 v240, 16, v172
	v_and_b32_e32 v241, 0xffff0000, v172
	v_pk_add_f32 v[68:69], v[68:69], v[240:241]
	v_lshlrev_b32_e32 v240, 16, v173
	v_and_b32_e32 v241, 0xffff0000, v173
	v_pk_add_f32 v[70:71], v[70:71], v[240:241]
	v_lshlrev_b32_e32 v240, 16, v174
	v_and_b32_e32 v241, 0xffff0000, v174
	v_pk_add_f32 v[64:65], v[64:65], v[240:241]
	v_lshlrev_b32_e32 v240, 16, v175
	v_and_b32_e32 v241, 0xffff0000, v175
	v_pk_add_f32 v[66:67], v[66:67], v[240:241]
	s_add_u32 s42, s10, 0x0
	s_addc_u32 s43, s11, 0
	global_load_dwordx4 v[172:175], v203, s[42:43]
	s_waitcnt vmcnt(8)
	v_lshlrev_b32_e32 v240, 16, v176
	v_and_b32_e32 v241, 0xffff0000, v176
	v_pk_add_f32 v[60:61], v[60:61], v[240:241]
	v_lshlrev_b32_e32 v240, 16, v177
	v_and_b32_e32 v241, 0xffff0000, v177
	v_pk_add_f32 v[62:63], v[62:63], v[240:241]
	v_lshlrev_b32_e32 v240, 16, v178
	v_and_b32_e32 v241, 0xffff0000, v178
	v_pk_add_f32 v[56:57], v[56:57], v[240:241]
	v_lshlrev_b32_e32 v240, 16, v179
	v_and_b32_e32 v241, 0xffff0000, v179
	v_pk_add_f32 v[58:59], v[58:59], v[240:241]
	s_add_u32 s98, s10, 0x0
	s_addc_u32 s99, s11, 0
	global_load_dwordx4 v[176:179], v203, s[98:99] offset:16
	s_waitcnt vmcnt(8)
	v_lshlrev_b32_e32 v240, 16, v180
	v_and_b32_e32 v241, 0xffff0000, v180
	v_pk_add_f32 v[28:29], v[28:29], v[240:241]
	v_lshlrev_b32_e32 v240, 16, v181
	v_and_b32_e32 v241, 0xffff0000, v181
	v_pk_add_f32 v[30:31], v[30:31], v[240:241]
	v_lshlrev_b32_e32 v240, 16, v182
	v_and_b32_e32 v241, 0xffff0000, v182
	v_pk_add_f32 v[24:25], v[24:25], v[240:241]
	v_lshlrev_b32_e32 v240, 16, v183
	v_and_b32_e32 v241, 0xffff0000, v183
	v_pk_add_f32 v[26:27], v[26:27], v[240:241]
	s_add_u32 s42, s10, 0x200
	s_addc_u32 s43, s11, 0
	global_load_dwordx4 v[180:183], v203, s[42:43]
	s_waitcnt vmcnt(8)
	v_lshlrev_b32_e32 v240, 16, v206
	v_and_b32_e32 v241, 0xffff0000, v206
	v_pk_add_f32 v[52:53], v[52:53], v[240:241]
	v_lshlrev_b32_e32 v240, 16, v207
	v_and_b32_e32 v241, 0xffff0000, v207
	v_pk_add_f32 v[54:55], v[54:55], v[240:241]
	v_lshlrev_b32_e32 v240, 16, v208
	v_and_b32_e32 v241, 0xffff0000, v208
	v_pk_add_f32 v[48:49], v[48:49], v[240:241]
	v_lshlrev_b32_e32 v240, 16, v209
	v_and_b32_e32 v241, 0xffff0000, v209
	v_pk_add_f32 v[50:51], v[50:51], v[240:241]
	s_add_u32 s98, s10, 0x200
	s_addc_u32 s99, s11, 0
	global_load_dwordx4 v[206:209], v203, s[98:99] offset:16
	s_waitcnt vmcnt(8)
	v_lshlrev_b32_e32 v240, 16, v210
	v_and_b32_e32 v241, 0xffff0000, v210
	v_pk_add_f32 v[20:21], v[20:21], v[240:241]
	v_lshlrev_b32_e32 v240, 16, v211
	v_and_b32_e32 v241, 0xffff0000, v211
	v_pk_add_f32 v[22:23], v[22:23], v[240:241]
	v_lshlrev_b32_e32 v240, 16, v212
	v_and_b32_e32 v241, 0xffff0000, v212
	v_pk_add_f32 v[16:17], v[16:17], v[240:241]
	v_lshlrev_b32_e32 v240, 16, v213
	v_and_b32_e32 v241, 0xffff0000, v213
	v_pk_add_f32 v[18:19], v[18:19], v[240:241]
	s_add_u32 s42, s10, 0x10000
	s_addc_u32 s43, s11, 0
	global_load_dwordx4 v[210:213], v203, s[42:43]
	s_waitcnt vmcnt(8)
	v_lshlrev_b32_e32 v240, 16, v236
	v_and_b32_e32 v241, 0xffff0000, v236
	v_pk_add_f32 v[44:45], v[44:45], v[240:241]
	v_lshlrev_b32_e32 v240, 16, v237
	v_and_b32_e32 v241, 0xffff0000, v237
	v_pk_add_f32 v[46:47], v[46:47], v[240:241]
	v_lshlrev_b32_e32 v240, 16, v238
	v_and_b32_e32 v241, 0xffff0000, v238
	v_pk_add_f32 v[40:41], v[40:41], v[240:241]
	v_lshlrev_b32_e32 v240, 16, v239
	v_and_b32_e32 v241, 0xffff0000, v239
	v_pk_add_f32 v[42:43], v[42:43], v[240:241]
	s_add_u32 s98, s10, 0x10000
	s_addc_u32 s99, s11, 0
	global_load_dwordx4 v[236:239], v203, s[98:99] offset:16
	s_waitcnt vmcnt(8)
	v_lshlrev_b32_e32 v240, 16, v160
	v_and_b32_e32 v241, 0xffff0000, v160
	v_pk_add_f32 v[12:13], v[12:13], v[240:241]
	v_lshlrev_b32_e32 v240, 16, v161
	v_and_b32_e32 v241, 0xffff0000, v161
	v_pk_add_f32 v[14:15], v[14:15], v[240:241]
	v_lshlrev_b32_e32 v240, 16, v162
	v_and_b32_e32 v241, 0xffff0000, v162
	v_pk_add_f32 v[8:9], v[8:9], v[240:241]
	v_lshlrev_b32_e32 v240, 16, v163
	v_and_b32_e32 v241, 0xffff0000, v163
	v_pk_add_f32 v[10:11], v[10:11], v[240:241]
	s_add_u32 s42, s10, 0x10200
	s_addc_u32 s43, s11, 0
	global_load_dwordx4 v[160:163], v203, s[42:43]
	s_waitcnt vmcnt(8)
	v_lshlrev_b32_e32 v240, 16, v164
	v_and_b32_e32 v241, 0xffff0000, v164
	v_pk_add_f32 v[36:37], v[36:37], v[240:241]
	v_lshlrev_b32_e32 v240, 16, v165
	v_and_b32_e32 v241, 0xffff0000, v165
	v_pk_add_f32 v[38:39], v[38:39], v[240:241]
	v_lshlrev_b32_e32 v240, 16, v166
	v_and_b32_e32 v241, 0xffff0000, v166
	v_pk_add_f32 v[32:33], v[32:33], v[240:241]
	v_lshlrev_b32_e32 v240, 16, v167
	v_and_b32_e32 v241, 0xffff0000, v167
	v_pk_add_f32 v[34:35], v[34:35], v[240:241]
	s_add_u32 s98, s10, 0x10200
	s_addc_u32 s99, s11, 0
	global_load_dwordx4 v[164:167], v203, s[98:99] offset:16
	s_waitcnt vmcnt(8)
	v_lshlrev_b32_e32 v240, 16, v168
	v_and_b32_e32 v241, 0xffff0000, v168
	v_pk_add_f32 v[4:5], v[4:5], v[240:241]
	v_lshlrev_b32_e32 v240, 16, v169
	v_and_b32_e32 v241, 0xffff0000, v169
	v_pk_add_f32 v[6:7], v[6:7], v[240:241]
	v_lshlrev_b32_e32 v240, 16, v170
	v_and_b32_e32 v241, 0xffff0000, v170
	v_pk_add_f32 v[0:1], v[0:1], v[240:241]
	v_lshlrev_b32_e32 v240, 16, v171
	v_and_b32_e32 v241, 0xffff0000, v171
	v_pk_add_f32 v[2:3], v[2:3], v[240:241]
	s_add_u32 s42, s10, 0x20000
	s_addc_u32 s43, s11, 0
	global_load_dwordx4 v[168:171], v203, s[42:43]
	s_waitcnt vmcnt(8)
	v_pk_fma_f32 v[124:125], v[148:149], v[124:125], v[172:173]
	v_pk_fma_f32 v[126:127], v[150:151], v[126:127], v[174:175]
	s_add_u32 s98, s10, 0x0
	s_addc_u32 s99, s11, 0
	global_store_dwordx4 v203, v[124:127], s[98:99] nt
	s_add_u32 s42, s10, 0x20000
	s_addc_u32 s43, s11, 0
	global_load_dwordx4 v[172:175], v203, s[42:43] offset:16
	s_waitcnt vmcnt(9)
	v_pk_fma_f32 v[120:121], v[144:145], v[120:121], v[176:177]
	v_pk_fma_f32 v[122:123], v[146:147], v[122:123], v[178:179]
	s_add_u32 s98, s10, 0x0
	s_addc_u32 s99, s11, 0
	global_store_dwordx4 v203, v[120:123], s[98:99] offset:16 nt
	s_add_u32 s42, s10, 0x20200
	s_addc_u32 s43, s11, 0
	global_load_dwordx4 v[176:179], v203, s[42:43]
	s_waitcnt vmcnt(10)
	v_pk_fma_f32 v[92:93], v[156:157], v[92:93], v[180:181]
	v_pk_fma_f32 v[94:95], v[158:159], v[94:95], v[182:183]
	s_add_u32 s98, s10, 0x200
	s_addc_u32 s99, s11, 0
	global_store_dwordx4 v203, v[92:95], s[98:99] nt
	s_add_u32 s42, s10, 0x20200
	s_addc_u32 s43, s11, 0
	global_load_dwordx4 v[180:183], v203, s[42:43] offset:16
	s_waitcnt vmcnt(11)
	v_pk_fma_f32 v[88:89], v[152:153], v[88:89], v[206:207]
	v_pk_fma_f32 v[90:91], v[154:155], v[90:91], v[208:209]
	s_add_u32 s98, s10, 0x200
	s_addc_u32 s99, s11, 0
	global_store_dwordx4 v203, v[88:91], s[98:99] offset:16 nt
	s_add_u32 s42, s10, 0x30000
	s_addc_u32 s43, s11, 0
	global_load_dwordx4 v[206:209], v203, s[42:43]
	s_waitcnt vmcnt(12)
	v_pk_fma_f32 v[116:117], v[148:149], v[116:117], v[210:211]
	v_pk_fma_f32 v[118:119], v[150:151], v[118:119], v[212:213]
	s_add_u32 s98, s10, 0x10000
	s_addc_u32 s99, s11, 0
	global_store_dwordx4 v203, v[116:119], s[98:99] nt
	s_add_u32 s42, s10, 0x30000
	s_addc_u32 s43, s11, 0
	global_load_dwordx4 v[210:213], v203, s[42:43] offset:16
	s_waitcnt vmcnt(13)
	v_pk_fma_f32 v[112:113], v[144:145], v[112:113], v[236:237]
	v_pk_fma_f32 v[114:115], v[146:147], v[114:115], v[238:239]
	s_add_u32 s98, s10, 0x10000
	s_addc_u32 s99, s11, 0
	global_store_dwordx4 v203, v[112:115], s[98:99] offset:16 nt
	s_add_u32 s42, s10, 0x30200
	s_addc_u32 s43, s11, 0
	global_load_dwordx4 v[236:239], v203, s[42:43]
	s_waitcnt vmcnt(14)
	v_pk_fma_f32 v[84:85], v[156:157], v[84:85], v[160:161]
	v_pk_fma_f32 v[86:87], v[158:159], v[86:87], v[162:163]
	s_add_u32 s98, s10, 0x10200
	s_addc_u32 s99, s11, 0
	global_store_dwordx4 v203, v[84:87], s[98:99] nt
	s_add_u32 s42, s10, 0x30200
	s_addc_u32 s43, s11, 0
	global_load_dwordx4 v[160:163], v203, s[42:43] offset:16
	s_waitcnt vmcnt(15)
	v_pk_fma_f32 v[80:81], v[152:153], v[80:81], v[164:165]
	v_pk_fma_f32 v[82:83], v[154:155], v[82:83], v[166:167]
	s_add_u32 s98, s10, 0x10200
	s_addc_u32 s99, s11, 0
	global_store_dwordx4 v203, v[80:83], s[98:99] offset:16 nt
	s_add_u32 s42, s10, 0x80000
	s_addc_u32 s43, s11, 0
	global_load_dwordx4 v[164:167], v203, s[42:43]
	s_waitcnt vmcnt(16)
	v_pk_fma_f32 v[108:109], v[148:149], v[108:109], v[168:169]
	v_pk_fma_f32 v[110:111], v[150:151], v[110:111], v[170:171]
	s_add_u32 s98, s10, 0x20000
	s_addc_u32 s99, s11, 0
	global_store_dwordx4 v203, v[108:111], s[98:99] nt
	s_add_u32 s42, s10, 0x80000
	s_addc_u32 s43, s11, 0
	global_load_dwordx4 v[168:171], v203, s[42:43] offset:16
	s_waitcnt vmcnt(16)
	v_pk_fma_f32 v[104:105], v[144:145], v[104:105], v[172:173]
	v_pk_fma_f32 v[106:107], v[146:147], v[106:107], v[174:175]
	s_add_u32 s98, s10, 0x20000
	s_addc_u32 s99, s11, 0
	global_store_dwordx4 v203, v[104:107], s[98:99] offset:16 nt
	s_add_u32 s42, s10, 0x80200
	s_addc_u32 s43, s11, 0
	global_load_dwordx4 v[172:175], v203, s[42:43]
	s_waitcnt vmcnt(16)
	v_pk_fma_f32 v[76:77], v[156:157], v[76:77], v[176:177]
	v_pk_fma_f32 v[78:79], v[158:159], v[78:79], v[178:179]
	s_add_u32 s98, s10, 0x20200
	s_addc_u32 s99, s11, 0
	global_store_dwordx4 v203, v[76:79], s[98:99] nt
	s_add_u32 s42, s10, 0x80200
	s_addc_u32 s43, s11, 0
	global_load_dwordx4 v[176:179], v203, s[42:43] offset:16
	s_waitcnt vmcnt(16)
	v_pk_fma_f32 v[72:73], v[152:153], v[72:73], v[180:181]
	v_pk_fma_f32 v[74:75], v[154:155], v[74:75], v[182:183]
	s_add_u32 s98, s10, 0x20200
	s_addc_u32 s99, s11, 0
	global_store_dwordx4 v203, v[72:75], s[98:99] offset:16 nt
	s_add_u32 s42, s10, 0x90000
	s_addc_u32 s43, s11, 0
	global_load_dwordx4 v[180:183], v203, s[42:43]
	s_waitcnt vmcnt(16)
	v_pk_fma_f32 v[100:101], v[148:149], v[100:101], v[206:207]
	v_pk_fma_f32 v[102:103], v[150:151], v[102:103], v[208:209]
	s_add_u32 s98, s10, 0x30000
	s_addc_u32 s99, s11, 0
	global_store_dwordx4 v203, v[100:103], s[98:99] nt
	s_add_u32 s42, s10, 0x90000
	s_addc_u32 s43, s11, 0
	global_load_dwordx4 v[206:209], v203, s[42:43] offset:16
	s_waitcnt vmcnt(16)
	v_pk_fma_f32 v[96:97], v[144:145], v[96:97], v[210:211]
	v_pk_fma_f32 v[98:99], v[146:147], v[98:99], v[212:213]
	s_add_u32 s98, s10, 0x30000
	s_addc_u32 s99, s11, 0
	global_store_dwordx4 v203, v[96:99], s[98:99] offset:16 nt
	s_add_u32 s42, s10, 0x90200
	s_addc_u32 s43, s11, 0
	global_load_dwordx4 v[210:213], v203, s[42:43]
	s_waitcnt vmcnt(16)
	v_pk_fma_f32 v[68:69], v[156:157], v[68:69], v[236:237]
	v_pk_fma_f32 v[70:71], v[158:159], v[70:71], v[238:239]
	s_add_u32 s98, s10, 0x30200
	s_addc_u32 s99, s11, 0
	global_store_dwordx4 v203, v[68:71], s[98:99] nt
	s_add_u32 s42, s10, 0x90200
	s_addc_u32 s43, s11, 0
	global_load_dwordx4 v[236:239], v203, s[42:43] offset:16
	s_waitcnt vmcnt(16)
	v_pk_fma_f32 v[64:65], v[152:153], v[64:65], v[160:161]
	v_pk_fma_f32 v[66:67], v[154:155], v[66:67], v[162:163]
	s_add_u32 s98, s10, 0x30200
	s_addc_u32 s99, s11, 0
	global_store_dwordx4 v203, v[64:67], s[98:99] offset:16 nt
	s_add_u32 s42, s10, 0xa0000
	s_addc_u32 s43, s11, 0
	global_load_dwordx4 v[160:163], v203, s[42:43]
	s_waitcnt vmcnt(16)
	v_pk_fma_f32 v[60:61], v[148:149], v[60:61], v[164:165]
	v_pk_fma_f32 v[62:63], v[150:151], v[62:63], v[166:167]
	s_add_u32 s98, s10, 0x80000
	s_addc_u32 s99, s11, 0
	global_store_dwordx4 v203, v[60:63], s[98:99] nt
	s_add_u32 s42, s10, 0xa0000
	s_addc_u32 s43, s11, 0
	global_load_dwordx4 v[164:167], v203, s[42:43] offset:16
	s_waitcnt vmcnt(16)
	v_pk_fma_f32 v[56:57], v[144:145], v[56:57], v[168:169]
	v_pk_fma_f32 v[58:59], v[146:147], v[58:59], v[170:171]
	s_add_u32 s98, s10, 0x80000
	s_addc_u32 s99, s11, 0
	global_store_dwordx4 v203, v[56:59], s[98:99] offset:16 nt
	s_add_u32 s42, s10, 0xa0200
	s_addc_u32 s43, s11, 0
	global_load_dwordx4 v[168:171], v203, s[42:43]
	s_waitcnt vmcnt(16)
	v_pk_fma_f32 v[28:29], v[156:157], v[28:29], v[172:173]
	v_pk_fma_f32 v[30:31], v[158:159], v[30:31], v[174:175]
	s_add_u32 s98, s10, 0x80200
	s_addc_u32 s99, s11, 0
	global_store_dwordx4 v203, v[28:31], s[98:99] nt
	s_add_u32 s42, s10, 0xa0200
	s_addc_u32 s43, s11, 0
	global_load_dwordx4 v[172:175], v203, s[42:43] offset:16
	s_waitcnt vmcnt(16)
	v_pk_fma_f32 v[24:25], v[152:153], v[24:25], v[176:177]
	v_pk_fma_f32 v[26:27], v[154:155], v[26:27], v[178:179]
	s_add_u32 s98, s10, 0x80200
	s_addc_u32 s99, s11, 0
	global_store_dwordx4 v203, v[24:27], s[98:99] offset:16 nt
	s_add_u32 s42, s10, 0xb0000
	s_addc_u32 s43, s11, 0
	global_load_dwordx4 v[176:179], v203, s[42:43]
	s_waitcnt vmcnt(16)
	v_pk_fma_f32 v[52:53], v[148:149], v[52:53], v[180:181]
	v_pk_fma_f32 v[54:55], v[150:151], v[54:55], v[182:183]
	s_add_u32 s98, s10, 0x90000
	s_addc_u32 s99, s11, 0
	global_store_dwordx4 v203, v[52:55], s[98:99] nt
	s_add_u32 s42, s10, 0xb0000
	s_addc_u32 s43, s11, 0
	global_load_dwordx4 v[180:183], v203, s[42:43] offset:16
	s_waitcnt vmcnt(16)
	v_pk_fma_f32 v[48:49], v[144:145], v[48:49], v[206:207]
	v_pk_fma_f32 v[50:51], v[146:147], v[50:51], v[208:209]
	s_add_u32 s98, s10, 0x90000
	s_addc_u32 s99, s11, 0
	global_store_dwordx4 v203, v[48:51], s[98:99] offset:16 nt
	s_add_u32 s42, s10, 0xb0200
	s_addc_u32 s43, s11, 0
	global_load_dwordx4 v[206:209], v203, s[42:43]
	s_waitcnt vmcnt(16)
	v_pk_fma_f32 v[20:21], v[156:157], v[20:21], v[210:211]
	v_pk_fma_f32 v[22:23], v[158:159], v[22:23], v[212:213]
	s_add_u32 s98, s10, 0x90200
	s_addc_u32 s99, s11, 0
	global_store_dwordx4 v203, v[20:23], s[98:99] nt
	s_add_u32 s42, s10, 0xb0200
	s_addc_u32 s43, s11, 0
	global_load_dwordx4 v[210:213], v203, s[42:43] offset:16
	s_waitcnt vmcnt(16)
	v_pk_fma_f32 v[16:17], v[152:153], v[16:17], v[236:237]
	v_pk_fma_f32 v[18:19], v[154:155], v[18:19], v[238:239]
	s_add_u32 s98, s10, 0x90200
	s_addc_u32 s99, s11, 0
	global_store_dwordx4 v203, v[16:19], s[98:99] offset:16 nt
	s_waitcnt vmcnt(15)
	v_pk_fma_f32 v[44:45], v[148:149], v[44:45], v[160:161]
	v_pk_fma_f32 v[46:47], v[150:151], v[46:47], v[162:163]
	s_add_u32 s42, s10, 0xa0000
	s_addc_u32 s43, s11, 0
	global_store_dwordx4 v203, v[44:47], s[42:43] nt
	s_waitcnt vmcnt(14)
	v_pk_fma_f32 v[40:41], v[144:145], v[40:41], v[164:165]
	v_pk_fma_f32 v[42:43], v[146:147], v[42:43], v[166:167]
	s_add_u32 s98, s10, 0xa0000
	s_addc_u32 s99, s11, 0
	global_store_dwordx4 v203, v[40:43], s[98:99] offset:16 nt
	s_waitcnt vmcnt(13)
	v_pk_fma_f32 v[12:13], v[156:157], v[12:13], v[168:169]
	v_pk_fma_f32 v[14:15], v[158:159], v[14:15], v[170:171]
	s_add_u32 s42, s10, 0xa0200
	s_addc_u32 s43, s11, 0
	global_store_dwordx4 v203, v[12:15], s[42:43] nt
	s_waitcnt vmcnt(12)
	v_pk_fma_f32 v[8:9], v[152:153], v[8:9], v[172:173]
	v_pk_fma_f32 v[10:11], v[154:155], v[10:11], v[174:175]
	s_add_u32 s98, s10, 0xa0200
	s_addc_u32 s99, s11, 0
	global_store_dwordx4 v203, v[8:11], s[98:99] offset:16 nt
	s_waitcnt vmcnt(11)
	v_pk_fma_f32 v[36:37], v[148:149], v[36:37], v[176:177]
	v_pk_fma_f32 v[38:39], v[150:151], v[38:39], v[178:179]
	s_add_u32 s42, s10, 0xb0000
	s_addc_u32 s43, s11, 0
	global_store_dwordx4 v203, v[36:39], s[42:43] nt
	s_waitcnt vmcnt(10)
	v_pk_fma_f32 v[32:33], v[144:145], v[32:33], v[180:181]
	v_pk_fma_f32 v[34:35], v[146:147], v[34:35], v[182:183]
	s_add_u32 s98, s10, 0xb0000
	s_addc_u32 s99, s11, 0
	global_store_dwordx4 v203, v[32:35], s[98:99] offset:16 nt
	s_waitcnt vmcnt(9)
	v_pk_fma_f32 v[4:5], v[156:157], v[4:5], v[206:207]
	v_pk_fma_f32 v[6:7], v[158:159], v[6:7], v[208:209]
	s_add_u32 s42, s10, 0xb0200
	s_addc_u32 s43, s11, 0
	global_store_dwordx4 v203, v[4:7], s[42:43] nt
	s_waitcnt vmcnt(8)
	v_pk_fma_f32 v[0:1], v[152:153], v[0:1], v[210:211]
	v_pk_fma_f32 v[2:3], v[154:155], v[2:3], v[212:213]
	s_add_u32 s98, s10, 0xb0200
	s_addc_u32 s99, s11, 0
	global_store_dwordx4 v203, v[0:3], s[98:99] offset:16 nt
	s_branch .Lfq_predone
.Lfq_np2:
	s_add_u32 s42, s62, 0x0
	s_addc_u32 s43, s63, 0
	global_load_dwordx4 v[160:163], v205, s[42:43] sc0 sc1
	s_add_u32 s98, s62, 0x1000
	s_addc_u32 s99, s63, 0
	global_load_dwordx4 v[164:167], v205, s[98:99] sc0 sc1
	s_add_u32 s42, s62, 0x400
	s_addc_u32 s43, s63, 0
	global_load_dwordx4 v[168:171], v205, s[42:43] sc0 sc1
	s_add_u32 s98, s62, 0x1400
	s_addc_u32 s99, s63, 0
	global_load_dwordx4 v[172:175], v205, s[98:99] sc0 sc1
	s_add_u32 s42, s62, 0x800
	s_addc_u32 s43, s63, 0
	global_load_dwordx4 v[176:179], v205, s[42:43] sc0 sc1
	s_add_u32 s98, s62, 0x1800
	s_addc_u32 s99, s63, 0
	global_load_dwordx4 v[180:183], v205, s[98:99] sc0 sc1
	s_add_u32 s42, s62, 0xc00
	s_addc_u32 s43, s63, 0
	global_load_dwordx4 v[206:209], v205, s[42:43] sc0 sc1
	s_add_u32 s98, s62, 0x1c00
	s_addc_u32 s99, s63, 0
	global_load_dwordx4 v[210:213], v205, s[98:99] sc0 sc1
	s_add_u32 s42, s62, 0x2000
	s_addc_u32 s43, s63, 0
	global_load_dwordx4 v[236:239], v205, s[42:43] sc0 sc1
	s_waitcnt vmcnt(8)
	v_lshlrev_b32_e32 v240, 16, v160
	v_and_b32_e32 v241, 0xffff0000, v160
	v_pk_add_f32 v[124:125], v[124:125], v[240:241]
	v_lshlrev_b32_e32 v240, 16, v161
	v_and_b32_e32 v241, 0xffff0000, v161
	v_pk_add_f32 v[126:127], v[126:127], v[240:241]
	v_lshlrev_b32_e32 v240, 16, v162
	v_and_b32_e32 v241, 0xffff0000, v162
	v_pk_add_f32 v[120:121], v[120:121], v[240:241]
	v_lshlrev_b32_e32 v240, 16, v163
	v_and_b32_e32 v241, 0xffff0000, v163
	v_pk_add_f32 v[122:123], v[122:123], v[240:241]
	s_add_u32 s98, s62, 0x3000
	s_addc_u32 s99, s63, 0
	global_load_dwordx4 v[160:163], v205, s[98:99] sc0 sc1
	s_waitcnt vmcnt(8)
	v_lshlrev_b32_e32 v240, 16, v164
	v_and_b32_e32 v241, 0xffff0000, v164
	v_pk_add_f32 v[92:93], v[92:93], v[240:241]
	v_lshlrev_b32_e32 v240, 16, v165
	v_and_b32_e32 v241, 0xffff0000, v165
	v_pk_add_f32 v[94:95], v[94:95], v[240:241]
	v_lshlrev_b32_e32 v240, 16, v166
	v_and_b32_e32 v241, 0xffff0000, v166
	v_pk_add_f32 v[88:89], v[88:89], v[240:241]
	v_lshlrev_b32_e32 v240, 16, v167
	v_and_b32_e32 v241, 0xffff0000, v167
	v_pk_add_f32 v[90:91], v[90:91], v[240:241]
	s_add_u32 s42, s62, 0x2400
	s_addc_u32 s43, s63, 0
	global_load_dwordx4 v[164:167], v205, s[42:43] sc0 sc1
	s_waitcnt vmcnt(8)
	v_lshlrev_b32_e32 v240, 16, v168
	v_and_b32_e32 v241, 0xffff0000, v168
	v_pk_add_f32 v[116:117], v[116:117], v[240:241]
	v_lshlrev_b32_e32 v240, 16, v169
	v_and_b32_e32 v241, 0xffff0000, v169
	v_pk_add_f32 v[118:119], v[118:119], v[240:241]
	v_lshlrev_b32_e32 v240, 16, v170
	v_and_b32_e32 v241, 0xffff0000, v170
	v_pk_add_f32 v[112:113], v[112:113], v[240:241]
	v_lshlrev_b32_e32 v240, 16, v171
	v_and_b32_e32 v241, 0xffff0000, v171
	v_pk_add_f32 v[114:115], v[114:115], v[240:241]
	s_add_u32 s98, s62, 0x3400
	s_addc_u32 s99, s63, 0
	global_load_dwordx4 v[168:171], v205, s[98:99] sc0 sc1
	s_waitcnt vmcnt(8)
	v_lshlrev_b32_e32 v240, 16, v172
	v_and_b32_e32 v241, 0xffff0000, v172
	v_pk_add_f32 v[84:85], v[84:85], v[240:241]
	v_lshlrev_b32_e32 v240, 16, v173
	v_and_b32_e32 v241, 0xffff0000, v173
	v_pk_add_f32 v[86:87], v[86:87], v[240:241]
	v_lshlrev_b32_e32 v240, 16, v174
	v_and_b32_e32 v241, 0xffff0000, v174
	v_pk_add_f32 v[80:81], v[80:81], v[240:241]
	v_lshlrev_b32_e32 v240, 16, v175
	v_and_b32_e32 v241, 0xffff0000, v175
	v_pk_add_f32 v[82:83], v[82:83], v[240:241]
	s_add_u32 s42, s62, 0x2800
	s_addc_u32 s43, s63, 0
	global_load_dwordx4 v[172:175], v205, s[42:43] sc0 sc1
	s_waitcnt vmcnt(8)
	v_lshlrev_b32_e32 v240, 16, v176
	v_and_b32_e32 v241, 0xffff0000, v176
	v_pk_add_f32 v[108:109], v[108:109], v[240:241]
	v_lshlrev_b32_e32 v240, 16, v177
	v_and_b32_e32 v241, 0xffff0000, v177
	v_pk_add_f32 v[110:111], v[110:111], v[240:241]
	v_lshlrev_b32_e32 v240, 16, v178
	v_and_b32_e32 v241, 0xffff0000, v178
	v_pk_add_f32 v[104:105], v[104:105], v[240:241]
	v_lshlrev_b32_e32 v240, 16, v179
	v_and_b32_e32 v241, 0xffff0000, v179
	v_pk_add_f32 v[106:107], v[106:107], v[240:241]
	s_add_u32 s98, s62, 0x3800
	s_addc_u32 s99, s63, 0
	global_load_dwordx4 v[176:179], v205, s[98:99] sc0 sc1
	s_waitcnt vmcnt(8)
	v_lshlrev_b32_e32 v240, 16, v180
	v_and_b32_e32 v241, 0xffff0000, v180
	v_pk_add_f32 v[76:77], v[76:77], v[240:241]
	v_lshlrev_b32_e32 v240, 16, v181
	v_and_b32_e32 v241, 0xffff0000, v181
	v_pk_add_f32 v[78:79], v[78:79], v[240:241]
	v_lshlrev_b32_e32 v240, 16, v182
	v_and_b32_e32 v241, 0xffff0000, v182
	v_pk_add_f32 v[72:73], v[72:73], v[240:241]
	v_lshlrev_b32_e32 v240, 16, v183
	v_and_b32_e32 v241, 0xffff0000, v183
	v_pk_add_f32 v[74:75], v[74:75], v[240:241]
	s_add_u32 s42, s62, 0x2c00
	s_addc_u32 s43, s63, 0
	global_load_dwordx4 v[180:183], v205, s[42:43] sc0 sc1
	s_waitcnt vmcnt(8)
	v_lshlrev_b32_e32 v240, 16, v206
	v_and_b32_e32 v241, 0xffff0000, v206
	v_pk_add_f32 v[100:101], v[100:101], v[240:241]
	v_lshlrev_b32_e32 v240, 16, v207
	v_and_b32_e32 v241, 0xffff0000, v207
	v_pk_add_f32 v[102:103], v[102:103], v[240:241]
	v_lshlrev_b32_e32 v240, 16, v208
	v_and_b32_e32 v241, 0xffff0000, v208
	v_pk_add_f32 v[96:97], v[96:97], v[240:241]
	v_lshlrev_b32_e32 v240, 16, v209
	v_and_b32_e32 v241, 0xffff0000, v209
	v_pk_add_f32 v[98:99], v[98:99], v[240:241]
	s_add_u32 s98, s62, 0x3c00
	s_addc_u32 s99, s63, 0
	global_load_dwordx4 v[206:209], v205, s[98:99] sc0 sc1
	s_waitcnt vmcnt(8)
	v_lshlrev_b32_e32 v240, 16, v210
	v_and_b32_e32 v241, 0xffff0000, v210
	v_pk_add_f32 v[68:69], v[68:69], v[240:241]
	v_lshlrev_b32_e32 v240, 16, v211
	v_and_b32_e32 v241, 0xffff0000, v211
	v_pk_add_f32 v[70:71], v[70:71], v[240:241]
	v_lshlrev_b32_e32 v240, 16, v212
	v_and_b32_e32 v241, 0xffff0000, v212
	v_pk_add_f32 v[64:65], v[64:65], v[240:241]
	v_lshlrev_b32_e32 v240, 16, v213
	v_and_b32_e32 v241, 0xffff0000, v213
	v_pk_add_f32 v[66:67], v[66:67], v[240:241]
	s_add_u32 s42, s62, 0x20000
	s_addc_u32 s43, s63, 0
	global_load_dwordx4 v[210:213], v205, s[42:43] sc0 sc1
	s_waitcnt vmcnt(8)
	v_lshlrev_b32_e32 v240, 16, v236
	v_and_b32_e32 v241, 0xffff0000, v236
	v_pk_add_f32 v[60:61], v[60:61], v[240:241]
	v_lshlrev_b32_e32 v240, 16, v237
	v_and_b32_e32 v241, 0xffff0000, v237
	v_pk_add_f32 v[62:63], v[62:63], v[240:241]
	v_lshlrev_b32_e32 v240, 16, v238
	v_and_b32_e32 v241, 0xffff0000, v238
	v_pk_add_f32 v[56:57], v[56:57], v[240:241]
	v_lshlrev_b32_e32 v240, 16, v239
	v_and_b32_e32 v241, 0xffff0000, v239
	v_pk_add_f32 v[58:59], v[58:59], v[240:241]
	s_add_u32 s98, s62, 0x21000
	s_addc_u32 s99, s63, 0
	global_load_dwordx4 v[236:239], v205, s[98:99] sc0 sc1
	s_waitcnt vmcnt(8)
	v_lshlrev_b32_e32 v240, 16, v160
	v_and_b32_e32 v241, 0xffff0000, v160
	v_pk_add_f32 v[28:29], v[28:29], v[240:241]
	v_lshlrev_b32_e32 v240, 16, v161
	v_and_b32_e32 v241, 0xffff0000, v161
	v_pk_add_f32 v[30:31], v[30:31], v[240:241]
	v_lshlrev_b32_e32 v240, 16, v162
	v_and_b32_e32 v241, 0xffff0000, v162
	v_pk_add_f32 v[24:25], v[24:25], v[240:241]
	v_lshlrev_b32_e32 v240, 16, v163
	v_and_b32_e32 v241, 0xffff0000, v163
	v_pk_add_f32 v[26:27], v[26:27], v[240:241]
	s_add_u32 s42, s62, 0x20400
	s_addc_u32 s43, s63, 0
	global_load_dwordx4 v[160:163], v205, s[42:43] sc0 sc1
	s_waitcnt vmcnt(8)
	v_lshlrev_b32_e32 v240, 16, v164
	v_and_b32_e32 v241, 0xffff0000, v164
	v_pk_add_f32 v[52:53], v[52:53], v[240:241]
	v_lshlrev_b32_e32 v240, 16, v165
	v_and_b32_e32 v241, 0xffff0000, v165
	v_pk_add_f32 v[54:55], v[54:55], v[240:241]
	v_lshlrev_b32_e32 v240, 16, v166
	v_and_b32_e32 v241, 0xffff0000, v166
	v_pk_add_f32 v[48:49], v[48:49], v[240:241]
	v_lshlrev_b32_e32 v240, 16, v167
	v_and_b32_e32 v241, 0xffff0000, v167
	v_pk_add_f32 v[50:51], v[50:51], v[240:241]
	s_add_u32 s98, s62, 0x21400
	s_addc_u32 s99, s63, 0
	global_load_dwordx4 v[164:167], v205, s[98:99] sc0 sc1
	s_waitcnt vmcnt(8)
	v_lshlrev_b32_e32 v240, 16, v168
	v_and_b32_e32 v241, 0xffff0000, v168
	v_pk_add_f32 v[20:21], v[20:21], v[240:241]
	v_lshlrev_b32_e32 v240, 16, v169
	v_and_b32_e32 v241, 0xffff0000, v169
	v_pk_add_f32 v[22:23], v[22:23], v[240:241]
	v_lshlrev_b32_e32 v240, 16, v170
	v_and_b32_e32 v241, 0xffff0000, v170
	v_pk_add_f32 v[16:17], v[16:17], v[240:241]
	v_lshlrev_b32_e32 v240, 16, v171
	v_and_b32_e32 v241, 0xffff0000, v171
	v_pk_add_f32 v[18:19], v[18:19], v[240:241]
	s_add_u32 s42, s62, 0x20800
	s_addc_u32 s43, s63, 0
	global_load_dwordx4 v[168:171], v205, s[42:43] sc0 sc1
	s_waitcnt vmcnt(8)
	v_lshlrev_b32_e32 v240, 16, v172
	v_and_b32_e32 v241, 0xffff0000, v172
	v_pk_add_f32 v[44:45], v[44:45], v[240:241]
	v_lshlrev_b32_e32 v240, 16, v173
	v_and_b32_e32 v241, 0xffff0000, v173
	v_pk_add_f32 v[46:47], v[46:47], v[240:241]
	v_lshlrev_b32_e32 v240, 16, v174
	v_and_b32_e32 v241, 0xffff0000, v174
	v_pk_add_f32 v[40:41], v[40:41], v[240:241]
	v_lshlrev_b32_e32 v240, 16, v175
	v_and_b32_e32 v241, 0xffff0000, v175
	v_pk_add_f32 v[42:43], v[42:43], v[240:241]
	s_add_u32 s98, s62, 0x21800
	s_addc_u32 s99, s63, 0
	global_load_dwordx4 v[172:175], v205, s[98:99] sc0 sc1
	s_waitcnt vmcnt(8)
	v_lshlrev_b32_e32 v240, 16, v176
	v_and_b32_e32 v241, 0xffff0000, v176
	v_pk_add_f32 v[12:13], v[12:13], v[240:241]
	v_lshlrev_b32_e32 v240, 16, v177
	v_and_b32_e32 v241, 0xffff0000, v177
	v_pk_add_f32 v[14:15], v[14:15], v[240:241]
	v_lshlrev_b32_e32 v240, 16, v178
	v_and_b32_e32 v241, 0xffff0000, v178
	v_pk_add_f32 v[8:9], v[8:9], v[240:241]
	v_lshlrev_b32_e32 v240, 16, v179
	v_and_b32_e32 v241, 0xffff0000, v179
	v_pk_add_f32 v[10:11], v[10:11], v[240:241]
	s_add_u32 s42, s62, 0x20c00
	s_addc_u32 s43, s63, 0
	global_load_dwordx4 v[176:179], v205, s[42:43] sc0 sc1
	s_waitcnt vmcnt(8)
	v_lshlrev_b32_e32 v240, 16, v180
	v_and_b32_e32 v241, 0xffff0000, v180
	v_pk_add_f32 v[36:37], v[36:37], v[240:241]
	v_lshlrev_b32_e32 v240, 16, v181
	v_and_b32_e32 v241, 0xffff0000, v181
	v_pk_add_f32 v[38:39], v[38:39], v[240:241]
	v_lshlrev_b32_e32 v240, 16, v182
	v_and_b32_e32 v241, 0xffff0000, v182
	v_pk_add_f32 v[32:33], v[32:33], v[240:241]
	v_lshlrev_b32_e32 v240, 16, v183
	v_and_b32_e32 v241, 0xffff0000, v183
	v_pk_add_f32 v[34:35], v[34:35], v[240:241]
	s_add_u32 s98, s62, 0x21c00
	s_addc_u32 s99, s63, 0
	global_load_dwordx4 v[180:183], v205, s[98:99] sc0 sc1
	s_waitcnt vmcnt(8)
	v_lshlrev_b32_e32 v240, 16, v206
	v_and_b32_e32 v241, 0xffff0000, v206
	v_pk_add_f32 v[4:5], v[4:5], v[240:241]
	v_lshlrev_b32_e32 v240, 16, v207
	v_and_b32_e32 v241, 0xffff0000, v207
	v_pk_add_f32 v[6:7], v[6:7], v[240:241]
	v_lshlrev_b32_e32 v240, 16, v208
	v_and_b32_e32 v241, 0xffff0000, v208
	v_pk_add_f32 v[0:1], v[0:1], v[240:241]
	v_lshlrev_b32_e32 v240, 16, v209
	v_and_b32_e32 v241, 0xffff0000, v209
	v_pk_add_f32 v[2:3], v[2:3], v[240:241]
	s_add_u32 s42, s62, 0x22000
	s_addc_u32 s43, s63, 0
	global_load_dwordx4 v[206:209], v205, s[42:43] sc0 sc1
	s_waitcnt vmcnt(8)
	v_lshlrev_b32_e32 v240, 16, v210
	v_and_b32_e32 v241, 0xffff0000, v210
	v_pk_add_f32 v[124:125], v[124:125], v[240:241]
	v_lshlrev_b32_e32 v240, 16, v211
	v_and_b32_e32 v241, 0xffff0000, v211
	v_pk_add_f32 v[126:127], v[126:127], v[240:241]
	v_lshlrev_b32_e32 v240, 16, v212
	v_and_b32_e32 v241, 0xffff0000, v212
	v_pk_add_f32 v[120:121], v[120:121], v[240:241]
	v_lshlrev_b32_e32 v240, 16, v213
	v_and_b32_e32 v241, 0xffff0000, v213
	v_pk_add_f32 v[122:123], v[122:123], v[240:241]
	s_add_u32 s98, s62, 0x23000
	s_addc_u32 s99, s63, 0
	global_load_dwordx4 v[210:213], v205, s[98:99] sc0 sc1
	s_waitcnt vmcnt(8)
	v_lshlrev_b32_e32 v240, 16, v236
	v_and_b32_e32 v241, 0xffff0000, v236
	v_pk_add_f32 v[92:93], v[92:93], v[240:241]
	v_lshlrev_b32_e32 v240, 16, v237
	v_and_b32_e32 v241, 0xffff0000, v237
	v_pk_add_f32 v[94:95], v[94:95], v[240:241]
	v_lshlrev_b32_e32 v240, 16, v238
	v_and_b32_e32 v241, 0xffff0000, v238
	v_pk_add_f32 v[88:89], v[88:89], v[240:241]
	v_lshlrev_b32_e32 v240, 16, v239
	v_and_b32_e32 v241, 0xffff0000, v239
	v_pk_add_f32 v[90:91], v[90:91], v[240:241]
	s_add_u32 s42, s62, 0x22400
	s_addc_u32 s43, s63, 0
	global_load_dwordx4 v[236:239], v205, s[42:43] sc0 sc1
	s_waitcnt vmcnt(8)
	v_lshlrev_b32_e32 v240, 16, v160
	v_and_b32_e32 v241, 0xffff0000, v160
	v_pk_add_f32 v[116:117], v[116:117], v[240:241]
	v_lshlrev_b32_e32 v240, 16, v161
	v_and_b32_e32 v241, 0xffff0000, v161
	v_pk_add_f32 v[118:119], v[118:119], v[240:241]
	v_lshlrev_b32_e32 v240, 16, v162
	v_and_b32_e32 v241, 0xffff0000, v162
	v_pk_add_f32 v[112:113], v[112:113], v[240:241]
	v_lshlrev_b32_e32 v240, 16, v163
	v_and_b32_e32 v241, 0xffff0000, v163
	v_pk_add_f32 v[114:115], v[114:115], v[240:241]
	s_add_u32 s98, s62, 0x23400
	s_addc_u32 s99, s63, 0
	global_load_dwordx4 v[160:163], v205, s[98:99] sc0 sc1
	s_waitcnt vmcnt(8)
	v_lshlrev_b32_e32 v240, 16, v164
	v_and_b32_e32 v241, 0xffff0000, v164
	v_pk_add_f32 v[84:85], v[84:85], v[240:241]
	v_lshlrev_b32_e32 v240, 16, v165
	v_and_b32_e32 v241, 0xffff0000, v165
	v_pk_add_f32 v[86:87], v[86:87], v[240:241]
	v_lshlrev_b32_e32 v240, 16, v166
	v_and_b32_e32 v241, 0xffff0000, v166
	v_pk_add_f32 v[80:81], v[80:81], v[240:241]
	v_lshlrev_b32_e32 v240, 16, v167
	v_and_b32_e32 v241, 0xffff0000, v167
	v_pk_add_f32 v[82:83], v[82:83], v[240:241]
	s_add_u32 s42, s62, 0x22800
	s_addc_u32 s43, s63, 0
	global_load_dwordx4 v[164:167], v205, s[42:43] sc0 sc1
	s_waitcnt vmcnt(8)
	v_lshlrev_b32_e32 v240, 16, v168
	v_and_b32_e32 v241, 0xffff0000, v168
	v_pk_add_f32 v[108:109], v[108:109], v[240:241]
	v_lshlrev_b32_e32 v240, 16, v169
	v_and_b32_e32 v241, 0xffff0000, v169
	v_pk_add_f32 v[110:111], v[110:111], v[240:241]
	v_lshlrev_b32_e32 v240, 16, v170
	v_and_b32_e32 v241, 0xffff0000, v170
	v_pk_add_f32 v[104:105], v[104:105], v[240:241]
	v_lshlrev_b32_e32 v240, 16, v171
	v_and_b32_e32 v241, 0xffff0000, v171
	v_pk_add_f32 v[106:107], v[106:107], v[240:241]
	s_add_u32 s98, s62, 0x23800
	s_addc_u32 s99, s63, 0
	global_load_dwordx4 v[168:171], v205, s[98:99] sc0 sc1
	s_waitcnt vmcnt(8)
	v_lshlrev_b32_e32 v240, 16, v172
	v_and_b32_e32 v241, 0xffff0000, v172
	v_pk_add_f32 v[76:77], v[76:77], v[240:241]
	v_lshlrev_b32_e32 v240, 16, v173
	v_and_b32_e32 v241, 0xffff0000, v173
	v_pk_add_f32 v[78:79], v[78:79], v[240:241]
	v_lshlrev_b32_e32 v240, 16, v174
	v_and_b32_e32 v241, 0xffff0000, v174
	v_pk_add_f32 v[72:73], v[72:73], v[240:241]
	v_lshlrev_b32_e32 v240, 16, v175
	v_and_b32_e32 v241, 0xffff0000, v175
	v_pk_add_f32 v[74:75], v[74:75], v[240:241]
	s_add_u32 s42, s62, 0x22c00
	s_addc_u32 s43, s63, 0
	global_load_dwordx4 v[172:175], v205, s[42:43] sc0 sc1
	s_waitcnt vmcnt(8)
	v_lshlrev_b32_e32 v240, 16, v176
	v_and_b32_e32 v241, 0xffff0000, v176
	v_pk_add_f32 v[100:101], v[100:101], v[240:241]
	v_lshlrev_b32_e32 v240, 16, v177
	v_and_b32_e32 v241, 0xffff0000, v177
	v_pk_add_f32 v[102:103], v[102:103], v[240:241]
	v_lshlrev_b32_e32 v240, 16, v178
	v_and_b32_e32 v241, 0xffff0000, v178
	v_pk_add_f32 v[96:97], v[96:97], v[240:241]
	v_lshlrev_b32_e32 v240, 16, v179
	v_and_b32_e32 v241, 0xffff0000, v179
	v_pk_add_f32 v[98:99], v[98:99], v[240:241]
	s_add_u32 s98, s62, 0x23c00
	s_addc_u32 s99, s63, 0
	global_load_dwordx4 v[176:179], v205, s[98:99] sc0 sc1
	s_waitcnt vmcnt(8)
	v_lshlrev_b32_e32 v240, 16, v180
	v_and_b32_e32 v241, 0xffff0000, v180
	v_pk_add_f32 v[68:69], v[68:69], v[240:241]
	v_lshlrev_b32_e32 v240, 16, v181
	v_and_b32_e32 v241, 0xffff0000, v181
	v_pk_add_f32 v[70:71], v[70:71], v[240:241]
	v_lshlrev_b32_e32 v240, 16, v182
	v_and_b32_e32 v241, 0xffff0000, v182
	v_pk_add_f32 v[64:65], v[64:65], v[240:241]
	v_lshlrev_b32_e32 v240, 16, v183
	v_and_b32_e32 v241, 0xffff0000, v183
	v_pk_add_f32 v[66:67], v[66:67], v[240:241]
	s_add_u32 s42, s10, 0x0
	s_addc_u32 s43, s11, 0
	global_load_dwordx4 v[180:183], v203, s[42:43]
	s_waitcnt vmcnt(8)
	v_lshlrev_b32_e32 v240, 16, v206
	v_and_b32_e32 v241, 0xffff0000, v206
	v_pk_add_f32 v[60:61], v[60:61], v[240:241]
	v_lshlrev_b32_e32 v240, 16, v207
	v_and_b32_e32 v241, 0xffff0000, v207
	v_pk_add_f32 v[62:63], v[62:63], v[240:241]
	v_lshlrev_b32_e32 v240, 16, v208
	v_and_b32_e32 v241, 0xffff0000, v208
	v_pk_add_f32 v[56:57], v[56:57], v[240:241]
	v_lshlrev_b32_e32 v240, 16, v209
	v_and_b32_e32 v241, 0xffff0000, v209
	v_pk_add_f32 v[58:59], v[58:59], v[240:241]
	s_add_u32 s98, s10, 0x0
	s_addc_u32 s99, s11, 0
	global_load_dwordx4 v[206:209], v203, s[98:99] offset:16
	s_waitcnt vmcnt(8)
	v_lshlrev_b32_e32 v240, 16, v210
	v_and_b32_e32 v241, 0xffff0000, v210
	v_pk_add_f32 v[28:29], v[28:29], v[240:241]
	v_lshlrev_b32_e32 v240, 16, v211
	v_and_b32_e32 v241, 0xffff0000, v211
	v_pk_add_f32 v[30:31], v[30:31], v[240:241]
	v_lshlrev_b32_e32 v240, 16, v212
	v_and_b32_e32 v241, 0xffff0000, v212
	v_pk_add_f32 v[24:25], v[24:25], v[240:241]
	v_lshlrev_b32_e32 v240, 16, v213
	v_and_b32_e32 v241, 0xffff0000, v213
	v_pk_add_f32 v[26:27], v[26:27], v[240:241]
	s_add_u32 s42, s10, 0x200
	s_addc_u32 s43, s11, 0
	global_load_dwordx4 v[210:213], v203, s[42:43]
	s_waitcnt vmcnt(8)
	v_lshlrev_b32_e32 v240, 16, v236
	v_and_b32_e32 v241, 0xffff0000, v236
	v_pk_add_f32 v[52:53], v[52:53], v[240:241]
	v_lshlrev_b32_e32 v240, 16, v237
	v_and_b32_e32 v241, 0xffff0000, v237
	v_pk_add_f32 v[54:55], v[54:55], v[240:241]
	v_lshlrev_b32_e32 v240, 16, v238
	v_and_b32_e32 v241, 0xffff0000, v238
	v_pk_add_f32 v[48:49], v[48:49], v[240:241]
	v_lshlrev_b32_e32 v240, 16, v239
	v_and_b32_e32 v241, 0xffff0000, v239
	v_pk_add_f32 v[50:51], v[50:51], v[240:241]
	s_add_u32 s98, s10, 0x200
	s_addc_u32 s99, s11, 0
	global_load_dwordx4 v[236:239], v203, s[98:99] offset:16
	s_waitcnt vmcnt(8)
	v_lshlrev_b32_e32 v240, 16, v160
	v_and_b32_e32 v241, 0xffff0000, v160
	v_pk_add_f32 v[20:21], v[20:21], v[240:241]
	v_lshlrev_b32_e32 v240, 16, v161
	v_and_b32_e32 v241, 0xffff0000, v161
	v_pk_add_f32 v[22:23], v[22:23], v[240:241]
	v_lshlrev_b32_e32 v240, 16, v162
	v_and_b32_e32 v241, 0xffff0000, v162
	v_pk_add_f32 v[16:17], v[16:17], v[240:241]
	v_lshlrev_b32_e32 v240, 16, v163
	v_and_b32_e32 v241, 0xffff0000, v163
	v_pk_add_f32 v[18:19], v[18:19], v[240:241]
	s_add_u32 s42, s10, 0x10000
	s_addc_u32 s43, s11, 0
	global_load_dwordx4 v[160:163], v203, s[42:43]
	s_waitcnt vmcnt(8)
	v_lshlrev_b32_e32 v240, 16, v164
	v_and_b32_e32 v241, 0xffff0000, v164
	v_pk_add_f32 v[44:45], v[44:45], v[240:241]
	v_lshlrev_b32_e32 v240, 16, v165
	v_and_b32_e32 v241, 0xffff0000, v165
	v_pk_add_f32 v[46:47], v[46:47], v[240:241]
	v_lshlrev_b32_e32 v240, 16, v166
	v_and_b32_e32 v241, 0xffff0000, v166
	v_pk_add_f32 v[40:41], v[40:41], v[240:241]
	v_lshlrev_b32_e32 v240, 16, v167
	v_and_b32_e32 v241, 0xffff0000, v167
	v_pk_add_f32 v[42:43], v[42:43], v[240:241]
	s_add_u32 s98, s10, 0x10000
	s_addc_u32 s99, s11, 0
	global_load_dwordx4 v[164:167], v203, s[98:99] offset:16
	s_waitcnt vmcnt(8)
	v_lshlrev_b32_e32 v240, 16, v168
	v_and_b32_e32 v241, 0xffff0000, v168
	v_pk_add_f32 v[12:13], v[12:13], v[240:241]
	v_lshlrev_b32_e32 v240, 16, v169
	v_and_b32_e32 v241, 0xffff0000, v169
	v_pk_add_f32 v[14:15], v[14:15], v[240:241]
	v_lshlrev_b32_e32 v240, 16, v170
	v_and_b32_e32 v241, 0xffff0000, v170
	v_pk_add_f32 v[8:9], v[8:9], v[240:241]
	v_lshlrev_b32_e32 v240, 16, v171
	v_and_b32_e32 v241, 0xffff0000, v171
	v_pk_add_f32 v[10:11], v[10:11], v[240:241]
	s_add_u32 s42, s10, 0x10200
	s_addc_u32 s43, s11, 0
	global_load_dwordx4 v[168:171], v203, s[42:43]
	s_waitcnt vmcnt(8)
	v_lshlrev_b32_e32 v240, 16, v172
	v_and_b32_e32 v241, 0xffff0000, v172
	v_pk_add_f32 v[36:37], v[36:37], v[240:241]
	v_lshlrev_b32_e32 v240, 16, v173
	v_and_b32_e32 v241, 0xffff0000, v173
	v_pk_add_f32 v[38:39], v[38:39], v[240:241]
	v_lshlrev_b32_e32 v240, 16, v174
	v_and_b32_e32 v241, 0xffff0000, v174
	v_pk_add_f32 v[32:33], v[32:33], v[240:241]
	v_lshlrev_b32_e32 v240, 16, v175
	v_and_b32_e32 v241, 0xffff0000, v175
	v_pk_add_f32 v[34:35], v[34:35], v[240:241]
	s_add_u32 s98, s10, 0x10200
	s_addc_u32 s99, s11, 0
	global_load_dwordx4 v[172:175], v203, s[98:99] offset:16
	s_waitcnt vmcnt(8)
	v_lshlrev_b32_e32 v240, 16, v176
	v_and_b32_e32 v241, 0xffff0000, v176
	v_pk_add_f32 v[4:5], v[4:5], v[240:241]
	v_lshlrev_b32_e32 v240, 16, v177
	v_and_b32_e32 v241, 0xffff0000, v177
	v_pk_add_f32 v[6:7], v[6:7], v[240:241]
	v_lshlrev_b32_e32 v240, 16, v178
	v_and_b32_e32 v241, 0xffff0000, v178
	v_pk_add_f32 v[0:1], v[0:1], v[240:241]
	v_lshlrev_b32_e32 v240, 16, v179
	v_and_b32_e32 v241, 0xffff0000, v179
	v_pk_add_f32 v[2:3], v[2:3], v[240:241]
	s_add_u32 s42, s10, 0x20000
	s_addc_u32 s43, s11, 0
	global_load_dwordx4 v[176:179], v203, s[42:43]
	s_waitcnt vmcnt(8)
	v_pk_fma_f32 v[124:125], v[148:149], v[124:125], v[180:181]
	v_pk_fma_f32 v[126:127], v[150:151], v[126:127], v[182:183]
	s_add_u32 s98, s10, 0x0
	s_addc_u32 s99, s11, 0
	global_store_dwordx4 v203, v[124:127], s[98:99] nt
	s_add_u32 s42, s10, 0x20000
	s_addc_u32 s43, s11, 0
	global_load_dwordx4 v[180:183], v203, s[42:43] offset:16
	s_waitcnt vmcnt(9)
	v_pk_fma_f32 v[120:121], v[144:145], v[120:121], v[206:207]
	v_pk_fma_f32 v[122:123], v[146:147], v[122:123], v[208:209]
	s_add_u32 s98, s10, 0x0
	s_addc_u32 s99, s11, 0
	global_store_dwordx4 v203, v[120:123], s[98:99] offset:16 nt
	s_add_u32 s42, s10, 0x20200
	s_addc_u32 s43, s11, 0
	global_load_dwordx4 v[206:209], v203, s[42:43]
	s_waitcnt vmcnt(10)
	v_pk_fma_f32 v[92:93], v[156:157], v[92:93], v[210:211]
	v_pk_fma_f32 v[94:95], v[158:159], v[94:95], v[212:213]
	s_add_u32 s98, s10, 0x200
	s_addc_u32 s99, s11, 0
	global_store_dwordx4 v203, v[92:95], s[98:99] nt
	s_add_u32 s42, s10, 0x20200
	s_addc_u32 s43, s11, 0
	global_load_dwordx4 v[210:213], v203, s[42:43] offset:16
	s_waitcnt vmcnt(11)
	v_pk_fma_f32 v[88:89], v[152:153], v[88:89], v[236:237]
	v_pk_fma_f32 v[90:91], v[154:155], v[90:91], v[238:239]
	s_add_u32 s98, s10, 0x200
	s_addc_u32 s99, s11, 0
	global_store_dwordx4 v203, v[88:91], s[98:99] offset:16 nt
	s_add_u32 s42, s10, 0x30000
	s_addc_u32 s43, s11, 0
	global_load_dwordx4 v[236:239], v203, s[42:43]
	s_waitcnt vmcnt(12)
	v_pk_fma_f32 v[116:117], v[148:149], v[116:117], v[160:161]
	v_pk_fma_f32 v[118:119], v[150:151], v[118:119], v[162:163]
	s_add_u32 s98, s10, 0x10000
	s_addc_u32 s99, s11, 0
	global_store_dwordx4 v203, v[116:119], s[98:99] nt
	s_add_u32 s42, s10, 0x30000
	s_addc_u32 s43, s11, 0
	global_load_dwordx4 v[160:163], v203, s[42:43] offset:16
	s_waitcnt vmcnt(13)
	v_pk_fma_f32 v[112:113], v[144:145], v[112:113], v[164:165]
	v_pk_fma_f32 v[114:115], v[146:147], v[114:115], v[166:167]
	s_add_u32 s98, s10, 0x10000
	s_addc_u32 s99, s11, 0
	global_store_dwordx4 v203, v[112:115], s[98:99] offset:16 nt
	s_add_u32 s42, s10, 0x30200
	s_addc_u32 s43, s11, 0
	global_load_dwordx4 v[164:167], v203, s[42:43]
	s_waitcnt vmcnt(14)
	v_pk_fma_f32 v[84:85], v[156:157], v[84:85], v[168:169]
	v_pk_fma_f32 v[86:87], v[158:159], v[86:87], v[170:171]
	s_add_u32 s98, s10, 0x10200
	s_addc_u32 s99, s11, 0
	global_store_dwordx4 v203, v[84:87], s[98:99] nt
	s_add_u32 s42, s10, 0x30200
	s_addc_u32 s43, s11, 0
	global_load_dwordx4 v[168:171], v203, s[42:43] offset:16
	s_waitcnt vmcnt(15)
	v_pk_fma_f32 v[80:81], v[152:153], v[80:81], v[172:173]
	v_pk_fma_f32 v[82:83], v[154:155], v[82:83], v[174:175]
	s_add_u32 s98, s10, 0x10200
	s_addc_u32 s99, s11, 0
	global_store_dwordx4 v203, v[80:83], s[98:99] offset:16 nt
	s_add_u32 s42, s10, 0x80000
	s_addc_u32 s43, s11, 0
	global_load_dwordx4 v[172:175], v203, s[42:43]
	s_waitcnt vmcnt(16)
	v_pk_fma_f32 v[108:109], v[148:149], v[108:109], v[176:177]
	v_pk_fma_f32 v[110:111], v[150:151], v[110:111], v[178:179]
	s_add_u32 s98, s10, 0x20000
	s_addc_u32 s99, s11, 0
	global_store_dwordx4 v203, v[108:111], s[98:99] nt
	s_add_u32 s42, s10, 0x80000
	s_addc_u32 s43, s11, 0
	global_load_dwordx4 v[176:179], v203, s[42:43] offset:16
	s_waitcnt vmcnt(16)
	v_pk_fma_f32 v[104:105], v[144:145], v[104:105], v[180:181]
	v_pk_fma_f32 v[106:107], v[146:147], v[106:107], v[182:183]
	s_add_u32 s98, s10, 0x20000
	s_addc_u32 s99, s11, 0
	global_store_dwordx4 v203, v[104:107], s[98:99] offset:16 nt
	s_add_u32 s42, s10, 0x80200
	s_addc_u32 s43, s11, 0
	global_load_dwordx4 v[180:183], v203, s[42:43]
	s_waitcnt vmcnt(16)
	v_pk_fma_f32 v[76:77], v[156:157], v[76:77], v[206:207]
	v_pk_fma_f32 v[78:79], v[158:159], v[78:79], v[208:209]
	s_add_u32 s98, s10, 0x20200
	s_addc_u32 s99, s11, 0
	global_store_dwordx4 v203, v[76:79], s[98:99] nt
	s_add_u32 s42, s10, 0x80200
	s_addc_u32 s43, s11, 0
	global_load_dwordx4 v[206:209], v203, s[42:43] offset:16
	s_waitcnt vmcnt(16)
	v_pk_fma_f32 v[72:73], v[152:153], v[72:73], v[210:211]
	v_pk_fma_f32 v[74:75], v[154:155], v[74:75], v[212:213]
	s_add_u32 s98, s10, 0x20200
	s_addc_u32 s99, s11, 0
	global_store_dwordx4 v203, v[72:75], s[98:99] offset:16 nt
	s_add_u32 s42, s10, 0x90000
	s_addc_u32 s43, s11, 0
	global_load_dwordx4 v[210:213], v203, s[42:43]
	s_waitcnt vmcnt(16)
	v_pk_fma_f32 v[100:101], v[148:149], v[100:101], v[236:237]
	v_pk_fma_f32 v[102:103], v[150:151], v[102:103], v[238:239]
	s_add_u32 s98, s10, 0x30000
	s_addc_u32 s99, s11, 0
	global_store_dwordx4 v203, v[100:103], s[98:99] nt
	s_add_u32 s42, s10, 0x90000
	s_addc_u32 s43, s11, 0
	global_load_dwordx4 v[236:239], v203, s[42:43] offset:16
	s_waitcnt vmcnt(16)
	v_pk_fma_f32 v[96:97], v[144:145], v[96:97], v[160:161]
	v_pk_fma_f32 v[98:99], v[146:147], v[98:99], v[162:163]
	s_add_u32 s98, s10, 0x30000
	s_addc_u32 s99, s11, 0
	global_store_dwordx4 v203, v[96:99], s[98:99] offset:16 nt
	s_add_u32 s42, s10, 0x90200
	s_addc_u32 s43, s11, 0
	global_load_dwordx4 v[160:163], v203, s[42:43]
	s_waitcnt vmcnt(16)
	v_pk_fma_f32 v[68:69], v[156:157], v[68:69], v[164:165]
	v_pk_fma_f32 v[70:71], v[158:159], v[70:71], v[166:167]
	s_add_u32 s98, s10, 0x30200
	s_addc_u32 s99, s11, 0
	global_store_dwordx4 v203, v[68:71], s[98:99] nt
	s_add_u32 s42, s10, 0x90200
	s_addc_u32 s43, s11, 0
	global_load_dwordx4 v[164:167], v203, s[42:43] offset:16
	s_waitcnt vmcnt(16)
	v_pk_fma_f32 v[64:65], v[152:153], v[64:65], v[168:169]
	v_pk_fma_f32 v[66:67], v[154:155], v[66:67], v[170:171]
	s_add_u32 s98, s10, 0x30200
	s_addc_u32 s99, s11, 0
	global_store_dwordx4 v203, v[64:67], s[98:99] offset:16 nt
	s_add_u32 s42, s10, 0xa0000
	s_addc_u32 s43, s11, 0
	global_load_dwordx4 v[168:171], v203, s[42:43]
	s_waitcnt vmcnt(16)
	v_pk_fma_f32 v[60:61], v[148:149], v[60:61], v[172:173]
	v_pk_fma_f32 v[62:63], v[150:151], v[62:63], v[174:175]
	s_add_u32 s98, s10, 0x80000
	s_addc_u32 s99, s11, 0
	global_store_dwordx4 v203, v[60:63], s[98:99] nt
	s_add_u32 s42, s10, 0xa0000
	s_addc_u32 s43, s11, 0
	global_load_dwordx4 v[172:175], v203, s[42:43] offset:16
	s_waitcnt vmcnt(16)
	v_pk_fma_f32 v[56:57], v[144:145], v[56:57], v[176:177]
	v_pk_fma_f32 v[58:59], v[146:147], v[58:59], v[178:179]
	s_add_u32 s98, s10, 0x80000
	s_addc_u32 s99, s11, 0
	global_store_dwordx4 v203, v[56:59], s[98:99] offset:16 nt
	s_add_u32 s42, s10, 0xa0200
	s_addc_u32 s43, s11, 0
	global_load_dwordx4 v[176:179], v203, s[42:43]
	s_waitcnt vmcnt(16)
	v_pk_fma_f32 v[28:29], v[156:157], v[28:29], v[180:181]
	v_pk_fma_f32 v[30:31], v[158:159], v[30:31], v[182:183]
	s_add_u32 s98, s10, 0x80200
	s_addc_u32 s99, s11, 0
	global_store_dwordx4 v203, v[28:31], s[98:99] nt
	s_add_u32 s42, s10, 0xa0200
	s_addc_u32 s43, s11, 0
	global_load_dwordx4 v[180:183], v203, s[42:43] offset:16
	s_waitcnt vmcnt(16)
	v_pk_fma_f32 v[24:25], v[152:153], v[24:25], v[206:207]
	v_pk_fma_f32 v[26:27], v[154:155], v[26:27], v[208:209]
	s_add_u32 s98, s10, 0x80200
	s_addc_u32 s99, s11, 0
	global_store_dwordx4 v203, v[24:27], s[98:99] offset:16 nt
	s_add_u32 s42, s10, 0xb0000
	s_addc_u32 s43, s11, 0
	global_load_dwordx4 v[206:209], v203, s[42:43]
	s_waitcnt vmcnt(16)
	v_pk_fma_f32 v[52:53], v[148:149], v[52:53], v[210:211]
	v_pk_fma_f32 v[54:55], v[150:151], v[54:55], v[212:213]
	s_add_u32 s98, s10, 0x90000
	s_addc_u32 s99, s11, 0
	global_store_dwordx4 v203, v[52:55], s[98:99] nt
	s_add_u32 s42, s10, 0xb0000
	s_addc_u32 s43, s11, 0
	global_load_dwordx4 v[210:213], v203, s[42:43] offset:16
	s_waitcnt vmcnt(16)
	v_pk_fma_f32 v[48:49], v[144:145], v[48:49], v[236:237]
	v_pk_fma_f32 v[50:51], v[146:147], v[50:51], v[238:239]
	s_add_u32 s98, s10, 0x90000
	s_addc_u32 s99, s11, 0
	global_store_dwordx4 v203, v[48:51], s[98:99] offset:16 nt
	s_add_u32 s42, s10, 0xb0200
	s_addc_u32 s43, s11, 0
	global_load_dwordx4 v[236:239], v203, s[42:43]
	s_waitcnt vmcnt(16)
	v_pk_fma_f32 v[20:21], v[156:157], v[20:21], v[160:161]
	v_pk_fma_f32 v[22:23], v[158:159], v[22:23], v[162:163]
	s_add_u32 s98, s10, 0x90200
	s_addc_u32 s99, s11, 0
	global_store_dwordx4 v203, v[20:23], s[98:99] nt
	s_add_u32 s42, s10, 0xb0200
	s_addc_u32 s43, s11, 0
	global_load_dwordx4 v[160:163], v203, s[42:43] offset:16
	s_waitcnt vmcnt(16)
	v_pk_fma_f32 v[16:17], v[152:153], v[16:17], v[164:165]
	v_pk_fma_f32 v[18:19], v[154:155], v[18:19], v[166:167]
	s_add_u32 s98, s10, 0x90200
	s_addc_u32 s99, s11, 0
	global_store_dwordx4 v203, v[16:19], s[98:99] offset:16 nt
	s_waitcnt vmcnt(15)
	v_pk_fma_f32 v[44:45], v[148:149], v[44:45], v[168:169]
	v_pk_fma_f32 v[46:47], v[150:151], v[46:47], v[170:171]
	s_add_u32 s42, s10, 0xa0000
	s_addc_u32 s43, s11, 0
	global_store_dwordx4 v203, v[44:47], s[42:43] nt
	s_waitcnt vmcnt(14)
	v_pk_fma_f32 v[40:41], v[144:145], v[40:41], v[172:173]
	v_pk_fma_f32 v[42:43], v[146:147], v[42:43], v[174:175]
	s_add_u32 s98, s10, 0xa0000
	s_addc_u32 s99, s11, 0
	global_store_dwordx4 v203, v[40:43], s[98:99] offset:16 nt
	s_waitcnt vmcnt(13)
	v_pk_fma_f32 v[12:13], v[156:157], v[12:13], v[176:177]
	v_pk_fma_f32 v[14:15], v[158:159], v[14:15], v[178:179]
	s_add_u32 s42, s10, 0xa0200
	s_addc_u32 s43, s11, 0
	global_store_dwordx4 v203, v[12:15], s[42:43] nt
	s_waitcnt vmcnt(12)
	v_pk_fma_f32 v[8:9], v[152:153], v[8:9], v[180:181]
	v_pk_fma_f32 v[10:11], v[154:155], v[10:11], v[182:183]
	s_add_u32 s98, s10, 0xa0200
	s_addc_u32 s99, s11, 0
	global_store_dwordx4 v203, v[8:11], s[98:99] offset:16 nt
	s_waitcnt vmcnt(11)
	v_pk_fma_f32 v[36:37], v[148:149], v[36:37], v[206:207]
	v_pk_fma_f32 v[38:39], v[150:151], v[38:39], v[208:209]
	s_add_u32 s42, s10, 0xb0000
	s_addc_u32 s43, s11, 0
	global_store_dwordx4 v203, v[36:39], s[42:43] nt
	s_waitcnt vmcnt(10)
	v_pk_fma_f32 v[32:33], v[144:145], v[32:33], v[210:211]
	v_pk_fma_f32 v[34:35], v[146:147], v[34:35], v[212:213]
	s_add_u32 s98, s10, 0xb0000
	s_addc_u32 s99, s11, 0
	global_store_dwordx4 v203, v[32:35], s[98:99] offset:16 nt
	s_waitcnt vmcnt(9)
	v_pk_fma_f32 v[4:5], v[156:157], v[4:5], v[236:237]
	v_pk_fma_f32 v[6:7], v[158:159], v[6:7], v[238:239]
	s_add_u32 s42, s10, 0xb0200
	s_addc_u32 s43, s11, 0
	global_store_dwordx4 v203, v[4:7], s[42:43] nt
	s_waitcnt vmcnt(8)
	v_pk_fma_f32 v[0:1], v[152:153], v[0:1], v[160:161]
	v_pk_fma_f32 v[2:3], v[154:155], v[2:3], v[162:163]
	s_add_u32 s98, s10, 0xb0200
	s_addc_u32 s99, s11, 0
	global_store_dwordx4 v203, v[0:3], s[98:99] offset:16 nt
	s_branch .Lfq_predone
.Lfq_np1:
	s_add_u32 s42, s62, 0x0
	s_addc_u32 s43, s63, 0
	global_load_dwordx4 v[160:163], v205, s[42:43] sc0 sc1
	s_add_u32 s98, s62, 0x1000
	s_addc_u32 s99, s63, 0
	global_load_dwordx4 v[164:167], v205, s[98:99] sc0 sc1
	s_add_u32 s42, s62, 0x400
	s_addc_u32 s43, s63, 0
	global_load_dwordx4 v[168:171], v205, s[42:43] sc0 sc1
	s_add_u32 s98, s62, 0x1400
	s_addc_u32 s99, s63, 0
	global_load_dwordx4 v[172:175], v205, s[98:99] sc0 sc1
	s_add_u32 s42, s62, 0x800
	s_addc_u32 s43, s63, 0
	global_load_dwordx4 v[176:179], v205, s[42:43] sc0 sc1
	s_add_u32 s98, s62, 0x1800
	s_addc_u32 s99, s63, 0
	global_load_dwordx4 v[180:183], v205, s[98:99] sc0 sc1
	s_add_u32 s42, s62, 0xc00
	s_addc_u32 s43, s63, 0
	global_load_dwordx4 v[206:209], v205, s[42:43] sc0 sc1
	s_add_u32 s98, s62, 0x1c00
	s_addc_u32 s99, s63, 0
	global_load_dwordx4 v[210:213], v205, s[98:99] sc0 sc1
	s_add_u32 s42, s62, 0x2000
	s_addc_u32 s43, s63, 0
	global_load_dwordx4 v[236:239], v205, s[42:43] sc0 sc1
	s_waitcnt vmcnt(8)
	v_lshlrev_b32_e32 v240, 16, v160
	v_and_b32_e32 v241, 0xffff0000, v160
	v_pk_add_f32 v[124:125], v[124:125], v[240:241]
	v_lshlrev_b32_e32 v240, 16, v161
	v_and_b32_e32 v241, 0xffff0000, v161
	v_pk_add_f32 v[126:127], v[126:127], v[240:241]
	v_lshlrev_b32_e32 v240, 16, v162
	v_and_b32_e32 v241, 0xffff0000, v162
	v_pk_add_f32 v[120:121], v[120:121], v[240:241]
	v_lshlrev_b32_e32 v240, 16, v163
	v_and_b32_e32 v241, 0xffff0000, v163
	v_pk_add_f32 v[122:123], v[122:123], v[240:241]
	s_add_u32 s98, s62, 0x3000
	s_addc_u32 s99, s63, 0
	global_load_dwordx4 v[160:163], v205, s[98:99] sc0 sc1
	s_waitcnt vmcnt(8)
	v_lshlrev_b32_e32 v240, 16, v164
	v_and_b32_e32 v241, 0xffff0000, v164
	v_pk_add_f32 v[92:93], v[92:93], v[240:241]
	v_lshlrev_b32_e32 v240, 16, v165
	v_and_b32_e32 v241, 0xffff0000, v165
	v_pk_add_f32 v[94:95], v[94:95], v[240:241]
	v_lshlrev_b32_e32 v240, 16, v166
	v_and_b32_e32 v241, 0xffff0000, v166
	v_pk_add_f32 v[88:89], v[88:89], v[240:241]
	v_lshlrev_b32_e32 v240, 16, v167
	v_and_b32_e32 v241, 0xffff0000, v167
	v_pk_add_f32 v[90:91], v[90:91], v[240:241]
	s_add_u32 s42, s62, 0x2400
	s_addc_u32 s43, s63, 0
	global_load_dwordx4 v[164:167], v205, s[42:43] sc0 sc1
	s_waitcnt vmcnt(8)
	v_lshlrev_b32_e32 v240, 16, v168
	v_and_b32_e32 v241, 0xffff0000, v168
	v_pk_add_f32 v[116:117], v[116:117], v[240:241]
	v_lshlrev_b32_e32 v240, 16, v169
	v_and_b32_e32 v241, 0xffff0000, v169
	v_pk_add_f32 v[118:119], v[118:119], v[240:241]
	v_lshlrev_b32_e32 v240, 16, v170
	v_and_b32_e32 v241, 0xffff0000, v170
	v_pk_add_f32 v[112:113], v[112:113], v[240:241]
	v_lshlrev_b32_e32 v240, 16, v171
	v_and_b32_e32 v241, 0xffff0000, v171
	v_pk_add_f32 v[114:115], v[114:115], v[240:241]
	s_add_u32 s98, s62, 0x3400
	s_addc_u32 s99, s63, 0
	global_load_dwordx4 v[168:171], v205, s[98:99] sc0 sc1
	s_waitcnt vmcnt(8)
	v_lshlrev_b32_e32 v240, 16, v172
	v_and_b32_e32 v241, 0xffff0000, v172
	v_pk_add_f32 v[84:85], v[84:85], v[240:241]
	v_lshlrev_b32_e32 v240, 16, v173
	v_and_b32_e32 v241, 0xffff0000, v173
	v_pk_add_f32 v[86:87], v[86:87], v[240:241]
	v_lshlrev_b32_e32 v240, 16, v174
	v_and_b32_e32 v241, 0xffff0000, v174
	v_pk_add_f32 v[80:81], v[80:81], v[240:241]
	v_lshlrev_b32_e32 v240, 16, v175
	v_and_b32_e32 v241, 0xffff0000, v175
	v_pk_add_f32 v[82:83], v[82:83], v[240:241]
	s_add_u32 s42, s62, 0x2800
	s_addc_u32 s43, s63, 0
	global_load_dwordx4 v[172:175], v205, s[42:43] sc0 sc1
	s_waitcnt vmcnt(8)
	v_lshlrev_b32_e32 v240, 16, v176
	v_and_b32_e32 v241, 0xffff0000, v176
	v_pk_add_f32 v[108:109], v[108:109], v[240:241]
	v_lshlrev_b32_e32 v240, 16, v177
	v_and_b32_e32 v241, 0xffff0000, v177
	v_pk_add_f32 v[110:111], v[110:111], v[240:241]
	v_lshlrev_b32_e32 v240, 16, v178
	v_and_b32_e32 v241, 0xffff0000, v178
	v_pk_add_f32 v[104:105], v[104:105], v[240:241]
	v_lshlrev_b32_e32 v240, 16, v179
	v_and_b32_e32 v241, 0xffff0000, v179
	v_pk_add_f32 v[106:107], v[106:107], v[240:241]
	s_add_u32 s98, s62, 0x3800
	s_addc_u32 s99, s63, 0
	global_load_dwordx4 v[176:179], v205, s[98:99] sc0 sc1
	s_waitcnt vmcnt(8)
	v_lshlrev_b32_e32 v240, 16, v180
	v_and_b32_e32 v241, 0xffff0000, v180
	v_pk_add_f32 v[76:77], v[76:77], v[240:241]
	v_lshlrev_b32_e32 v240, 16, v181
	v_and_b32_e32 v241, 0xffff0000, v181
	v_pk_add_f32 v[78:79], v[78:79], v[240:241]
	v_lshlrev_b32_e32 v240, 16, v182
	v_and_b32_e32 v241, 0xffff0000, v182
	v_pk_add_f32 v[72:73], v[72:73], v[240:241]
	v_lshlrev_b32_e32 v240, 16, v183
	v_and_b32_e32 v241, 0xffff0000, v183
	v_pk_add_f32 v[74:75], v[74:75], v[240:241]
	s_add_u32 s42, s62, 0x2c00
	s_addc_u32 s43, s63, 0
	global_load_dwordx4 v[180:183], v205, s[42:43] sc0 sc1
	s_waitcnt vmcnt(8)
	v_lshlrev_b32_e32 v240, 16, v206
	v_and_b32_e32 v241, 0xffff0000, v206
	v_pk_add_f32 v[100:101], v[100:101], v[240:241]
	v_lshlrev_b32_e32 v240, 16, v207
	v_and_b32_e32 v241, 0xffff0000, v207
	v_pk_add_f32 v[102:103], v[102:103], v[240:241]
	v_lshlrev_b32_e32 v240, 16, v208
	v_and_b32_e32 v241, 0xffff0000, v208
	v_pk_add_f32 v[96:97], v[96:97], v[240:241]
	v_lshlrev_b32_e32 v240, 16, v209
	v_and_b32_e32 v241, 0xffff0000, v209
	v_pk_add_f32 v[98:99], v[98:99], v[240:241]
	s_add_u32 s98, s62, 0x3c00
	s_addc_u32 s99, s63, 0
	global_load_dwordx4 v[206:209], v205, s[98:99] sc0 sc1
	s_waitcnt vmcnt(8)
	v_lshlrev_b32_e32 v240, 16, v210
	v_and_b32_e32 v241, 0xffff0000, v210
	v_pk_add_f32 v[68:69], v[68:69], v[240:241]
	v_lshlrev_b32_e32 v240, 16, v211
	v_and_b32_e32 v241, 0xffff0000, v211
	v_pk_add_f32 v[70:71], v[70:71], v[240:241]
	v_lshlrev_b32_e32 v240, 16, v212
	v_and_b32_e32 v241, 0xffff0000, v212
	v_pk_add_f32 v[64:65], v[64:65], v[240:241]
	v_lshlrev_b32_e32 v240, 16, v213
	v_and_b32_e32 v241, 0xffff0000, v213
	v_pk_add_f32 v[66:67], v[66:67], v[240:241]
	s_add_u32 s42, s10, 0x0
	s_addc_u32 s43, s11, 0
	global_load_dwordx4 v[210:213], v203, s[42:43]
	s_waitcnt vmcnt(8)
	v_lshlrev_b32_e32 v240, 16, v236
	v_and_b32_e32 v241, 0xffff0000, v236
	v_pk_add_f32 v[60:61], v[60:61], v[240:241]
	v_lshlrev_b32_e32 v240, 16, v237
	v_and_b32_e32 v241, 0xffff0000, v237
	v_pk_add_f32 v[62:63], v[62:63], v[240:241]
	v_lshlrev_b32_e32 v240, 16, v238
	v_and_b32_e32 v241, 0xffff0000, v238
	v_pk_add_f32 v[56:57], v[56:57], v[240:241]
	v_lshlrev_b32_e32 v240, 16, v239
	v_and_b32_e32 v241, 0xffff0000, v239
	v_pk_add_f32 v[58:59], v[58:59], v[240:241]
	s_add_u32 s98, s10, 0x0
	s_addc_u32 s99, s11, 0
	global_load_dwordx4 v[236:239], v203, s[98:99] offset:16
	s_waitcnt vmcnt(8)
	v_lshlrev_b32_e32 v240, 16, v160
	v_and_b32_e32 v241, 0xffff0000, v160
	v_pk_add_f32 v[28:29], v[28:29], v[240:241]
	v_lshlrev_b32_e32 v240, 16, v161
	v_and_b32_e32 v241, 0xffff0000, v161
	v_pk_add_f32 v[30:31], v[30:31], v[240:241]
	v_lshlrev_b32_e32 v240, 16, v162
	v_and_b32_e32 v241, 0xffff0000, v162
	v_pk_add_f32 v[24:25], v[24:25], v[240:241]
	v_lshlrev_b32_e32 v240, 16, v163
	v_and_b32_e32 v241, 0xffff0000, v163
	v_pk_add_f32 v[26:27], v[26:27], v[240:241]
	s_add_u32 s42, s10, 0x200
	s_addc_u32 s43, s11, 0
	global_load_dwordx4 v[160:163], v203, s[42:43]
	s_waitcnt vmcnt(8)
	v_lshlrev_b32_e32 v240, 16, v164
	v_and_b32_e32 v241, 0xffff0000, v164
	v_pk_add_f32 v[52:53], v[52:53], v[240:241]
	v_lshlrev_b32_e32 v240, 16, v165
	v_and_b32_e32 v241, 0xffff0000, v165
	v_pk_add_f32 v[54:55], v[54:55], v[240:241]
	v_lshlrev_b32_e32 v240, 16, v166
	v_and_b32_e32 v241, 0xffff0000, v166
	v_pk_add_f32 v[48:49], v[48:49], v[240:241]
	v_lshlrev_b32_e32 v240, 16, v167
	v_and_b32_e32 v241, 0xffff0000, v167
	v_pk_add_f32 v[50:51], v[50:51], v[240:241]
	s_add_u32 s98, s10, 0x200
	s_addc_u32 s99, s11, 0
	global_load_dwordx4 v[164:167], v203, s[98:99] offset:16
	s_waitcnt vmcnt(8)
	v_lshlrev_b32_e32 v240, 16, v168
	v_and_b32_e32 v241, 0xffff0000, v168
	v_pk_add_f32 v[20:21], v[20:21], v[240:241]
	v_lshlrev_b32_e32 v240, 16, v169
	v_and_b32_e32 v241, 0xffff0000, v169
	v_pk_add_f32 v[22:23], v[22:23], v[240:241]
	v_lshlrev_b32_e32 v240, 16, v170
	v_and_b32_e32 v241, 0xffff0000, v170
	v_pk_add_f32 v[16:17], v[16:17], v[240:241]
	v_lshlrev_b32_e32 v240, 16, v171
	v_and_b32_e32 v241, 0xffff0000, v171
	v_pk_add_f32 v[18:19], v[18:19], v[240:241]
	s_add_u32 s42, s10, 0x10000
	s_addc_u32 s43, s11, 0
	global_load_dwordx4 v[168:171], v203, s[42:43]
	s_waitcnt vmcnt(8)
	v_lshlrev_b32_e32 v240, 16, v172
	v_and_b32_e32 v241, 0xffff0000, v172
	v_pk_add_f32 v[44:45], v[44:45], v[240:241]
	v_lshlrev_b32_e32 v240, 16, v173
	v_and_b32_e32 v241, 0xffff0000, v173
	v_pk_add_f32 v[46:47], v[46:47], v[240:241]
	v_lshlrev_b32_e32 v240, 16, v174
	v_and_b32_e32 v241, 0xffff0000, v174
	v_pk_add_f32 v[40:41], v[40:41], v[240:241]
	v_lshlrev_b32_e32 v240, 16, v175
	v_and_b32_e32 v241, 0xffff0000, v175
	v_pk_add_f32 v[42:43], v[42:43], v[240:241]
	s_add_u32 s98, s10, 0x10000
	s_addc_u32 s99, s11, 0
	global_load_dwordx4 v[172:175], v203, s[98:99] offset:16
	s_waitcnt vmcnt(8)
	v_lshlrev_b32_e32 v240, 16, v176
	v_and_b32_e32 v241, 0xffff0000, v176
	v_pk_add_f32 v[12:13], v[12:13], v[240:241]
	v_lshlrev_b32_e32 v240, 16, v177
	v_and_b32_e32 v241, 0xffff0000, v177
	v_pk_add_f32 v[14:15], v[14:15], v[240:241]
	v_lshlrev_b32_e32 v240, 16, v178
	v_and_b32_e32 v241, 0xffff0000, v178
	v_pk_add_f32 v[8:9], v[8:9], v[240:241]
	v_lshlrev_b32_e32 v240, 16, v179
	v_and_b32_e32 v241, 0xffff0000, v179
	v_pk_add_f32 v[10:11], v[10:11], v[240:241]
	s_add_u32 s42, s10, 0x10200
	s_addc_u32 s43, s11, 0
	global_load_dwordx4 v[176:179], v203, s[42:43]
	s_waitcnt vmcnt(8)
	v_lshlrev_b32_e32 v240, 16, v180
	v_and_b32_e32 v241, 0xffff0000, v180
	v_pk_add_f32 v[36:37], v[36:37], v[240:241]
	v_lshlrev_b32_e32 v240, 16, v181
	v_and_b32_e32 v241, 0xffff0000, v181
	v_pk_add_f32 v[38:39], v[38:39], v[240:241]
	v_lshlrev_b32_e32 v240, 16, v182
	v_and_b32_e32 v241, 0xffff0000, v182
	v_pk_add_f32 v[32:33], v[32:33], v[240:241]
	v_lshlrev_b32_e32 v240, 16, v183
	v_and_b32_e32 v241, 0xffff0000, v183
	v_pk_add_f32 v[34:35], v[34:35], v[240:241]
	s_add_u32 s98, s10, 0x10200
	s_addc_u32 s99, s11, 0
	global_load_dwordx4 v[180:183], v203, s[98:99] offset:16
	s_waitcnt vmcnt(8)
	v_lshlrev_b32_e32 v240, 16, v206
	v_and_b32_e32 v241, 0xffff0000, v206
	v_pk_add_f32 v[4:5], v[4:5], v[240:241]
	v_lshlrev_b32_e32 v240, 16, v207
	v_and_b32_e32 v241, 0xffff0000, v207
	v_pk_add_f32 v[6:7], v[6:7], v[240:241]
	v_lshlrev_b32_e32 v240, 16, v208
	v_and_b32_e32 v241, 0xffff0000, v208
	v_pk_add_f32 v[0:1], v[0:1], v[240:241]
	v_lshlrev_b32_e32 v240, 16, v209
	v_and_b32_e32 v241, 0xffff0000, v209
	v_pk_add_f32 v[2:3], v[2:3], v[240:241]
	s_add_u32 s42, s10, 0x20000
	s_addc_u32 s43, s11, 0
	global_load_dwordx4 v[206:209], v203, s[42:43]
	s_waitcnt vmcnt(8)
	v_pk_fma_f32 v[124:125], v[148:149], v[124:125], v[210:211]
	v_pk_fma_f32 v[126:127], v[150:151], v[126:127], v[212:213]
	s_add_u32 s98, s10, 0x0
	s_addc_u32 s99, s11, 0
	global_store_dwordx4 v203, v[124:127], s[98:99] nt
	s_add_u32 s42, s10, 0x20000
	s_addc_u32 s43, s11, 0
	global_load_dwordx4 v[210:213], v203, s[42:43] offset:16
	s_waitcnt vmcnt(9)
	v_pk_fma_f32 v[120:121], v[144:145], v[120:121], v[236:237]
	v_pk_fma_f32 v[122:123], v[146:147], v[122:123], v[238:239]
	s_add_u32 s98, s10, 0x0
	s_addc_u32 s99, s11, 0
	global_store_dwordx4 v203, v[120:123], s[98:99] offset:16 nt
	s_add_u32 s42, s10, 0x20200
	s_addc_u32 s43, s11, 0
	global_load_dwordx4 v[236:239], v203, s[42:43]
	s_waitcnt vmcnt(10)
	v_pk_fma_f32 v[92:93], v[156:157], v[92:93], v[160:161]
	v_pk_fma_f32 v[94:95], v[158:159], v[94:95], v[162:163]
	s_add_u32 s98, s10, 0x200
	s_addc_u32 s99, s11, 0
	global_store_dwordx4 v203, v[92:95], s[98:99] nt
	s_add_u32 s42, s10, 0x20200
	s_addc_u32 s43, s11, 0
	global_load_dwordx4 v[160:163], v203, s[42:43] offset:16
	s_waitcnt vmcnt(11)
	v_pk_fma_f32 v[88:89], v[152:153], v[88:89], v[164:165]
	v_pk_fma_f32 v[90:91], v[154:155], v[90:91], v[166:167]
	s_add_u32 s98, s10, 0x200
	s_addc_u32 s99, s11, 0
	global_store_dwordx4 v203, v[88:91], s[98:99] offset:16 nt
	s_add_u32 s42, s10, 0x30000
	s_addc_u32 s43, s11, 0
	global_load_dwordx4 v[164:167], v203, s[42:43]
	s_waitcnt vmcnt(12)
	v_pk_fma_f32 v[116:117], v[148:149], v[116:117], v[168:169]
	v_pk_fma_f32 v[118:119], v[150:151], v[118:119], v[170:171]
	s_add_u32 s98, s10, 0x10000
	s_addc_u32 s99, s11, 0
	global_store_dwordx4 v203, v[116:119], s[98:99] nt
	s_add_u32 s42, s10, 0x30000
	s_addc_u32 s43, s11, 0
	global_load_dwordx4 v[168:171], v203, s[42:43] offset:16
	s_waitcnt vmcnt(13)
	v_pk_fma_f32 v[112:113], v[144:145], v[112:113], v[172:173]
	v_pk_fma_f32 v[114:115], v[146:147], v[114:115], v[174:175]
	s_add_u32 s98, s10, 0x10000
	s_addc_u32 s99, s11, 0
	global_store_dwordx4 v203, v[112:115], s[98:99] offset:16 nt
	s_add_u32 s42, s10, 0x30200
	s_addc_u32 s43, s11, 0
	global_load_dwordx4 v[172:175], v203, s[42:43]
	s_waitcnt vmcnt(14)
	v_pk_fma_f32 v[84:85], v[156:157], v[84:85], v[176:177]
	v_pk_fma_f32 v[86:87], v[158:159], v[86:87], v[178:179]
	s_add_u32 s98, s10, 0x10200
	s_addc_u32 s99, s11, 0
	global_store_dwordx4 v203, v[84:87], s[98:99] nt
	s_add_u32 s42, s10, 0x30200
	s_addc_u32 s43, s11, 0
	global_load_dwordx4 v[176:179], v203, s[42:43] offset:16
	s_waitcnt vmcnt(15)
	v_pk_fma_f32 v[80:81], v[152:153], v[80:81], v[180:181]
	v_pk_fma_f32 v[82:83], v[154:155], v[82:83], v[182:183]
	s_add_u32 s98, s10, 0x10200
	s_addc_u32 s99, s11, 0
	global_store_dwordx4 v203, v[80:83], s[98:99] offset:16 nt
	s_add_u32 s42, s10, 0x80000
	s_addc_u32 s43, s11, 0
	global_load_dwordx4 v[180:183], v203, s[42:43]
	s_waitcnt vmcnt(16)
	v_pk_fma_f32 v[108:109], v[148:149], v[108:109], v[206:207]
	v_pk_fma_f32 v[110:111], v[150:151], v[110:111], v[208:209]
	s_add_u32 s98, s10, 0x20000
	s_addc_u32 s99, s11, 0
	global_store_dwordx4 v203, v[108:111], s[98:99] nt
	s_add_u32 s42, s10, 0x80000
	s_addc_u32 s43, s11, 0
	global_load_dwordx4 v[206:209], v203, s[42:43] offset:16
	s_waitcnt vmcnt(16)
	v_pk_fma_f32 v[104:105], v[144:145], v[104:105], v[210:211]
	v_pk_fma_f32 v[106:107], v[146:147], v[106:107], v[212:213]
	s_add_u32 s98, s10, 0x20000
	s_addc_u32 s99, s11, 0
	global_store_dwordx4 v203, v[104:107], s[98:99] offset:16 nt
	s_add_u32 s42, s10, 0x80200
	s_addc_u32 s43, s11, 0
	global_load_dwordx4 v[210:213], v203, s[42:43]
	s_waitcnt vmcnt(16)
	v_pk_fma_f32 v[76:77], v[156:157], v[76:77], v[236:237]
	v_pk_fma_f32 v[78:79], v[158:159], v[78:79], v[238:239]
	s_add_u32 s98, s10, 0x20200
	s_addc_u32 s99, s11, 0
	global_store_dwordx4 v203, v[76:79], s[98:99] nt
	s_add_u32 s42, s10, 0x80200
	s_addc_u32 s43, s11, 0
	global_load_dwordx4 v[236:239], v203, s[42:43] offset:16
	s_waitcnt vmcnt(16)
	v_pk_fma_f32 v[72:73], v[152:153], v[72:73], v[160:161]
	v_pk_fma_f32 v[74:75], v[154:155], v[74:75], v[162:163]
	s_add_u32 s98, s10, 0x20200
	s_addc_u32 s99, s11, 0
	global_store_dwordx4 v203, v[72:75], s[98:99] offset:16 nt
	s_add_u32 s42, s10, 0x90000
	s_addc_u32 s43, s11, 0
	global_load_dwordx4 v[160:163], v203, s[42:43]
	s_waitcnt vmcnt(16)
	v_pk_fma_f32 v[100:101], v[148:149], v[100:101], v[164:165]
	v_pk_fma_f32 v[102:103], v[150:151], v[102:103], v[166:167]
	s_add_u32 s98, s10, 0x30000
	s_addc_u32 s99, s11, 0
	global_store_dwordx4 v203, v[100:103], s[98:99] nt
	s_add_u32 s42, s10, 0x90000
	s_addc_u32 s43, s11, 0
	global_load_dwordx4 v[164:167], v203, s[42:43] offset:16
	s_waitcnt vmcnt(16)
	v_pk_fma_f32 v[96:97], v[144:145], v[96:97], v[168:169]
	v_pk_fma_f32 v[98:99], v[146:147], v[98:99], v[170:171]
	s_add_u32 s98, s10, 0x30000
	s_addc_u32 s99, s11, 0
	global_store_dwordx4 v203, v[96:99], s[98:99] offset:16 nt
	s_add_u32 s42, s10, 0x90200
	s_addc_u32 s43, s11, 0
	global_load_dwordx4 v[168:171], v203, s[42:43]
	s_waitcnt vmcnt(16)
	v_pk_fma_f32 v[68:69], v[156:157], v[68:69], v[172:173]
	v_pk_fma_f32 v[70:71], v[158:159], v[70:71], v[174:175]
	s_add_u32 s98, s10, 0x30200
	s_addc_u32 s99, s11, 0
	global_store_dwordx4 v203, v[68:71], s[98:99] nt
	s_add_u32 s42, s10, 0x90200
	s_addc_u32 s43, s11, 0
	global_load_dwordx4 v[172:175], v203, s[42:43] offset:16
	s_waitcnt vmcnt(16)
	v_pk_fma_f32 v[64:65], v[152:153], v[64:65], v[176:177]
	v_pk_fma_f32 v[66:67], v[154:155], v[66:67], v[178:179]
	s_add_u32 s98, s10, 0x30200
	s_addc_u32 s99, s11, 0
	global_store_dwordx4 v203, v[64:67], s[98:99] offset:16 nt
	s_add_u32 s42, s10, 0xa0000
	s_addc_u32 s43, s11, 0
	global_load_dwordx4 v[176:179], v203, s[42:43]
	s_waitcnt vmcnt(16)
	v_pk_fma_f32 v[60:61], v[148:149], v[60:61], v[180:181]
	v_pk_fma_f32 v[62:63], v[150:151], v[62:63], v[182:183]
	s_add_u32 s98, s10, 0x80000
	s_addc_u32 s99, s11, 0
	global_store_dwordx4 v203, v[60:63], s[98:99] nt
	s_add_u32 s42, s10, 0xa0000
	s_addc_u32 s43, s11, 0
	global_load_dwordx4 v[180:183], v203, s[42:43] offset:16
	s_waitcnt vmcnt(16)
	v_pk_fma_f32 v[56:57], v[144:145], v[56:57], v[206:207]
	v_pk_fma_f32 v[58:59], v[146:147], v[58:59], v[208:209]
	s_add_u32 s98, s10, 0x80000
	s_addc_u32 s99, s11, 0
	global_store_dwordx4 v203, v[56:59], s[98:99] offset:16 nt
	s_add_u32 s42, s10, 0xa0200
	s_addc_u32 s43, s11, 0
	global_load_dwordx4 v[206:209], v203, s[42:43]
	s_waitcnt vmcnt(16)
	v_pk_fma_f32 v[28:29], v[156:157], v[28:29], v[210:211]
	v_pk_fma_f32 v[30:31], v[158:159], v[30:31], v[212:213]
	s_add_u32 s98, s10, 0x80200
	s_addc_u32 s99, s11, 0
	global_store_dwordx4 v203, v[28:31], s[98:99] nt
	s_add_u32 s42, s10, 0xa0200
	s_addc_u32 s43, s11, 0
	global_load_dwordx4 v[210:213], v203, s[42:43] offset:16
	s_waitcnt vmcnt(16)
	v_pk_fma_f32 v[24:25], v[152:153], v[24:25], v[236:237]
	v_pk_fma_f32 v[26:27], v[154:155], v[26:27], v[238:239]
	s_add_u32 s98, s10, 0x80200
	s_addc_u32 s99, s11, 0
	global_store_dwordx4 v203, v[24:27], s[98:99] offset:16 nt
	s_add_u32 s42, s10, 0xb0000
	s_addc_u32 s43, s11, 0
	global_load_dwordx4 v[236:239], v203, s[42:43]
	s_waitcnt vmcnt(16)
	v_pk_fma_f32 v[52:53], v[148:149], v[52:53], v[160:161]
	v_pk_fma_f32 v[54:55], v[150:151], v[54:55], v[162:163]
	s_add_u32 s98, s10, 0x90000
	s_addc_u32 s99, s11, 0
	global_store_dwordx4 v203, v[52:55], s[98:99] nt
	s_add_u32 s42, s10, 0xb0000
	s_addc_u32 s43, s11, 0
	global_load_dwordx4 v[160:163], v203, s[42:43] offset:16
	s_waitcnt vmcnt(16)
	v_pk_fma_f32 v[48:49], v[144:145], v[48:49], v[164:165]
	v_pk_fma_f32 v[50:51], v[146:147], v[50:51], v[166:167]
	s_add_u32 s98, s10, 0x90000
	s_addc_u32 s99, s11, 0
	global_store_dwordx4 v203, v[48:51], s[98:99] offset:16 nt
	s_add_u32 s42, s10, 0xb0200
	s_addc_u32 s43, s11, 0
	global_load_dwordx4 v[164:167], v203, s[42:43]
	s_waitcnt vmcnt(16)
	v_pk_fma_f32 v[20:21], v[156:157], v[20:21], v[168:169]
	v_pk_fma_f32 v[22:23], v[158:159], v[22:23], v[170:171]
	s_add_u32 s98, s10, 0x90200
	s_addc_u32 s99, s11, 0
	global_store_dwordx4 v203, v[20:23], s[98:99] nt
	s_add_u32 s42, s10, 0xb0200
	s_addc_u32 s43, s11, 0
	global_load_dwordx4 v[168:171], v203, s[42:43] offset:16
	s_waitcnt vmcnt(16)
	v_pk_fma_f32 v[16:17], v[152:153], v[16:17], v[172:173]
	v_pk_fma_f32 v[18:19], v[154:155], v[18:19], v[174:175]
	s_add_u32 s98, s10, 0x90200
	s_addc_u32 s99, s11, 0
	global_store_dwordx4 v203, v[16:19], s[98:99] offset:16 nt
	s_waitcnt vmcnt(15)
	v_pk_fma_f32 v[44:45], v[148:149], v[44:45], v[176:177]
	v_pk_fma_f32 v[46:47], v[150:151], v[46:47], v[178:179]
	s_add_u32 s42, s10, 0xa0000
	s_addc_u32 s43, s11, 0
	global_store_dwordx4 v203, v[44:47], s[42:43] nt
	s_waitcnt vmcnt(14)
	v_pk_fma_f32 v[40:41], v[144:145], v[40:41], v[180:181]
	v_pk_fma_f32 v[42:43], v[146:147], v[42:43], v[182:183]
	s_add_u32 s98, s10, 0xa0000
	s_addc_u32 s99, s11, 0
	global_store_dwordx4 v203, v[40:43], s[98:99] offset:16 nt
	s_waitcnt vmcnt(13)
	v_pk_fma_f32 v[12:13], v[156:157], v[12:13], v[206:207]
	v_pk_fma_f32 v[14:15], v[158:159], v[14:15], v[208:209]
	s_add_u32 s42, s10, 0xa0200
	s_addc_u32 s43, s11, 0
	global_store_dwordx4 v203, v[12:15], s[42:43] nt
	s_waitcnt vmcnt(12)
	v_pk_fma_f32 v[8:9], v[152:153], v[8:9], v[210:211]
	v_pk_fma_f32 v[10:11], v[154:155], v[10:11], v[212:213]
	s_add_u32 s98, s10, 0xa0200
	s_addc_u32 s99, s11, 0
	global_store_dwordx4 v203, v[8:11], s[98:99] offset:16 nt
	s_waitcnt vmcnt(11)
	v_pk_fma_f32 v[36:37], v[148:149], v[36:37], v[236:237]
	v_pk_fma_f32 v[38:39], v[150:151], v[38:39], v[238:239]
	s_add_u32 s42, s10, 0xb0000
	s_addc_u32 s43, s11, 0
	global_store_dwordx4 v203, v[36:39], s[42:43] nt
	s_waitcnt vmcnt(10)
	v_pk_fma_f32 v[32:33], v[144:145], v[32:33], v[160:161]
	v_pk_fma_f32 v[34:35], v[146:147], v[34:35], v[162:163]
	s_add_u32 s98, s10, 0xb0000
	s_addc_u32 s99, s11, 0
	global_store_dwordx4 v203, v[32:35], s[98:99] offset:16 nt
	s_waitcnt vmcnt(9)
	v_pk_fma_f32 v[4:5], v[156:157], v[4:5], v[164:165]
	v_pk_fma_f32 v[6:7], v[158:159], v[6:7], v[166:167]
	s_add_u32 s42, s10, 0xb0200
	s_addc_u32 s43, s11, 0
	global_store_dwordx4 v203, v[4:7], s[42:43] nt
	s_waitcnt vmcnt(8)
	v_pk_fma_f32 v[0:1], v[152:153], v[0:1], v[168:169]
	v_pk_fma_f32 v[2:3], v[154:155], v[2:3], v[170:171]
	s_add_u32 s98, s10, 0xb0200
	s_addc_u32 s99, s11, 0
	global_store_dwordx4 v203, v[0:3], s[98:99] offset:16 nt

.Lfq_LBB0_1428:
	v_ashrrev_i32_e32 v203, 31, v202
	v_lshlrev_b64 v[206:207], 10, v[202:203]
	s_and_b64 vcc, exec, s[80:81]
	s_cbranch_vccnz .Lfq_LBB0_1430
	v_lshl_add_u64 v[172:173], v[206:207], 1, s[18:19]
	v_mul_f32_e32 v174, v140, v160
	v_mul_f32_e32 v175, v141, v161
	v_cvt_pk_bf16_f32 v168, v174, v175
	v_mul_f32_e32 v178, v142, v162
	v_mul_f32_e32 v179, v143, v163
	v_cvt_pk_bf16_f32 v169, v178, v179
	v_lshl_add_u64 v[172:173], v[200:201], 1, v[172:173]
	v_mul_f32_e32 v180, v136, v164
	v_mul_f32_e32 v181, v137, v165
	v_cvt_pk_bf16_f32 v170, v180, v181
	v_mul_f32_e32 v182, v138, v166
	v_mul_f32_e32 v183, v139, v167
	v_cvt_pk_bf16_f32 v171, v182, v183
	global_store_dwordx4 v[172:173], v[168:171], off nt
	s_nop 1
	v_mov_b32_e32 v168, v185
	v_mov_b32_e32 v169, v185
	v_cvt_pk_fp8_f32 v168, v174, v175
	v_cvt_pk_fp8_f32 v169, v180, v181
	v_lshl_add_u64 v[170:171], s[70:71], 0, v[206:207]
	v_lshl_add_u64 v[170:171], v[170:171], 0, v[200:201]
	v_cvt_pk_fp8_f32 v168, v178, v179 op_sel:[0,0,1]
	v_cvt_pk_fp8_f32 v169, v182, v183 op_sel:[0,0,1]
	global_store_dwordx2 v[170:171], v[168:169], off nt

.Lfq_LBB0_1435:
	s_and_b64 vcc, exec, s[80:81]
	s_cbranch_vccnz .Lfq_LBB0_1437
	v_lshl_add_u64 v[180:181], v[206:207], 1, s[18:19]
	v_mul_f32_e32 v182, v132, v172
	v_mul_f32_e32 v183, v133, v173
	v_cvt_pk_bf16_f32 v176, v182, v183
	v_mul_f32_e32 v203, v134, v174
	v_mul_f32_e32 v205, v135, v175
	v_cvt_pk_bf16_f32 v177, v203, v205
	v_lshl_add_u64 v[180:181], v[200:201], 1, v[180:181]
	v_mul_f32_e32 v208, v128, v168
	v_mul_f32_e32 v209, v129, v169
	v_cvt_pk_bf16_f32 v178, v208, v209
	v_mul_f32_e32 v210, v130, v170
	v_mul_f32_e32 v211, v131, v171
	v_cvt_pk_bf16_f32 v179, v210, v211
	global_store_dwordx4 v[180:181], v[176:179], off offset:256 nt
	s_nop 1
	v_mov_b32_e32 v176, v185
	v_mov_b32_e32 v177, v185
	v_cvt_pk_fp8_f32 v176, v182, v183
	v_cvt_pk_fp8_f32 v177, v208, v209
	v_lshl_add_u64 v[178:179], s[70:71], 0, v[206:207]
	v_lshl_add_u64 v[178:179], v[178:179], 0, v[200:201]
	v_cvt_pk_fp8_f32 v176, v203, v205 op_sel:[0,0,1]
	v_cvt_pk_fp8_f32 v177, v210, v211 op_sel:[0,0,1]
	global_store_dwordx2 v[178:179], v[176:177], off offset:128 nt

.Lfq_LBB0_1561:
	v_ashrrev_i32_e32 v177, 31, v176
	v_lshlrev_b64 v[180:181], 10, v[176:177]
	v_mov_b64_e32 v[150:151], v[38:39]
	v_mov_b64_e32 v[148:149], v[36:37]
	v_mov_b64_e32 v[146:147], v[34:35]
	v_mov_b64_e32 v[144:145], v[32:33]
	s_and_b64 vcc, exec, s[80:81]
	s_cbranch_vccnz .Lfq_LBB0_1563
	v_mul_f32_e32 v160, v140, v148
	v_mul_f32_e32 v161, v141, v149
	v_mul_f32_e32 v164, v136, v144
	v_mul_f32_e32 v165, v137, v145
	v_mov_b32_e32 v136, v185
	v_mov_b32_e32 v137, v185
	v_cvt_pk_fp8_f32 v136, v160, v161
	v_cvt_pk_fp8_f32 v137, v164, v165
	v_mul_f32_e32 v162, v142, v150
	v_mul_f32_e32 v163, v143, v151
	v_mul_f32_e32 v166, v138, v146
	v_mul_f32_e32 v167, v139, v147
	v_lshl_add_u64 v[138:139], v[180:181], 1, s[18:19]
	v_cvt_pk_fp8_f32 v136, v162, v163 op_sel:[0,0,1]
	v_cvt_pk_fp8_f32 v137, v166, v167 op_sel:[0,0,1]
	v_lshl_add_u64 v[138:139], v[200:201], 1, v[138:139]
	v_cvt_pk_bf16_f32 v140, v160, v161
	v_cvt_pk_bf16_f32 v141, v162, v163
	v_cvt_pk_bf16_f32 v142, v164, v165
	v_cvt_pk_bf16_f32 v143, v166, v167
	global_store_dwordx4 v[138:139], v[140:143], off nt
	v_lshl_add_u64 v[138:139], s[70:71], 0, v[180:181]
	v_lshl_add_u64 v[138:139], v[138:139], 0, v[200:201]
	global_store_dwordx2 v[138:139], v[136:137], off nt

.Lfq_LBB0_1568:
	s_and_b64 vcc, exec, s[80:81]
	s_cbranch_vccnz .Lfq_LBB0_1570
	v_mul_f32_e32 v152, v132, v140
	v_mul_f32_e32 v153, v133, v141
	v_mul_f32_e32 v156, v128, v136
	v_mul_f32_e32 v157, v129, v137
	v_mov_b32_e32 v128, v185
	v_mov_b32_e32 v129, v185
	v_cvt_pk_fp8_f32 v128, v152, v153
	v_cvt_pk_fp8_f32 v129, v156, v157
	v_mul_f32_e32 v154, v134, v142
	v_mul_f32_e32 v155, v135, v143
	v_mul_f32_e32 v158, v130, v138
	v_mul_f32_e32 v159, v131, v139
	v_lshl_add_u64 v[130:131], v[180:181], 1, s[18:19]
	v_cvt_pk_fp8_f32 v128, v154, v155 op_sel:[0,0,1]
	v_cvt_pk_fp8_f32 v129, v158, v159 op_sel:[0,0,1]
	v_lshl_add_u64 v[130:131], v[200:201], 1, v[130:131]
	v_cvt_pk_bf16_f32 v132, v152, v153
	v_cvt_pk_bf16_f32 v133, v154, v155
	v_cvt_pk_bf16_f32 v134, v156, v157
	v_cvt_pk_bf16_f32 v135, v158, v159
	global_store_dwordx4 v[130:131], v[132:135], off offset:256 nt
	v_lshl_add_u64 v[130:131], s[70:71], 0, v[180:181]
	v_lshl_add_u64 v[130:131], v[130:131], 0, v[200:201]
	global_store_dwordx2 v[130:131], v[128:129], off offset:128 nt

.Lfs_LBB0_1420:
	s_lshl_b32 s31, s31, 8
	v_add_u32_e32 v202, s31, v224
	v_mov_b32_e32 v160, s92
	v_mov_b32_e32 v161, s93
	v_cmp_gt_i32_e32 vcc, s33, v202
	s_nop 1
	v_cndmask_b32_e32 v160, v160, v161, vcc
	v_cndmask_b32_e64 v161, 0, 1, s[84:85]
	v_cmp_ne_u32_e64 s[82:83], 1, v161
	v_add_u32_e32 v204, v202, v160
	v_lshlrev_b32_e32 v203, 12, v204
	v_lshl_add_u32 v203, v200, 2, v203
	v_lshlrev_b32_e32 v205, 2, v194
	v_add_u32_e32 v235, 0xffffc000, v204
	v_lshrrev_b32_e32 v235, 3, v235
	v_add_u32_e32 v235, 8, v235
	v_mul_u32_u24_e32 v235, 0xc000, v235
	v_lshl_add_u32 v235, v200, 2, v235
	s_cmp_eq_u32 s30, 1
	s_cbranch_scc1 .Lfs_np1
	s_cmp_eq_u32 s30, 2
	s_cbranch_scc1 .Lfs_np2
	s_add_u32 s42, s62, 0x0
	s_addc_u32 s43, s63, 0
	global_load_dwordx4 v[128:131], v205, s[42:43] sc0 sc1
	s_add_u32 s98, s62, 0x1000
	s_addc_u32 s99, s63, 0
	global_load_dwordx4 v[132:135], v205, s[98:99] sc0 sc1
	s_add_u32 s42, s62, 0x400
	s_addc_u32 s43, s63, 0
	global_load_dwordx4 v[136:139], v205, s[42:43] sc0 sc1
	s_add_u32 s98, s62, 0x1400
	s_addc_u32 s99, s63, 0
	global_load_dwordx4 v[140:143], v205, s[98:99] sc0 sc1
	s_add_u32 s42, s62, 0x800
	s_addc_u32 s43, s63, 0
	global_load_dwordx4 v[144:147], v205, s[42:43] sc0 sc1
	s_add_u32 s98, s62, 0x1800
	s_addc_u32 s99, s63, 0
	global_load_dwordx4 v[148:151], v205, s[98:99] sc0 sc1
	s_add_u32 s42, s62, 0xc00
	s_addc_u32 s43, s63, 0
	global_load_dwordx4 v[152:155], v205, s[42:43] sc0 sc1
	s_add_u32 s98, s62, 0x1c00
	s_addc_u32 s99, s63, 0
	global_load_dwordx4 v[156:159], v205, s[98:99] sc0 sc1
	s_add_u32 s42, s62, 0x2000
	s_addc_u32 s43, s63, 0
	global_load_dwordx4 v[160:163], v205, s[42:43] sc0 sc1
	s_add_u32 s98, s62, 0x3000
	s_addc_u32 s99, s63, 0
	global_load_dwordx4 v[164:167], v205, s[98:99] sc0 sc1
	s_add_u32 s42, s62, 0x2400
	s_addc_u32 s43, s63, 0
	global_load_dwordx4 v[168:171], v205, s[42:43] sc0 sc1
	s_add_u32 s98, s62, 0x3400
	s_addc_u32 s99, s63, 0
	global_load_dwordx4 v[172:175], v205, s[98:99] sc0 sc1
	s_add_u32 s42, s62, 0x2800
	s_addc_u32 s43, s63, 0
	global_load_dwordx4 v[176:179], v205, s[42:43] sc0 sc1
	s_add_u32 s98, s62, 0x3800
	s_addc_u32 s99, s63, 0
	global_load_dwordx4 v[180:183], v205, s[98:99] sc0 sc1
	s_add_u32 s42, s62, 0x2c00
	s_addc_u32 s43, s63, 0
	global_load_dwordx4 v[206:209], v205, s[42:43] sc0 sc1
	s_add_u32 s98, s62, 0x3c00
	s_addc_u32 s99, s63, 0
	global_load_dwordx4 v[210:213], v205, s[98:99] sc0 sc1
	s_add_u32 s42, s62, 0x20000
	s_addc_u32 s43, s63, 0
	global_load_dwordx4 v[236:239], v205, s[42:43] sc0 sc1
	s_waitcnt vmcnt(16)
	v_lshlrev_b32_e32 v240, 16, v128
	v_and_b32_e32 v241, 0xffff0000, v128
	v_pk_add_f32 v[124:125], v[124:125], v[240:241]
	v_lshlrev_b32_e32 v240, 16, v129
	v_and_b32_e32 v241, 0xffff0000, v129
	v_pk_add_f32 v[126:127], v[126:127], v[240:241]
	v_lshlrev_b32_e32 v240, 16, v130
	v_and_b32_e32 v241, 0xffff0000, v130
	v_pk_add_f32 v[120:121], v[120:121], v[240:241]
	v_lshlrev_b32_e32 v240, 16, v131
	v_and_b32_e32 v241, 0xffff0000, v131
	v_pk_add_f32 v[122:123], v[122:123], v[240:241]
	s_add_u32 s98, s62, 0x21000
	s_addc_u32 s99, s63, 0
	global_load_dwordx4 v[128:131], v205, s[98:99] sc0 sc1
	s_waitcnt vmcnt(16)
	v_lshlrev_b32_e32 v240, 16, v132
	v_and_b32_e32 v241, 0xffff0000, v132
	v_pk_add_f32 v[92:93], v[92:93], v[240:241]
	v_lshlrev_b32_e32 v240, 16, v133
	v_and_b32_e32 v241, 0xffff0000, v133
	v_pk_add_f32 v[94:95], v[94:95], v[240:241]
	v_lshlrev_b32_e32 v240, 16, v134
	v_and_b32_e32 v241, 0xffff0000, v134
	v_pk_add_f32 v[88:89], v[88:89], v[240:241]
	v_lshlrev_b32_e32 v240, 16, v135
	v_and_b32_e32 v241, 0xffff0000, v135
	v_pk_add_f32 v[90:91], v[90:91], v[240:241]
	s_add_u32 s42, s62, 0x20400
	s_addc_u32 s43, s63, 0
	global_load_dwordx4 v[132:135], v205, s[42:43] sc0 sc1
	s_waitcnt vmcnt(16)
	v_lshlrev_b32_e32 v240, 16, v136
	v_and_b32_e32 v241, 0xffff0000, v136
	v_pk_add_f32 v[116:117], v[116:117], v[240:241]
	v_lshlrev_b32_e32 v240, 16, v137
	v_and_b32_e32 v241, 0xffff0000, v137
	v_pk_add_f32 v[118:119], v[118:119], v[240:241]
	v_lshlrev_b32_e32 v240, 16, v138
	v_and_b32_e32 v241, 0xffff0000, v138
	v_pk_add_f32 v[112:113], v[112:113], v[240:241]
	v_lshlrev_b32_e32 v240, 16, v139
	v_and_b32_e32 v241, 0xffff0000, v139
	v_pk_add_f32 v[114:115], v[114:115], v[240:241]
	s_add_u32 s98, s62, 0x21400
	s_addc_u32 s99, s63, 0
	global_load_dwordx4 v[136:139], v205, s[98:99] sc0 sc1
	s_waitcnt vmcnt(16)
	v_lshlrev_b32_e32 v240, 16, v140
	v_and_b32_e32 v241, 0xffff0000, v140
	v_pk_add_f32 v[84:85], v[84:85], v[240:241]
	v_lshlrev_b32_e32 v240, 16, v141
	v_and_b32_e32 v241, 0xffff0000, v141
	v_pk_add_f32 v[86:87], v[86:87], v[240:241]
	v_lshlrev_b32_e32 v240, 16, v142
	v_and_b32_e32 v241, 0xffff0000, v142
	v_pk_add_f32 v[80:81], v[80:81], v[240:241]
	v_lshlrev_b32_e32 v240, 16, v143
	v_and_b32_e32 v241, 0xffff0000, v143
	v_pk_add_f32 v[82:83], v[82:83], v[240:241]
	s_add_u32 s42, s62, 0x20800
	s_addc_u32 s43, s63, 0
	global_load_dwordx4 v[140:143], v205, s[42:43] sc0 sc1
	s_waitcnt vmcnt(16)
	v_lshlrev_b32_e32 v240, 16, v144
	v_and_b32_e32 v241, 0xffff0000, v144
	v_pk_add_f32 v[108:109], v[108:109], v[240:241]
	v_lshlrev_b32_e32 v240, 16, v145
	v_and_b32_e32 v241, 0xffff0000, v145
	v_pk_add_f32 v[110:111], v[110:111], v[240:241]
	v_lshlrev_b32_e32 v240, 16, v146
	v_and_b32_e32 v241, 0xffff0000, v146
	v_pk_add_f32 v[104:105], v[104:105], v[240:241]
	v_lshlrev_b32_e32 v240, 16, v147
	v_and_b32_e32 v241, 0xffff0000, v147
	v_pk_add_f32 v[106:107], v[106:107], v[240:241]
	s_add_u32 s98, s62, 0x21800
	s_addc_u32 s99, s63, 0
	global_load_dwordx4 v[144:147], v205, s[98:99] sc0 sc1
	s_waitcnt vmcnt(16)
	v_lshlrev_b32_e32 v240, 16, v148
	v_and_b32_e32 v241, 0xffff0000, v148
	v_pk_add_f32 v[76:77], v[76:77], v[240:241]
	v_lshlrev_b32_e32 v240, 16, v149
	v_and_b32_e32 v241, 0xffff0000, v149
	v_pk_add_f32 v[78:79], v[78:79], v[240:241]
	v_lshlrev_b32_e32 v240, 16, v150
	v_and_b32_e32 v241, 0xffff0000, v150
	v_pk_add_f32 v[72:73], v[72:73], v[240:241]
	v_lshlrev_b32_e32 v240, 16, v151
	v_and_b32_e32 v241, 0xffff0000, v151
	v_pk_add_f32 v[74:75], v[74:75], v[240:241]
	s_add_u32 s42, s62, 0x20c00
	s_addc_u32 s43, s63, 0
	global_load_dwordx4 v[148:151], v205, s[42:43] sc0 sc1
	s_waitcnt vmcnt(16)
	v_lshlrev_b32_e32 v240, 16, v152
	v_and_b32_e32 v241, 0xffff0000, v152
	v_pk_add_f32 v[100:101], v[100:101], v[240:241]
	v_lshlrev_b32_e32 v240, 16, v153
	v_and_b32_e32 v241, 0xffff0000, v153
	v_pk_add_f32 v[102:103], v[102:103], v[240:241]
	v_lshlrev_b32_e32 v240, 16, v154
	v_and_b32_e32 v241, 0xffff0000, v154
	v_pk_add_f32 v[96:97], v[96:97], v[240:241]
	v_lshlrev_b32_e32 v240, 16, v155
	v_and_b32_e32 v241, 0xffff0000, v155
	v_pk_add_f32 v[98:99], v[98:99], v[240:241]
	s_add_u32 s98, s62, 0x21c00
	s_addc_u32 s99, s63, 0
	global_load_dwordx4 v[152:155], v205, s[98:99] sc0 sc1
	s_waitcnt vmcnt(16)
	v_lshlrev_b32_e32 v240, 16, v156
	v_and_b32_e32 v241, 0xffff0000, v156
	v_pk_add_f32 v[68:69], v[68:69], v[240:241]
	v_lshlrev_b32_e32 v240, 16, v157
	v_and_b32_e32 v241, 0xffff0000, v157
	v_pk_add_f32 v[70:71], v[70:71], v[240:241]
	v_lshlrev_b32_e32 v240, 16, v158
	v_and_b32_e32 v241, 0xffff0000, v158
	v_pk_add_f32 v[64:65], v[64:65], v[240:241]
	v_lshlrev_b32_e32 v240, 16, v159
	v_and_b32_e32 v241, 0xffff0000, v159
	v_pk_add_f32 v[66:67], v[66:67], v[240:241]
	s_add_u32 s42, s62, 0x22000
	s_addc_u32 s43, s63, 0
	global_load_dwordx4 v[156:159], v205, s[42:43] sc0 sc1
	s_waitcnt vmcnt(16)
	v_lshlrev_b32_e32 v240, 16, v160
	v_and_b32_e32 v241, 0xffff0000, v160
	v_pk_add_f32 v[60:61], v[60:61], v[240:241]
	v_lshlrev_b32_e32 v240, 16, v161
	v_and_b32_e32 v241, 0xffff0000, v161
	v_pk_add_f32 v[62:63], v[62:63], v[240:241]
	v_lshlrev_b32_e32 v240, 16, v162
	v_and_b32_e32 v241, 0xffff0000, v162
	v_pk_add_f32 v[56:57], v[56:57], v[240:241]
	v_lshlrev_b32_e32 v240, 16, v163
	v_and_b32_e32 v241, 0xffff0000, v163
	v_pk_add_f32 v[58:59], v[58:59], v[240:241]
	s_add_u32 s98, s62, 0x23000
	s_addc_u32 s99, s63, 0
	global_load_dwordx4 v[160:163], v205, s[98:99] sc0 sc1
	s_waitcnt vmcnt(16)
	v_lshlrev_b32_e32 v240, 16, v164
	v_and_b32_e32 v241, 0xffff0000, v164
	v_pk_add_f32 v[28:29], v[28:29], v[240:241]
	v_lshlrev_b32_e32 v240, 16, v165
	v_and_b32_e32 v241, 0xffff0000, v165
	v_pk_add_f32 v[30:31], v[30:31], v[240:241]
	v_lshlrev_b32_e32 v240, 16, v166
	v_and_b32_e32 v241, 0xffff0000, v166
	v_pk_add_f32 v[24:25], v[24:25], v[240:241]
	v_lshlrev_b32_e32 v240, 16, v167
	v_and_b32_e32 v241, 0xffff0000, v167
	v_pk_add_f32 v[26:27], v[26:27], v[240:241]
	s_add_u32 s42, s62, 0x22400
	s_addc_u32 s43, s63, 0
	global_load_dwordx4 v[164:167], v205, s[42:43] sc0 sc1
	s_waitcnt vmcnt(16)
	v_lshlrev_b32_e32 v240, 16, v168
	v_and_b32_e32 v241, 0xffff0000, v168
	v_pk_add_f32 v[52:53], v[52:53], v[240:241]
	v_lshlrev_b32_e32 v240, 16, v169
	v_and_b32_e32 v241, 0xffff0000, v169
	v_pk_add_f32 v[54:55], v[54:55], v[240:241]
	v_lshlrev_b32_e32 v240, 16, v170
	v_and_b32_e32 v241, 0xffff0000, v170
	v_pk_add_f32 v[48:49], v[48:49], v[240:241]
	v_lshlrev_b32_e32 v240, 16, v171
	v_and_b32_e32 v241, 0xffff0000, v171
	v_pk_add_f32 v[50:51], v[50:51], v[240:241]
	s_add_u32 s98, s62, 0x23400
	s_addc_u32 s99, s63, 0
	global_load_dwordx4 v[168:171], v205, s[98:99] sc0 sc1
	s_waitcnt vmcnt(16)
	v_lshlrev_b32_e32 v240, 16, v172
	v_and_b32_e32 v241, 0xffff0000, v172
	v_pk_add_f32 v[20:21], v[20:21], v[240:241]
	v_lshlrev_b32_e32 v240, 16, v173
	v_and_b32_e32 v241, 0xffff0000, v173
	v_pk_add_f32 v[22:23], v[22:23], v[240:241]
	v_lshlrev_b32_e32 v240, 16, v174
	v_and_b32_e32 v241, 0xffff0000, v174
	v_pk_add_f32 v[16:17], v[16:17], v[240:241]
	v_lshlrev_b32_e32 v240, 16, v175
	v_and_b32_e32 v241, 0xffff0000, v175
	v_pk_add_f32 v[18:19], v[18:19], v[240:241]
	s_add_u32 s42, s62, 0x22800
	s_addc_u32 s43, s63, 0
	global_load_dwordx4 v[172:175], v205, s[42:43] sc0 sc1
	s_waitcnt vmcnt(16)
	v_lshlrev_b32_e32 v240, 16, v176
	v_and_b32_e32 v241, 0xffff0000, v176
	v_pk_add_f32 v[44:45], v[44:45], v[240:241]
	v_lshlrev_b32_e32 v240, 16, v177
	v_and_b32_e32 v241, 0xffff0000, v177
	v_pk_add_f32 v[46:47], v[46:47], v[240:241]
	v_lshlrev_b32_e32 v240, 16, v178
	v_and_b32_e32 v241, 0xffff0000, v178
	v_pk_add_f32 v[40:41], v[40:41], v[240:241]
	v_lshlrev_b32_e32 v240, 16, v179
	v_and_b32_e32 v241, 0xffff0000, v179
	v_pk_add_f32 v[42:43], v[42:43], v[240:241]
	s_add_u32 s98, s62, 0x23800
	s_addc_u32 s99, s63, 0
	global_load_dwordx4 v[176:179], v205, s[98:99] sc0 sc1
	s_waitcnt vmcnt(16)
	v_lshlrev_b32_e32 v240, 16, v180
	v_and_b32_e32 v241, 0xffff0000, v180
	v_pk_add_f32 v[12:13], v[12:13], v[240:241]
	v_lshlrev_b32_e32 v240, 16, v181
	v_and_b32_e32 v241, 0xffff0000, v181
	v_pk_add_f32 v[14:15], v[14:15], v[240:241]
	v_lshlrev_b32_e32 v240, 16, v182
	v_and_b32_e32 v241, 0xffff0000, v182
	v_pk_add_f32 v[8:9], v[8:9], v[240:241]
	v_lshlrev_b32_e32 v240, 16, v183
	v_and_b32_e32 v241, 0xffff0000, v183
	v_pk_add_f32 v[10:11], v[10:11], v[240:241]
	s_add_u32 s42, s62, 0x22c00
	s_addc_u32 s43, s63, 0
	global_load_dwordx4 v[180:183], v205, s[42:43] sc0 sc1
	s_waitcnt vmcnt(16)
	v_lshlrev_b32_e32 v240, 16, v206
	v_and_b32_e32 v241, 0xffff0000, v206
	v_pk_add_f32 v[36:37], v[36:37], v[240:241]
	v_lshlrev_b32_e32 v240, 16, v207
	v_and_b32_e32 v241, 0xffff0000, v207
	v_pk_add_f32 v[38:39], v[38:39], v[240:241]
	v_lshlrev_b32_e32 v240, 16, v208
	v_and_b32_e32 v241, 0xffff0000, v208
	v_pk_add_f32 v[32:33], v[32:33], v[240:241]
	v_lshlrev_b32_e32 v240, 16, v209
	v_and_b32_e32 v241, 0xffff0000, v209
	v_pk_add_f32 v[34:35], v[34:35], v[240:241]
	s_add_u32 s98, s62, 0x23c00
	s_addc_u32 s99, s63, 0
	global_load_dwordx4 v[206:209], v205, s[98:99] sc0 sc1
	s_waitcnt vmcnt(16)
	v_lshlrev_b32_e32 v240, 16, v210
	v_and_b32_e32 v241, 0xffff0000, v210
	v_pk_add_f32 v[4:5], v[4:5], v[240:241]
	v_lshlrev_b32_e32 v240, 16, v211
	v_and_b32_e32 v241, 0xffff0000, v211
	v_pk_add_f32 v[6:7], v[6:7], v[240:241]
	v_lshlrev_b32_e32 v240, 16, v212
	v_and_b32_e32 v241, 0xffff0000, v212
	v_pk_add_f32 v[0:1], v[0:1], v[240:241]
	v_lshlrev_b32_e32 v240, 16, v213
	v_and_b32_e32 v241, 0xffff0000, v213
	v_pk_add_f32 v[2:3], v[2:3], v[240:241]
	s_add_u32 s42, s62, 0x40000
	s_addc_u32 s43, s63, 0
	global_load_dwordx4 v[210:213], v205, s[42:43] sc0 sc1
	s_waitcnt vmcnt(16)
	v_lshlrev_b32_e32 v240, 16, v236
	v_and_b32_e32 v241, 0xffff0000, v236
	v_pk_add_f32 v[124:125], v[124:125], v[240:241]
	v_lshlrev_b32_e32 v240, 16, v237
	v_and_b32_e32 v241, 0xffff0000, v237
	v_pk_add_f32 v[126:127], v[126:127], v[240:241]
	v_lshlrev_b32_e32 v240, 16, v238
	v_and_b32_e32 v241, 0xffff0000, v238
	v_pk_add_f32 v[120:121], v[120:121], v[240:241]
	v_lshlrev_b32_e32 v240, 16, v239
	v_and_b32_e32 v241, 0xffff0000, v239
	v_pk_add_f32 v[122:123], v[122:123], v[240:241]
	s_add_u32 s98, s62, 0x41000
	s_addc_u32 s99, s63, 0
	global_load_dwordx4 v[236:239], v205, s[98:99] sc0 sc1
	s_waitcnt vmcnt(16)
	v_lshlrev_b32_e32 v240, 16, v128
	v_and_b32_e32 v241, 0xffff0000, v128
	v_pk_add_f32 v[92:93], v[92:93], v[240:241]
	v_lshlrev_b32_e32 v240, 16, v129
	v_and_b32_e32 v241, 0xffff0000, v129
	v_pk_add_f32 v[94:95], v[94:95], v[240:241]
	v_lshlrev_b32_e32 v240, 16, v130
	v_and_b32_e32 v241, 0xffff0000, v130
	v_pk_add_f32 v[88:89], v[88:89], v[240:241]
	v_lshlrev_b32_e32 v240, 16, v131
	v_and_b32_e32 v241, 0xffff0000, v131
	v_pk_add_f32 v[90:91], v[90:91], v[240:241]
	s_add_u32 s42, s62, 0x40400
	s_addc_u32 s43, s63, 0
	global_load_dwordx4 v[128:131], v205, s[42:43] sc0 sc1
	s_waitcnt vmcnt(16)
	v_lshlrev_b32_e32 v240, 16, v132
	v_and_b32_e32 v241, 0xffff0000, v132
	v_pk_add_f32 v[116:117], v[116:117], v[240:241]
	v_lshlrev_b32_e32 v240, 16, v133
	v_and_b32_e32 v241, 0xffff0000, v133
	v_pk_add_f32 v[118:119], v[118:119], v[240:241]
	v_lshlrev_b32_e32 v240, 16, v134
	v_and_b32_e32 v241, 0xffff0000, v134
	v_pk_add_f32 v[112:113], v[112:113], v[240:241]
	v_lshlrev_b32_e32 v240, 16, v135
	v_and_b32_e32 v241, 0xffff0000, v135
	v_pk_add_f32 v[114:115], v[114:115], v[240:241]
	s_add_u32 s98, s62, 0x41400
	s_addc_u32 s99, s63, 0
	global_load_dwordx4 v[132:135], v205, s[98:99] sc0 sc1
	s_waitcnt vmcnt(16)
	v_lshlrev_b32_e32 v240, 16, v136
	v_and_b32_e32 v241, 0xffff0000, v136
	v_pk_add_f32 v[84:85], v[84:85], v[240:241]
	v_lshlrev_b32_e32 v240, 16, v137
	v_and_b32_e32 v241, 0xffff0000, v137
	v_pk_add_f32 v[86:87], v[86:87], v[240:241]
	v_lshlrev_b32_e32 v240, 16, v138
	v_and_b32_e32 v241, 0xffff0000, v138
	v_pk_add_f32 v[80:81], v[80:81], v[240:241]
	v_lshlrev_b32_e32 v240, 16, v139
	v_and_b32_e32 v241, 0xffff0000, v139
	v_pk_add_f32 v[82:83], v[82:83], v[240:241]
	s_add_u32 s42, s62, 0x40800
	s_addc_u32 s43, s63, 0
	global_load_dwordx4 v[136:139], v205, s[42:43] sc0 sc1
	s_waitcnt vmcnt(16)
	v_lshlrev_b32_e32 v240, 16, v140
	v_and_b32_e32 v241, 0xffff0000, v140
	v_pk_add_f32 v[108:109], v[108:109], v[240:241]
	v_lshlrev_b32_e32 v240, 16, v141
	v_and_b32_e32 v241, 0xffff0000, v141
	v_pk_add_f32 v[110:111], v[110:111], v[240:241]
	v_lshlrev_b32_e32 v240, 16, v142
	v_and_b32_e32 v241, 0xffff0000, v142
	v_pk_add_f32 v[104:105], v[104:105], v[240:241]
	v_lshlrev_b32_e32 v240, 16, v143
	v_and_b32_e32 v241, 0xffff0000, v143
	v_pk_add_f32 v[106:107], v[106:107], v[240:241]
	s_add_u32 s98, s62, 0x41800
	s_addc_u32 s99, s63, 0
	global_load_dwordx4 v[140:143], v205, s[98:99] sc0 sc1
	s_waitcnt vmcnt(16)
	v_lshlrev_b32_e32 v240, 16, v144
	v_and_b32_e32 v241, 0xffff0000, v144
	v_pk_add_f32 v[76:77], v[76:77], v[240:241]
	v_lshlrev_b32_e32 v240, 16, v145
	v_and_b32_e32 v241, 0xffff0000, v145
	v_pk_add_f32 v[78:79], v[78:79], v[240:241]
	v_lshlrev_b32_e32 v240, 16, v146
	v_and_b32_e32 v241, 0xffff0000, v146
	v_pk_add_f32 v[72:73], v[72:73], v[240:241]
	v_lshlrev_b32_e32 v240, 16, v147
	v_and_b32_e32 v241, 0xffff0000, v147
	v_pk_add_f32 v[74:75], v[74:75], v[240:241]
	s_add_u32 s42, s62, 0x40c00
	s_addc_u32 s43, s63, 0
	global_load_dwordx4 v[144:147], v205, s[42:43] sc0 sc1
	s_waitcnt vmcnt(16)
	v_lshlrev_b32_e32 v240, 16, v148
	v_and_b32_e32 v241, 0xffff0000, v148
	v_pk_add_f32 v[100:101], v[100:101], v[240:241]
	v_lshlrev_b32_e32 v240, 16, v149
	v_and_b32_e32 v241, 0xffff0000, v149
	v_pk_add_f32 v[102:103], v[102:103], v[240:241]
	v_lshlrev_b32_e32 v240, 16, v150
	v_and_b32_e32 v241, 0xffff0000, v150
	v_pk_add_f32 v[96:97], v[96:97], v[240:241]
	v_lshlrev_b32_e32 v240, 16, v151
	v_and_b32_e32 v241, 0xffff0000, v151
	v_pk_add_f32 v[98:99], v[98:99], v[240:241]
	s_add_u32 s98, s62, 0x41c00
	s_addc_u32 s99, s63, 0
	global_load_dwordx4 v[148:151], v205, s[98:99] sc0 sc1
	s_waitcnt vmcnt(16)
	v_lshlrev_b32_e32 v240, 16, v152
	v_and_b32_e32 v241, 0xffff0000, v152
	v_pk_add_f32 v[68:69], v[68:69], v[240:241]
	v_lshlrev_b32_e32 v240, 16, v153
	v_and_b32_e32 v241, 0xffff0000, v153
	v_pk_add_f32 v[70:71], v[70:71], v[240:241]
	v_lshlrev_b32_e32 v240, 16, v154
	v_and_b32_e32 v241, 0xffff0000, v154
	v_pk_add_f32 v[64:65], v[64:65], v[240:241]
	v_lshlrev_b32_e32 v240, 16, v155
	v_and_b32_e32 v241, 0xffff0000, v155
	v_pk_add_f32 v[66:67], v[66:67], v[240:241]
	s_add_u32 s42, s62, 0x42000
	s_addc_u32 s43, s63, 0
	global_load_dwordx4 v[152:155], v205, s[42:43] sc0 sc1
	s_waitcnt vmcnt(16)
	v_lshlrev_b32_e32 v240, 16, v156
	v_and_b32_e32 v241, 0xffff0000, v156
	v_pk_add_f32 v[60:61], v[60:61], v[240:241]
	v_lshlrev_b32_e32 v240, 16, v157
	v_and_b32_e32 v241, 0xffff0000, v157
	v_pk_add_f32 v[62:63], v[62:63], v[240:241]
	v_lshlrev_b32_e32 v240, 16, v158
	v_and_b32_e32 v241, 0xffff0000, v158
	v_pk_add_f32 v[56:57], v[56:57], v[240:241]
	v_lshlrev_b32_e32 v240, 16, v159
	v_and_b32_e32 v241, 0xffff0000, v159
	v_pk_add_f32 v[58:59], v[58:59], v[240:241]
	s_add_u32 s98, s62, 0x43000
	s_addc_u32 s99, s63, 0
	global_load_dwordx4 v[156:159], v205, s[98:99] sc0 sc1
	s_waitcnt vmcnt(16)
	v_lshlrev_b32_e32 v240, 16, v160
	v_and_b32_e32 v241, 0xffff0000, v160
	v_pk_add_f32 v[28:29], v[28:29], v[240:241]
	v_lshlrev_b32_e32 v240, 16, v161
	v_and_b32_e32 v241, 0xffff0000, v161
	v_pk_add_f32 v[30:31], v[30:31], v[240:241]
	v_lshlrev_b32_e32 v240, 16, v162
	v_and_b32_e32 v241, 0xffff0000, v162
	v_pk_add_f32 v[24:25], v[24:25], v[240:241]
	v_lshlrev_b32_e32 v240, 16, v163
	v_and_b32_e32 v241, 0xffff0000, v163
	v_pk_add_f32 v[26:27], v[26:27], v[240:241]
	s_add_u32 s42, s62, 0x42400
	s_addc_u32 s43, s63, 0
	global_load_dwordx4 v[160:163], v205, s[42:43] sc0 sc1
	s_waitcnt vmcnt(16)
	v_lshlrev_b32_e32 v240, 16, v164
	v_and_b32_e32 v241, 0xffff0000, v164
	v_pk_add_f32 v[52:53], v[52:53], v[240:241]
	v_lshlrev_b32_e32 v240, 16, v165
	v_and_b32_e32 v241, 0xffff0000, v165
	v_pk_add_f32 v[54:55], v[54:55], v[240:241]
	v_lshlrev_b32_e32 v240, 16, v166
	v_and_b32_e32 v241, 0xffff0000, v166
	v_pk_add_f32 v[48:49], v[48:49], v[240:241]
	v_lshlrev_b32_e32 v240, 16, v167
	v_and_b32_e32 v241, 0xffff0000, v167
	v_pk_add_f32 v[50:51], v[50:51], v[240:241]
	s_add_u32 s98, s62, 0x43400
	s_addc_u32 s99, s63, 0
	global_load_dwordx4 v[164:167], v205, s[98:99] sc0 sc1
	s_waitcnt vmcnt(16)
	v_lshlrev_b32_e32 v240, 16, v168
	v_and_b32_e32 v241, 0xffff0000, v168
	v_pk_add_f32 v[20:21], v[20:21], v[240:241]
	v_lshlrev_b32_e32 v240, 16, v169
	v_and_b32_e32 v241, 0xffff0000, v169
	v_pk_add_f32 v[22:23], v[22:23], v[240:241]
	v_lshlrev_b32_e32 v240, 16, v170
	v_and_b32_e32 v241, 0xffff0000, v170
	v_pk_add_f32 v[16:17], v[16:17], v[240:241]
	v_lshlrev_b32_e32 v240, 16, v171
	v_and_b32_e32 v241, 0xffff0000, v171
	v_pk_add_f32 v[18:19], v[18:19], v[240:241]
	s_add_u32 s42, s62, 0x42800
	s_addc_u32 s43, s63, 0
	global_load_dwordx4 v[168:171], v205, s[42:43] sc0 sc1
	s_waitcnt vmcnt(16)
	v_lshlrev_b32_e32 v240, 16, v172
	v_and_b32_e32 v241, 0xffff0000, v172
	v_pk_add_f32 v[44:45], v[44:45], v[240:241]
	v_lshlrev_b32_e32 v240, 16, v173
	v_and_b32_e32 v241, 0xffff0000, v173
	v_pk_add_f32 v[46:47], v[46:47], v[240:241]
	v_lshlrev_b32_e32 v240, 16, v174
	v_and_b32_e32 v241, 0xffff0000, v174
	v_pk_add_f32 v[40:41], v[40:41], v[240:241]
	v_lshlrev_b32_e32 v240, 16, v175
	v_and_b32_e32 v241, 0xffff0000, v175
	v_pk_add_f32 v[42:43], v[42:43], v[240:241]
	s_add_u32 s98, s62, 0x43800
	s_addc_u32 s99, s63, 0
	global_load_dwordx4 v[172:175], v205, s[98:99] sc0 sc1
	s_waitcnt vmcnt(16)
	v_lshlrev_b32_e32 v240, 16, v176
	v_and_b32_e32 v241, 0xffff0000, v176
	v_pk_add_f32 v[12:13], v[12:13], v[240:241]
	v_lshlrev_b32_e32 v240, 16, v177
	v_and_b32_e32 v241, 0xffff0000, v177
	v_pk_add_f32 v[14:15], v[14:15], v[240:241]
	v_lshlrev_b32_e32 v240, 16, v178
	v_and_b32_e32 v241, 0xffff0000, v178
	v_pk_add_f32 v[8:9], v[8:9], v[240:241]
	v_lshlrev_b32_e32 v240, 16, v179
	v_and_b32_e32 v241, 0xffff0000, v179
	v_pk_add_f32 v[10:11], v[10:11], v[240:241]
	s_add_u32 s42, s62, 0x42c00
	s_addc_u32 s43, s63, 0
	global_load_dwordx4 v[176:179], v205, s[42:43] sc0 sc1
	s_waitcnt vmcnt(16)
	v_lshlrev_b32_e32 v240, 16, v180
	v_and_b32_e32 v241, 0xffff0000, v180
	v_pk_add_f32 v[36:37], v[36:37], v[240:241]
	v_lshlrev_b32_e32 v240, 16, v181
	v_and_b32_e32 v241, 0xffff0000, v181
	v_pk_add_f32 v[38:39], v[38:39], v[240:241]
	v_lshlrev_b32_e32 v240, 16, v182
	v_and_b32_e32 v241, 0xffff0000, v182
	v_pk_add_f32 v[32:33], v[32:33], v[240:241]
	v_lshlrev_b32_e32 v240, 16, v183
	v_and_b32_e32 v241, 0xffff0000, v183
	v_pk_add_f32 v[34:35], v[34:35], v[240:241]
	s_add_u32 s98, s62, 0x43c00
	s_addc_u32 s99, s63, 0
	global_load_dwordx4 v[180:183], v205, s[98:99] sc0 sc1
	s_waitcnt vmcnt(16)
	v_lshlrev_b32_e32 v240, 16, v206
	v_and_b32_e32 v241, 0xffff0000, v206
	v_pk_add_f32 v[4:5], v[4:5], v[240:241]
	v_lshlrev_b32_e32 v240, 16, v207
	v_and_b32_e32 v241, 0xffff0000, v207
	v_pk_add_f32 v[6:7], v[6:7], v[240:241]
	v_lshlrev_b32_e32 v240, 16, v208
	v_and_b32_e32 v241, 0xffff0000, v208
	v_pk_add_f32 v[0:1], v[0:1], v[240:241]
	v_lshlrev_b32_e32 v240, 16, v209
	v_and_b32_e32 v241, 0xffff0000, v209
	v_pk_add_f32 v[2:3], v[2:3], v[240:241]
	s_add_u32 s42, s14, 0x0
	s_addc_u32 s43, s15, 0
	global_load_dwordx4 v[206:209], v235, s[42:43]
	s_waitcnt vmcnt(16)
	v_lshlrev_b32_e32 v240, 16, v210
	v_and_b32_e32 v241, 0xffff0000, v210
	v_pk_add_f32 v[124:125], v[124:125], v[240:241]
	v_lshlrev_b32_e32 v240, 16, v211
	v_and_b32_e32 v241, 0xffff0000, v211
	v_pk_add_f32 v[126:127], v[126:127], v[240:241]
	v_lshlrev_b32_e32 v240, 16, v212
	v_and_b32_e32 v241, 0xffff0000, v212
	v_pk_add_f32 v[120:121], v[120:121], v[240:241]
	v_lshlrev_b32_e32 v240, 16, v213
	v_and_b32_e32 v241, 0xffff0000, v213
	v_pk_add_f32 v[122:123], v[122:123], v[240:241]
	s_add_u32 s98, s10, 0x0
	s_addc_u32 s99, s11, 0
	global_load_dwordx4 v[210:213], v203, s[98:99]
	s_waitcnt vmcnt(16)
	v_lshlrev_b32_e32 v240, 16, v236
	v_and_b32_e32 v241, 0xffff0000, v236
	v_pk_add_f32 v[92:93], v[92:93], v[240:241]
	v_lshlrev_b32_e32 v240, 16, v237
	v_and_b32_e32 v241, 0xffff0000, v237
	v_pk_add_f32 v[94:95], v[94:95], v[240:241]
	v_lshlrev_b32_e32 v240, 16, v238
	v_and_b32_e32 v241, 0xffff0000, v238
	v_pk_add_f32 v[88:89], v[88:89], v[240:241]
	v_lshlrev_b32_e32 v240, 16, v239
	v_and_b32_e32 v241, 0xffff0000, v239
	v_pk_add_f32 v[90:91], v[90:91], v[240:241]
	s_add_u32 s42, s14, 0x0
	s_addc_u32 s43, s15, 0
	global_load_dwordx4 v[236:239], v235, s[42:43] offset:16
	s_waitcnt vmcnt(16)
	v_lshlrev_b32_e32 v240, 16, v128
	v_and_b32_e32 v241, 0xffff0000, v128
	v_pk_add_f32 v[116:117], v[116:117], v[240:241]
	v_lshlrev_b32_e32 v240, 16, v129
	v_and_b32_e32 v241, 0xffff0000, v129
	v_pk_add_f32 v[118:119], v[118:119], v[240:241]
	v_lshlrev_b32_e32 v240, 16, v130
	v_and_b32_e32 v241, 0xffff0000, v130
	v_pk_add_f32 v[112:113], v[112:113], v[240:241]
	v_lshlrev_b32_e32 v240, 16, v131
	v_and_b32_e32 v241, 0xffff0000, v131
	v_pk_add_f32 v[114:115], v[114:115], v[240:241]
	s_add_u32 s98, s10, 0x0
	s_addc_u32 s99, s11, 0
	global_load_dwordx4 v[128:131], v203, s[98:99] offset:16
	s_waitcnt vmcnt(16)
	v_lshlrev_b32_e32 v240, 16, v132
	v_and_b32_e32 v241, 0xffff0000, v132
	v_pk_add_f32 v[84:85], v[84:85], v[240:241]
	v_lshlrev_b32_e32 v240, 16, v133
	v_and_b32_e32 v241, 0xffff0000, v133
	v_pk_add_f32 v[86:87], v[86:87], v[240:241]
	v_lshlrev_b32_e32 v240, 16, v134
	v_and_b32_e32 v241, 0xffff0000, v134
	v_pk_add_f32 v[80:81], v[80:81], v[240:241]
	v_lshlrev_b32_e32 v240, 16, v135
	v_and_b32_e32 v241, 0xffff0000, v135
	v_pk_add_f32 v[82:83], v[82:83], v[240:241]
	s_add_u32 s42, s14, 0x200
	s_addc_u32 s43, s15, 0
	global_load_dwordx4 v[132:135], v235, s[42:43]
	s_waitcnt vmcnt(16)
	v_lshlrev_b32_e32 v240, 16, v136
	v_and_b32_e32 v241, 0xffff0000, v136
	v_pk_add_f32 v[108:109], v[108:109], v[240:241]
	v_lshlrev_b32_e32 v240, 16, v137
	v_and_b32_e32 v241, 0xffff0000, v137
	v_pk_add_f32 v[110:111], v[110:111], v[240:241]
	v_lshlrev_b32_e32 v240, 16, v138
	v_and_b32_e32 v241, 0xffff0000, v138
	v_pk_add_f32 v[104:105], v[104:105], v[240:241]
	v_lshlrev_b32_e32 v240, 16, v139
	v_and_b32_e32 v241, 0xffff0000, v139
	v_pk_add_f32 v[106:107], v[106:107], v[240:241]
	s_add_u32 s98, s10, 0x200
	s_addc_u32 s99, s11, 0
	global_load_dwordx4 v[136:139], v203, s[98:99]
	s_waitcnt vmcnt(16)
	v_lshlrev_b32_e32 v240, 16, v140
	v_and_b32_e32 v241, 0xffff0000, v140
	v_pk_add_f32 v[76:77], v[76:77], v[240:241]
	v_lshlrev_b32_e32 v240, 16, v141
	v_and_b32_e32 v241, 0xffff0000, v141
	v_pk_add_f32 v[78:79], v[78:79], v[240:241]
	v_lshlrev_b32_e32 v240, 16, v142
	v_and_b32_e32 v241, 0xffff0000, v142
	v_pk_add_f32 v[72:73], v[72:73], v[240:241]
	v_lshlrev_b32_e32 v240, 16, v143
	v_and_b32_e32 v241, 0xffff0000, v143
	v_pk_add_f32 v[74:75], v[74:75], v[240:241]
	s_add_u32 s42, s14, 0x200
	s_addc_u32 s43, s15, 0
	global_load_dwordx4 v[140:143], v235, s[42:43] offset:16
	s_waitcnt vmcnt(16)
	v_lshlrev_b32_e32 v240, 16, v144
	v_and_b32_e32 v241, 0xffff0000, v144
	v_pk_add_f32 v[100:101], v[100:101], v[240:241]
	v_lshlrev_b32_e32 v240, 16, v145
	v_and_b32_e32 v241, 0xffff0000, v145
	v_pk_add_f32 v[102:103], v[102:103], v[240:241]
	v_lshlrev_b32_e32 v240, 16, v146
	v_and_b32_e32 v241, 0xffff0000, v146
	v_pk_add_f32 v[96:97], v[96:97], v[240:241]
	v_lshlrev_b32_e32 v240, 16, v147
	v_and_b32_e32 v241, 0xffff0000, v147
	v_pk_add_f32 v[98:99], v[98:99], v[240:241]
	s_add_u32 s98, s10, 0x200
	s_addc_u32 s99, s11, 0
	global_load_dwordx4 v[144:147], v203, s[98:99] offset:16
	s_waitcnt vmcnt(16)
	v_lshlrev_b32_e32 v240, 16, v148
	v_and_b32_e32 v241, 0xffff0000, v148
	v_pk_add_f32 v[68:69], v[68:69], v[240:241]
	v_lshlrev_b32_e32 v240, 16, v149
	v_and_b32_e32 v241, 0xffff0000, v149
	v_pk_add_f32 v[70:71], v[70:71], v[240:241]
	v_lshlrev_b32_e32 v240, 16, v150
	v_and_b32_e32 v241, 0xffff0000, v150
	v_pk_add_f32 v[64:65], v[64:65], v[240:241]
	v_lshlrev_b32_e32 v240, 16, v151
	v_and_b32_e32 v241, 0xffff0000, v151
	v_pk_add_f32 v[66:67], v[66:67], v[240:241]
	s_add_u32 s42, s14, 0x18000
	s_addc_u32 s43, s15, 0
	global_load_dwordx4 v[148:151], v235, s[42:43]
	s_waitcnt vmcnt(16)
	v_lshlrev_b32_e32 v240, 16, v152
	v_and_b32_e32 v241, 0xffff0000, v152
	v_pk_add_f32 v[60:61], v[60:61], v[240:241]
	v_lshlrev_b32_e32 v240, 16, v153
	v_and_b32_e32 v241, 0xffff0000, v153
	v_pk_add_f32 v[62:63], v[62:63], v[240:241]
	v_lshlrev_b32_e32 v240, 16, v154
	v_and_b32_e32 v241, 0xffff0000, v154
	v_pk_add_f32 v[56:57], v[56:57], v[240:241]
	v_lshlrev_b32_e32 v240, 16, v155
	v_and_b32_e32 v241, 0xffff0000, v155
	v_pk_add_f32 v[58:59], v[58:59], v[240:241]
	s_add_u32 s98, s10, 0x10000
	s_addc_u32 s99, s11, 0
	global_load_dwordx4 v[152:155], v203, s[98:99]
	s_waitcnt vmcnt(16)
	v_lshlrev_b32_e32 v240, 16, v156
	v_and_b32_e32 v241, 0xffff0000, v156
	v_pk_add_f32 v[28:29], v[28:29], v[240:241]
	v_lshlrev_b32_e32 v240, 16, v157
	v_and_b32_e32 v241, 0xffff0000, v157
	v_pk_add_f32 v[30:31], v[30:31], v[240:241]
	v_lshlrev_b32_e32 v240, 16, v158
	v_and_b32_e32 v241, 0xffff0000, v158
	v_pk_add_f32 v[24:25], v[24:25], v[240:241]
	v_lshlrev_b32_e32 v240, 16, v159
	v_and_b32_e32 v241, 0xffff0000, v159
	v_pk_add_f32 v[26:27], v[26:27], v[240:241]
	s_add_u32 s42, s14, 0x18000
	s_addc_u32 s43, s15, 0
	global_load_dwordx4 v[156:159], v235, s[42:43] offset:16
	s_waitcnt vmcnt(16)
	v_lshlrev_b32_e32 v240, 16, v160
	v_and_b32_e32 v241, 0xffff0000, v160
	v_pk_add_f32 v[52:53], v[52:53], v[240:241]
	v_lshlrev_b32_e32 v240, 16, v161
	v_and_b32_e32 v241, 0xffff0000, v161
	v_pk_add_f32 v[54:55], v[54:55], v[240:241]
	v_lshlrev_b32_e32 v240, 16, v162
	v_and_b32_e32 v241, 0xffff0000, v162
	v_pk_add_f32 v[48:49], v[48:49], v[240:241]
	v_lshlrev_b32_e32 v240, 16, v163
	v_and_b32_e32 v241, 0xffff0000, v163
	v_pk_add_f32 v[50:51], v[50:51], v[240:241]
	s_add_u32 s98, s10, 0x10000
	s_addc_u32 s99, s11, 0
	global_load_dwordx4 v[160:163], v203, s[98:99] offset:16
	s_waitcnt vmcnt(16)
	v_lshlrev_b32_e32 v240, 16, v164
	v_and_b32_e32 v241, 0xffff0000, v164
	v_pk_add_f32 v[20:21], v[20:21], v[240:241]
	v_lshlrev_b32_e32 v240, 16, v165
	v_and_b32_e32 v241, 0xffff0000, v165
	v_pk_add_f32 v[22:23], v[22:23], v[240:241]
	v_lshlrev_b32_e32 v240, 16, v166
	v_and_b32_e32 v241, 0xffff0000, v166
	v_pk_add_f32 v[16:17], v[16:17], v[240:241]
	v_lshlrev_b32_e32 v240, 16, v167
	v_and_b32_e32 v241, 0xffff0000, v167
	v_pk_add_f32 v[18:19], v[18:19], v[240:241]
	s_add_u32 s42, s14, 0x18200
	s_addc_u32 s43, s15, 0
	global_load_dwordx4 v[164:167], v235, s[42:43]
	s_waitcnt vmcnt(16)
	v_lshlrev_b32_e32 v240, 16, v168
	v_and_b32_e32 v241, 0xffff0000, v168
	v_pk_add_f32 v[44:45], v[44:45], v[240:241]
	v_lshlrev_b32_e32 v240, 16, v169
	v_and_b32_e32 v241, 0xffff0000, v169
	v_pk_add_f32 v[46:47], v[46:47], v[240:241]
	v_lshlrev_b32_e32 v240, 16, v170
	v_and_b32_e32 v241, 0xffff0000, v170
	v_pk_add_f32 v[40:41], v[40:41], v[240:241]
	v_lshlrev_b32_e32 v240, 16, v171
	v_and_b32_e32 v241, 0xffff0000, v171
	v_pk_add_f32 v[42:43], v[42:43], v[240:241]
	s_add_u32 s98, s10, 0x10200
	s_addc_u32 s99, s11, 0
	global_load_dwordx4 v[168:171], v203, s[98:99]
	s_waitcnt vmcnt(16)
	v_lshlrev_b32_e32 v240, 16, v172
	v_and_b32_e32 v241, 0xffff0000, v172
	v_pk_add_f32 v[12:13], v[12:13], v[240:241]
	v_lshlrev_b32_e32 v240, 16, v173
	v_and_b32_e32 v241, 0xffff0000, v173
	v_pk_add_f32 v[14:15], v[14:15], v[240:241]
	v_lshlrev_b32_e32 v240, 16, v174
	v_and_b32_e32 v241, 0xffff0000, v174
	v_pk_add_f32 v[8:9], v[8:9], v[240:241]
	v_lshlrev_b32_e32 v240, 16, v175
	v_and_b32_e32 v241, 0xffff0000, v175
	v_pk_add_f32 v[10:11], v[10:11], v[240:241]
	s_add_u32 s42, s14, 0x18200
	s_addc_u32 s43, s15, 0
	global_load_dwordx4 v[172:175], v235, s[42:43] offset:16
	s_waitcnt vmcnt(16)
	v_lshlrev_b32_e32 v240, 16, v176
	v_and_b32_e32 v241, 0xffff0000, v176
	v_pk_add_f32 v[36:37], v[36:37], v[240:241]
	v_lshlrev_b32_e32 v240, 16, v177
	v_and_b32_e32 v241, 0xffff0000, v177
	v_pk_add_f32 v[38:39], v[38:39], v[240:241]
	v_lshlrev_b32_e32 v240, 16, v178
	v_and_b32_e32 v241, 0xffff0000, v178
	v_pk_add_f32 v[32:33], v[32:33], v[240:241]
	v_lshlrev_b32_e32 v240, 16, v179
	v_and_b32_e32 v241, 0xffff0000, v179
	v_pk_add_f32 v[34:35], v[34:35], v[240:241]
	s_add_u32 s98, s10, 0x10200
	s_addc_u32 s99, s11, 0
	global_load_dwordx4 v[176:179], v203, s[98:99] offset:16
	s_waitcnt vmcnt(16)
	v_lshlrev_b32_e32 v240, 16, v180
	v_and_b32_e32 v241, 0xffff0000, v180
	v_pk_add_f32 v[4:5], v[4:5], v[240:241]
	v_lshlrev_b32_e32 v240, 16, v181
	v_and_b32_e32 v241, 0xffff0000, v181
	v_pk_add_f32 v[6:7], v[6:7], v[240:241]
	v_lshlrev_b32_e32 v240, 16, v182
	v_and_b32_e32 v241, 0xffff0000, v182
	v_pk_add_f32 v[0:1], v[0:1], v[240:241]
	v_lshlrev_b32_e32 v240, 16, v183
	v_and_b32_e32 v241, 0xffff0000, v183
	v_pk_add_f32 v[2:3], v[2:3], v[240:241]
	s_add_u32 s42, s14, 0x30000
	s_addc_u32 s43, s15, 0
	global_load_dwordx4 v[180:183], v235, s[42:43]
	s_waitcnt vmcnt(15)
	v_pk_fma_f32 v[124:125], v[206:207], v[124:125], v[210:211]
	v_pk_fma_f32 v[126:127], v[208:209], v[126:127], v[212:213]
	s_add_u32 s98, s10, 0x0
	s_addc_u32 s99, s11, 0
	global_store_dwordx4 v203, v[124:127], s[98:99] nt
	s_add_u32 s42, s10, 0x20000
	s_addc_u32 s43, s11, 0
	global_load_dwordx4 v[206:209], v203, s[42:43]
	s_add_u32 s98, s14, 0x30000
	s_addc_u32 s99, s15, 0
	global_load_dwordx4 v[210:213], v235, s[98:99] offset:16
	s_waitcnt vmcnt(16)
	v_pk_fma_f32 v[120:121], v[236:237], v[120:121], v[128:129]
	v_pk_fma_f32 v[122:123], v[238:239], v[122:123], v[130:131]
	s_add_u32 s42, s10, 0x0
	s_addc_u32 s43, s11, 0
	global_store_dwordx4 v203, v[120:123], s[42:43] offset:16 nt
	s_add_u32 s98, s10, 0x20000
	s_addc_u32 s99, s11, 0
	global_load_dwordx4 v[236:239], v203, s[98:99] offset:16
	s_add_u32 s42, s14, 0x30200
	s_addc_u32 s43, s15, 0
	global_load_dwordx4 v[128:131], v235, s[42:43]
	s_waitcnt vmcnt(17)
	v_pk_fma_f32 v[92:93], v[132:133], v[92:93], v[136:137]
	v_pk_fma_f32 v[94:95], v[134:135], v[94:95], v[138:139]
	s_add_u32 s98, s10, 0x200
	s_addc_u32 s99, s11, 0
	global_store_dwordx4 v203, v[92:95], s[98:99] nt
	s_add_u32 s42, s10, 0x20200
	s_addc_u32 s43, s11, 0
	global_load_dwordx4 v[132:135], v203, s[42:43]
	s_add_u32 s98, s14, 0x30200
	s_addc_u32 s99, s15, 0
	global_load_dwordx4 v[136:139], v235, s[98:99] offset:16
	s_waitcnt vmcnt(18)
	v_pk_fma_f32 v[88:89], v[140:141], v[88:89], v[144:145]
	v_pk_fma_f32 v[90:91], v[142:143], v[90:91], v[146:147]
	s_add_u32 s42, s10, 0x200
	s_addc_u32 s43, s11, 0
	global_store_dwordx4 v203, v[88:91], s[42:43] offset:16 nt
	s_add_u32 s98, s10, 0x20200
	s_addc_u32 s99, s11, 0
	global_load_dwordx4 v[140:143], v203, s[98:99] offset:16
	s_add_u32 s42, s14, 0x48000
	s_addc_u32 s43, s15, 0
	global_load_dwordx4 v[144:147], v235, s[42:43]
	s_waitcnt vmcnt(19)
	v_pk_fma_f32 v[116:117], v[148:149], v[116:117], v[152:153]
	v_pk_fma_f32 v[118:119], v[150:151], v[118:119], v[154:155]
	s_add_u32 s98, s10, 0x10000
	s_addc_u32 s99, s11, 0
	global_store_dwordx4 v203, v[116:119], s[98:99] nt
	s_add_u32 s42, s10, 0x30000
	s_addc_u32 s43, s11, 0
	global_load_dwordx4 v[148:151], v203, s[42:43]
	s_add_u32 s98, s14, 0x48000
	s_addc_u32 s99, s15, 0
	global_load_dwordx4 v[152:155], v235, s[98:99] offset:16
	s_waitcnt vmcnt(20)
	v_pk_fma_f32 v[112:113], v[156:157], v[112:113], v[160:161]
	v_pk_fma_f32 v[114:115], v[158:159], v[114:115], v[162:163]
	s_add_u32 s42, s10, 0x10000
	s_addc_u32 s43, s11, 0
	global_store_dwordx4 v203, v[112:115], s[42:43] offset:16 nt
	s_add_u32 s98, s10, 0x30000
	s_addc_u32 s99, s11, 0
	global_load_dwordx4 v[156:159], v203, s[98:99] offset:16
	s_add_u32 s42, s14, 0x48200
	s_addc_u32 s43, s15, 0
	global_load_dwordx4 v[160:163], v235, s[42:43]
	s_waitcnt vmcnt(21)
	v_pk_fma_f32 v[84:85], v[164:165], v[84:85], v[168:169]
	v_pk_fma_f32 v[86:87], v[166:167], v[86:87], v[170:171]
	s_add_u32 s98, s10, 0x10200
	s_addc_u32 s99, s11, 0
	global_store_dwordx4 v203, v[84:87], s[98:99] nt
	s_add_u32 s42, s10, 0x30200
	s_addc_u32 s43, s11, 0
	global_load_dwordx4 v[164:167], v203, s[42:43]
	s_add_u32 s98, s14, 0x48200
	s_addc_u32 s99, s15, 0
	global_load_dwordx4 v[168:171], v235, s[98:99] offset:16
	s_waitcnt vmcnt(22)
	v_pk_fma_f32 v[80:81], v[172:173], v[80:81], v[176:177]
	v_pk_fma_f32 v[82:83], v[174:175], v[82:83], v[178:179]
	s_add_u32 s42, s10, 0x10200
	s_addc_u32 s43, s11, 0
	global_store_dwordx4 v203, v[80:83], s[42:43] offset:16 nt
	s_add_u32 s98, s10, 0x30200
	s_addc_u32 s99, s11, 0
	global_load_dwordx4 v[172:175], v203, s[98:99] offset:16
	s_add_u32 s42, s14, 0xc0000
	s_addc_u32 s43, s15, 0
	global_load_dwordx4 v[176:179], v235, s[42:43]
	s_waitcnt vmcnt(22)
	v_pk_fma_f32 v[108:109], v[180:181], v[108:109], v[206:207]
	v_pk_fma_f32 v[110:111], v[182:183], v[110:111], v[208:209]
	s_add_u32 s98, s10, 0x20000
	s_addc_u32 s99, s11, 0
	global_store_dwordx4 v203, v[108:111], s[98:99] nt
	s_add_u32 s42, s10, 0x80000
	s_addc_u32 s43, s11, 0
	global_load_dwordx4 v[180:183], v203, s[42:43]
	s_add_u32 s98, s14, 0xc0000
	s_addc_u32 s99, s15, 0
	global_load_dwordx4 v[206:209], v235, s[98:99] offset:16
	s_waitcnt vmcnt(22)
	v_pk_fma_f32 v[104:105], v[210:211], v[104:105], v[236:237]
	v_pk_fma_f32 v[106:107], v[212:213], v[106:107], v[238:239]
	s_add_u32 s42, s10, 0x20000
	s_addc_u32 s43, s11, 0
	global_store_dwordx4 v203, v[104:107], s[42:43] offset:16 nt
	s_add_u32 s98, s10, 0x80000
	s_addc_u32 s99, s11, 0
	global_load_dwordx4 v[210:213], v203, s[98:99] offset:16
	s_add_u32 s42, s14, 0xc0200
	s_addc_u32 s43, s15, 0
	global_load_dwordx4 v[236:239], v235, s[42:43]
	s_waitcnt vmcnt(22)
	v_pk_fma_f32 v[76:77], v[128:129], v[76:77], v[132:133]
	v_pk_fma_f32 v[78:79], v[130:131], v[78:79], v[134:135]
	s_add_u32 s98, s10, 0x20200
	s_addc_u32 s99, s11, 0
	global_store_dwordx4 v203, v[76:79], s[98:99] nt
	s_add_u32 s42, s10, 0x80200
	s_addc_u32 s43, s11, 0
	global_load_dwordx4 v[128:131], v203, s[42:43]
	s_add_u32 s98, s14, 0xc0200
	s_addc_u32 s99, s15, 0
	global_load_dwordx4 v[132:135], v235, s[98:99] offset:16
	s_waitcnt vmcnt(22)
	v_pk_fma_f32 v[72:73], v[136:137], v[72:73], v[140:141]
	v_pk_fma_f32 v[74:75], v[138:139], v[74:75], v[142:143]
	s_add_u32 s42, s10, 0x20200
	s_addc_u32 s43, s11, 0
	global_store_dwordx4 v203, v[72:75], s[42:43] offset:16 nt
	s_add_u32 s98, s10, 0x80200
	s_addc_u32 s99, s11, 0
	global_load_dwordx4 v[136:139], v203, s[98:99] offset:16
	s_add_u32 s42, s14, 0xd8000
	s_addc_u32 s43, s15, 0
	global_load_dwordx4 v[140:143], v235, s[42:43]
	s_waitcnt vmcnt(22)
	v_pk_fma_f32 v[100:101], v[144:145], v[100:101], v[148:149]
	v_pk_fma_f32 v[102:103], v[146:147], v[102:103], v[150:151]
	s_add_u32 s98, s10, 0x30000
	s_addc_u32 s99, s11, 0
	global_store_dwordx4 v203, v[100:103], s[98:99] nt
	s_add_u32 s42, s10, 0x90000
	s_addc_u32 s43, s11, 0
	global_load_dwordx4 v[144:147], v203, s[42:43]
	s_add_u32 s98, s14, 0xd8000
	s_addc_u32 s99, s15, 0
	global_load_dwordx4 v[148:151], v235, s[98:99] offset:16
	s_waitcnt vmcnt(22)
	v_pk_fma_f32 v[96:97], v[152:153], v[96:97], v[156:157]
	v_pk_fma_f32 v[98:99], v[154:155], v[98:99], v[158:159]
	s_add_u32 s42, s10, 0x30000
	s_addc_u32 s43, s11, 0
	global_store_dwordx4 v203, v[96:99], s[42:43] offset:16 nt
	s_add_u32 s98, s10, 0x90000
	s_addc_u32 s99, s11, 0
	global_load_dwordx4 v[152:155], v203, s[98:99] offset:16
	s_add_u32 s42, s14, 0xd8200
	s_addc_u32 s43, s15, 0
	global_load_dwordx4 v[156:159], v235, s[42:43]
	s_waitcnt vmcnt(22)
	v_pk_fma_f32 v[68:69], v[160:161], v[68:69], v[164:165]
	v_pk_fma_f32 v[70:71], v[162:163], v[70:71], v[166:167]
	s_add_u32 s98, s10, 0x30200
	s_addc_u32 s99, s11, 0
	global_store_dwordx4 v203, v[68:71], s[98:99] nt
	s_add_u32 s42, s10, 0x90200
	s_addc_u32 s43, s11, 0
	global_load_dwordx4 v[160:163], v203, s[42:43]
	s_add_u32 s98, s14, 0xd8200
	s_addc_u32 s99, s15, 0
	global_load_dwordx4 v[164:167], v235, s[98:99] offset:16
	s_waitcnt vmcnt(22)
	v_pk_fma_f32 v[64:65], v[168:169], v[64:65], v[172:173]
	v_pk_fma_f32 v[66:67], v[170:171], v[66:67], v[174:175]
	s_add_u32 s42, s10, 0x30200
	s_addc_u32 s43, s11, 0
	global_store_dwordx4 v203, v[64:67], s[42:43] offset:16 nt
	s_add_u32 s98, s10, 0x90200
	s_addc_u32 s99, s11, 0
	global_load_dwordx4 v[168:171], v203, s[98:99] offset:16
	s_add_u32 s42, s14, 0xf0000
	s_addc_u32 s43, s15, 0
	global_load_dwordx4 v[172:175], v235, s[42:43]
	s_waitcnt vmcnt(22)
	v_pk_fma_f32 v[60:61], v[176:177], v[60:61], v[180:181]
	v_pk_fma_f32 v[62:63], v[178:179], v[62:63], v[182:183]
	s_add_u32 s98, s10, 0x80000
	s_addc_u32 s99, s11, 0
	global_store_dwordx4 v203, v[60:63], s[98:99] nt
	s_add_u32 s42, s10, 0xa0000
	s_addc_u32 s43, s11, 0
	global_load_dwordx4 v[176:179], v203, s[42:43]
	s_add_u32 s98, s14, 0xf0000
	s_addc_u32 s99, s15, 0
	global_load_dwordx4 v[180:183], v235, s[98:99] offset:16
	s_waitcnt vmcnt(22)
	v_pk_fma_f32 v[56:57], v[206:207], v[56:57], v[210:211]
	v_pk_fma_f32 v[58:59], v[208:209], v[58:59], v[212:213]
	s_add_u32 s42, s10, 0x80000
	s_addc_u32 s43, s11, 0
	global_store_dwordx4 v203, v[56:59], s[42:43] offset:16 nt
	s_add_u32 s98, s10, 0xa0000
	s_addc_u32 s99, s11, 0
	global_load_dwordx4 v[206:209], v203, s[98:99] offset:16
	s_add_u32 s42, s14, 0xf0200
	s_addc_u32 s43, s15, 0
	global_load_dwordx4 v[210:213], v235, s[42:43]
	s_waitcnt vmcnt(22)
	v_pk_fma_f32 v[28:29], v[236:237], v[28:29], v[128:129]
	v_pk_fma_f32 v[30:31], v[238:239], v[30:31], v[130:131]
	s_add_u32 s98, s10, 0x80200
	s_addc_u32 s99, s11, 0
	global_store_dwordx4 v203, v[28:31], s[98:99] nt
	s_add_u32 s42, s10, 0xa0200
	s_addc_u32 s43, s11, 0
	global_load_dwordx4 v[236:239], v203, s[42:43]
	s_add_u32 s98, s14, 0xf0200
	s_addc_u32 s99, s15, 0
	global_load_dwordx4 v[128:131], v235, s[98:99] offset:16
	s_waitcnt vmcnt(22)
	v_pk_fma_f32 v[24:25], v[132:133], v[24:25], v[136:137]
	v_pk_fma_f32 v[26:27], v[134:135], v[26:27], v[138:139]
	s_add_u32 s42, s10, 0x80200
	s_addc_u32 s43, s11, 0
	global_store_dwordx4 v203, v[24:27], s[42:43] offset:16 nt
	s_add_u32 s98, s10, 0xa0200
	s_addc_u32 s99, s11, 0
	global_load_dwordx4 v[132:135], v203, s[98:99] offset:16
	s_add_u32 s42, s14, 0x108000
	s_addc_u32 s43, s15, 0
	global_load_dwordx4 v[136:139], v235, s[42:43]
	s_waitcnt vmcnt(22)
	v_pk_fma_f32 v[52:53], v[140:141], v[52:53], v[144:145]
	v_pk_fma_f32 v[54:55], v[142:143], v[54:55], v[146:147]
	s_add_u32 s98, s10, 0x90000
	s_addc_u32 s99, s11, 0
	global_store_dwordx4 v203, v[52:55], s[98:99] nt
	s_add_u32 s42, s10, 0xb0000
	s_addc_u32 s43, s11, 0
	global_load_dwordx4 v[140:143], v203, s[42:43]
	s_add_u32 s98, s14, 0x108000
	s_addc_u32 s99, s15, 0
	global_load_dwordx4 v[144:147], v235, s[98:99] offset:16
	s_waitcnt vmcnt(22)
	v_pk_fma_f32 v[48:49], v[148:149], v[48:49], v[152:153]
	v_pk_fma_f32 v[50:51], v[150:151], v[50:51], v[154:155]
	s_add_u32 s42, s10, 0x90000
	s_addc_u32 s43, s11, 0
	global_store_dwordx4 v203, v[48:51], s[42:43] offset:16 nt
	s_add_u32 s98, s10, 0xb0000
	s_addc_u32 s99, s11, 0
	global_load_dwordx4 v[148:151], v203, s[98:99] offset:16
	s_add_u32 s42, s14, 0x108200
	s_addc_u32 s43, s15, 0
	global_load_dwordx4 v[152:155], v235, s[42:43]
	s_waitcnt vmcnt(22)
	v_pk_fma_f32 v[20:21], v[156:157], v[20:21], v[160:161]
	v_pk_fma_f32 v[22:23], v[158:159], v[22:23], v[162:163]
	s_add_u32 s98, s10, 0x90200
	s_addc_u32 s99, s11, 0
	global_store_dwordx4 v203, v[20:23], s[98:99] nt
	s_add_u32 s42, s10, 0xb0200
	s_addc_u32 s43, s11, 0
	global_load_dwordx4 v[156:159], v203, s[42:43]
	s_add_u32 s98, s14, 0x108200
	s_addc_u32 s99, s15, 0
	global_load_dwordx4 v[160:163], v235, s[98:99] offset:16
	s_waitcnt vmcnt(22)
	v_pk_fma_f32 v[16:17], v[164:165], v[16:17], v[168:169]
	v_pk_fma_f32 v[18:19], v[166:167], v[18:19], v[170:171]
	s_add_u32 s42, s10, 0x90200
	s_addc_u32 s43, s11, 0
	global_store_dwordx4 v203, v[16:19], s[42:43] offset:16 nt
	s_add_u32 s98, s10, 0xb0200
	s_addc_u32 s99, s11, 0
	global_load_dwordx4 v[164:167], v203, s[98:99] offset:16
	s_waitcnt vmcnt(21)
	v_pk_fma_f32 v[44:45], v[172:173], v[44:45], v[176:177]
	v_pk_fma_f32 v[46:47], v[174:175], v[46:47], v[178:179]
	s_add_u32 s42, s10, 0xa0000
	s_addc_u32 s43, s11, 0
	global_store_dwordx4 v203, v[44:47], s[42:43] nt
	s_waitcnt vmcnt(19)
	v_pk_fma_f32 v[40:41], v[180:181], v[40:41], v[206:207]
	v_pk_fma_f32 v[42:43], v[182:183], v[42:43], v[208:209]
	s_add_u32 s98, s10, 0xa0000
	s_addc_u32 s99, s11, 0
	global_store_dwordx4 v203, v[40:43], s[98:99] offset:16 nt
	s_waitcnt vmcnt(17)
	v_pk_fma_f32 v[12:13], v[210:211], v[12:13], v[236:237]
	v_pk_fma_f32 v[14:15], v[212:213], v[14:15], v[238:239]
	s_add_u32 s42, s10, 0xa0200
	s_addc_u32 s43, s11, 0
	global_store_dwordx4 v203, v[12:15], s[42:43] nt
	s_waitcnt vmcnt(15)
	v_pk_fma_f32 v[8:9], v[128:129], v[8:9], v[132:133]
	v_pk_fma_f32 v[10:11], v[130:131], v[10:11], v[134:135]
	s_add_u32 s98, s10, 0xa0200
	s_addc_u32 s99, s11, 0
	global_store_dwordx4 v203, v[8:11], s[98:99] offset:16 nt
	s_waitcnt vmcnt(13)
	v_pk_fma_f32 v[36:37], v[136:137], v[36:37], v[140:141]
	v_pk_fma_f32 v[38:39], v[138:139], v[38:39], v[142:143]
	s_add_u32 s42, s10, 0xb0000
	s_addc_u32 s43, s11, 0
	global_store_dwordx4 v203, v[36:39], s[42:43] nt
	s_waitcnt vmcnt(11)
	v_pk_fma_f32 v[32:33], v[144:145], v[32:33], v[148:149]
	v_pk_fma_f32 v[34:35], v[146:147], v[34:35], v[150:151]
	s_add_u32 s98, s10, 0xb0000
	s_addc_u32 s99, s11, 0
	global_store_dwordx4 v203, v[32:35], s[98:99] offset:16 nt
	s_waitcnt vmcnt(9)
	v_pk_fma_f32 v[4:5], v[152:153], v[4:5], v[156:157]
	v_pk_fma_f32 v[6:7], v[154:155], v[6:7], v[158:159]
	s_add_u32 s42, s10, 0xb0200
	s_addc_u32 s43, s11, 0
	global_store_dwordx4 v203, v[4:7], s[42:43] nt
	s_waitcnt vmcnt(7)
	v_pk_fma_f32 v[0:1], v[160:161], v[0:1], v[164:165]
	v_pk_fma_f32 v[2:3], v[162:163], v[2:3], v[166:167]
	s_add_u32 s98, s10, 0xb0200
	s_addc_u32 s99, s11, 0
	global_store_dwordx4 v203, v[0:3], s[98:99] offset:16 nt
	s_branch .Lfs_predone
.Lfs_np2:
	s_add_u32 s42, s62, 0x0
	s_addc_u32 s43, s63, 0
	global_load_dwordx4 v[128:131], v205, s[42:43] sc0 sc1
	s_add_u32 s98, s62, 0x1000
	s_addc_u32 s99, s63, 0
	global_load_dwordx4 v[132:135], v205, s[98:99] sc0 sc1
	s_add_u32 s42, s62, 0x400
	s_addc_u32 s43, s63, 0
	global_load_dwordx4 v[136:139], v205, s[42:43] sc0 sc1
	s_add_u32 s98, s62, 0x1400
	s_addc_u32 s99, s63, 0
	global_load_dwordx4 v[140:143], v205, s[98:99] sc0 sc1
	s_add_u32 s42, s62, 0x800
	s_addc_u32 s43, s63, 0
	global_load_dwordx4 v[144:147], v205, s[42:43] sc0 sc1
	s_add_u32 s98, s62, 0x1800
	s_addc_u32 s99, s63, 0
	global_load_dwordx4 v[148:151], v205, s[98:99] sc0 sc1
	s_add_u32 s42, s62, 0xc00
	s_addc_u32 s43, s63, 0
	global_load_dwordx4 v[152:155], v205, s[42:43] sc0 sc1
	s_add_u32 s98, s62, 0x1c00
	s_addc_u32 s99, s63, 0
	global_load_dwordx4 v[156:159], v205, s[98:99] sc0 sc1
	s_add_u32 s42, s62, 0x2000
	s_addc_u32 s43, s63, 0
	global_load_dwordx4 v[160:163], v205, s[42:43] sc0 sc1
	s_add_u32 s98, s62, 0x3000
	s_addc_u32 s99, s63, 0
	global_load_dwordx4 v[164:167], v205, s[98:99] sc0 sc1
	s_add_u32 s42, s62, 0x2400
	s_addc_u32 s43, s63, 0
	global_load_dwordx4 v[168:171], v205, s[42:43] sc0 sc1
	s_add_u32 s98, s62, 0x3400
	s_addc_u32 s99, s63, 0
	global_load_dwordx4 v[172:175], v205, s[98:99] sc0 sc1
	s_add_u32 s42, s62, 0x2800
	s_addc_u32 s43, s63, 0
	global_load_dwordx4 v[176:179], v205, s[42:43] sc0 sc1
	s_add_u32 s98, s62, 0x3800
	s_addc_u32 s99, s63, 0
	global_load_dwordx4 v[180:183], v205, s[98:99] sc0 sc1
	s_add_u32 s42, s62, 0x2c00
	s_addc_u32 s43, s63, 0
	global_load_dwordx4 v[206:209], v205, s[42:43] sc0 sc1
	s_add_u32 s98, s62, 0x3c00
	s_addc_u32 s99, s63, 0
	global_load_dwordx4 v[210:213], v205, s[98:99] sc0 sc1
	s_add_u32 s42, s62, 0x20000
	s_addc_u32 s43, s63, 0
	global_load_dwordx4 v[236:239], v205, s[42:43] sc0 sc1
	s_waitcnt vmcnt(16)
	v_lshlrev_b32_e32 v240, 16, v128
	v_and_b32_e32 v241, 0xffff0000, v128
	v_pk_add_f32 v[124:125], v[124:125], v[240:241]
	v_lshlrev_b32_e32 v240, 16, v129
	v_and_b32_e32 v241, 0xffff0000, v129
	v_pk_add_f32 v[126:127], v[126:127], v[240:241]
	v_lshlrev_b32_e32 v240, 16, v130
	v_and_b32_e32 v241, 0xffff0000, v130
	v_pk_add_f32 v[120:121], v[120:121], v[240:241]
	v_lshlrev_b32_e32 v240, 16, v131
	v_and_b32_e32 v241, 0xffff0000, v131
	v_pk_add_f32 v[122:123], v[122:123], v[240:241]
	s_add_u32 s98, s62, 0x21000
	s_addc_u32 s99, s63, 0
	global_load_dwordx4 v[128:131], v205, s[98:99] sc0 sc1
	s_waitcnt vmcnt(16)
	v_lshlrev_b32_e32 v240, 16, v132
	v_and_b32_e32 v241, 0xffff0000, v132
	v_pk_add_f32 v[92:93], v[92:93], v[240:241]
	v_lshlrev_b32_e32 v240, 16, v133
	v_and_b32_e32 v241, 0xffff0000, v133
	v_pk_add_f32 v[94:95], v[94:95], v[240:241]
	v_lshlrev_b32_e32 v240, 16, v134
	v_and_b32_e32 v241, 0xffff0000, v134
	v_pk_add_f32 v[88:89], v[88:89], v[240:241]
	v_lshlrev_b32_e32 v240, 16, v135
	v_and_b32_e32 v241, 0xffff0000, v135
	v_pk_add_f32 v[90:91], v[90:91], v[240:241]
	s_add_u32 s42, s62, 0x20400
	s_addc_u32 s43, s63, 0
	global_load_dwordx4 v[132:135], v205, s[42:43] sc0 sc1
	s_waitcnt vmcnt(16)
	v_lshlrev_b32_e32 v240, 16, v136
	v_and_b32_e32 v241, 0xffff0000, v136
	v_pk_add_f32 v[116:117], v[116:117], v[240:241]
	v_lshlrev_b32_e32 v240, 16, v137
	v_and_b32_e32 v241, 0xffff0000, v137
	v_pk_add_f32 v[118:119], v[118:119], v[240:241]
	v_lshlrev_b32_e32 v240, 16, v138
	v_and_b32_e32 v241, 0xffff0000, v138
	v_pk_add_f32 v[112:113], v[112:113], v[240:241]
	v_lshlrev_b32_e32 v240, 16, v139
	v_and_b32_e32 v241, 0xffff0000, v139
	v_pk_add_f32 v[114:115], v[114:115], v[240:241]
	s_add_u32 s98, s62, 0x21400
	s_addc_u32 s99, s63, 0
	global_load_dwordx4 v[136:139], v205, s[98:99] sc0 sc1
	s_waitcnt vmcnt(16)
	v_lshlrev_b32_e32 v240, 16, v140
	v_and_b32_e32 v241, 0xffff0000, v140
	v_pk_add_f32 v[84:85], v[84:85], v[240:241]
	v_lshlrev_b32_e32 v240, 16, v141
	v_and_b32_e32 v241, 0xffff0000, v141
	v_pk_add_f32 v[86:87], v[86:87], v[240:241]
	v_lshlrev_b32_e32 v240, 16, v142
	v_and_b32_e32 v241, 0xffff0000, v142
	v_pk_add_f32 v[80:81], v[80:81], v[240:241]
	v_lshlrev_b32_e32 v240, 16, v143
	v_and_b32_e32 v241, 0xffff0000, v143
	v_pk_add_f32 v[82:83], v[82:83], v[240:241]
	s_add_u32 s42, s62, 0x20800
	s_addc_u32 s43, s63, 0
	global_load_dwordx4 v[140:143], v205, s[42:43] sc0 sc1
	s_waitcnt vmcnt(16)
	v_lshlrev_b32_e32 v240, 16, v144
	v_and_b32_e32 v241, 0xffff0000, v144
	v_pk_add_f32 v[108:109], v[108:109], v[240:241]
	v_lshlrev_b32_e32 v240, 16, v145
	v_and_b32_e32 v241, 0xffff0000, v145
	v_pk_add_f32 v[110:111], v[110:111], v[240:241]
	v_lshlrev_b32_e32 v240, 16, v146
	v_and_b32_e32 v241, 0xffff0000, v146
	v_pk_add_f32 v[104:105], v[104:105], v[240:241]
	v_lshlrev_b32_e32 v240, 16, v147
	v_and_b32_e32 v241, 0xffff0000, v147
	v_pk_add_f32 v[106:107], v[106:107], v[240:241]
	s_add_u32 s98, s62, 0x21800
	s_addc_u32 s99, s63, 0
	global_load_dwordx4 v[144:147], v205, s[98:99] sc0 sc1
	s_waitcnt vmcnt(16)
	v_lshlrev_b32_e32 v240, 16, v148
	v_and_b32_e32 v241, 0xffff0000, v148
	v_pk_add_f32 v[76:77], v[76:77], v[240:241]
	v_lshlrev_b32_e32 v240, 16, v149
	v_and_b32_e32 v241, 0xffff0000, v149
	v_pk_add_f32 v[78:79], v[78:79], v[240:241]
	v_lshlrev_b32_e32 v240, 16, v150
	v_and_b32_e32 v241, 0xffff0000, v150
	v_pk_add_f32 v[72:73], v[72:73], v[240:241]
	v_lshlrev_b32_e32 v240, 16, v151
	v_and_b32_e32 v241, 0xffff0000, v151
	v_pk_add_f32 v[74:75], v[74:75], v[240:241]
	s_add_u32 s42, s62, 0x20c00
	s_addc_u32 s43, s63, 0
	global_load_dwordx4 v[148:151], v205, s[42:43] sc0 sc1
	s_waitcnt vmcnt(16)
	v_lshlrev_b32_e32 v240, 16, v152
	v_and_b32_e32 v241, 0xffff0000, v152
	v_pk_add_f32 v[100:101], v[100:101], v[240:241]
	v_lshlrev_b32_e32 v240, 16, v153
	v_and_b32_e32 v241, 0xffff0000, v153
	v_pk_add_f32 v[102:103], v[102:103], v[240:241]
	v_lshlrev_b32_e32 v240, 16, v154
	v_and_b32_e32 v241, 0xffff0000, v154
	v_pk_add_f32 v[96:97], v[96:97], v[240:241]
	v_lshlrev_b32_e32 v240, 16, v155
	v_and_b32_e32 v241, 0xffff0000, v155
	v_pk_add_f32 v[98:99], v[98:99], v[240:241]
	s_add_u32 s98, s62, 0x21c00
	s_addc_u32 s99, s63, 0
	global_load_dwordx4 v[152:155], v205, s[98:99] sc0 sc1
	s_waitcnt vmcnt(16)
	v_lshlrev_b32_e32 v240, 16, v156
	v_and_b32_e32 v241, 0xffff0000, v156
	v_pk_add_f32 v[68:69], v[68:69], v[240:241]
	v_lshlrev_b32_e32 v240, 16, v157
	v_and_b32_e32 v241, 0xffff0000, v157
	v_pk_add_f32 v[70:71], v[70:71], v[240:241]
	v_lshlrev_b32_e32 v240, 16, v158
	v_and_b32_e32 v241, 0xffff0000, v158
	v_pk_add_f32 v[64:65], v[64:65], v[240:241]
	v_lshlrev_b32_e32 v240, 16, v159
	v_and_b32_e32 v241, 0xffff0000, v159
	v_pk_add_f32 v[66:67], v[66:67], v[240:241]
	s_add_u32 s42, s62, 0x22000
	s_addc_u32 s43, s63, 0
	global_load_dwordx4 v[156:159], v205, s[42:43] sc0 sc1
	s_waitcnt vmcnt(16)
	v_lshlrev_b32_e32 v240, 16, v160
	v_and_b32_e32 v241, 0xffff0000, v160
	v_pk_add_f32 v[60:61], v[60:61], v[240:241]
	v_lshlrev_b32_e32 v240, 16, v161
	v_and_b32_e32 v241, 0xffff0000, v161
	v_pk_add_f32 v[62:63], v[62:63], v[240:241]
	v_lshlrev_b32_e32 v240, 16, v162
	v_and_b32_e32 v241, 0xffff0000, v162
	v_pk_add_f32 v[56:57], v[56:57], v[240:241]
	v_lshlrev_b32_e32 v240, 16, v163
	v_and_b32_e32 v241, 0xffff0000, v163
	v_pk_add_f32 v[58:59], v[58:59], v[240:241]
	s_add_u32 s98, s62, 0x23000
	s_addc_u32 s99, s63, 0
	global_load_dwordx4 v[160:163], v205, s[98:99] sc0 sc1
	s_waitcnt vmcnt(16)
	v_lshlrev_b32_e32 v240, 16, v164
	v_and_b32_e32 v241, 0xffff0000, v164
	v_pk_add_f32 v[28:29], v[28:29], v[240:241]
	v_lshlrev_b32_e32 v240, 16, v165
	v_and_b32_e32 v241, 0xffff0000, v165
	v_pk_add_f32 v[30:31], v[30:31], v[240:241]
	v_lshlrev_b32_e32 v240, 16, v166
	v_and_b32_e32 v241, 0xffff0000, v166
	v_pk_add_f32 v[24:25], v[24:25], v[240:241]
	v_lshlrev_b32_e32 v240, 16, v167
	v_and_b32_e32 v241, 0xffff0000, v167
	v_pk_add_f32 v[26:27], v[26:27], v[240:241]
	s_add_u32 s42, s62, 0x22400
	s_addc_u32 s43, s63, 0
	global_load_dwordx4 v[164:167], v205, s[42:43] sc0 sc1
	s_waitcnt vmcnt(16)
	v_lshlrev_b32_e32 v240, 16, v168
	v_and_b32_e32 v241, 0xffff0000, v168
	v_pk_add_f32 v[52:53], v[52:53], v[240:241]
	v_lshlrev_b32_e32 v240, 16, v169
	v_and_b32_e32 v241, 0xffff0000, v169
	v_pk_add_f32 v[54:55], v[54:55], v[240:241]
	v_lshlrev_b32_e32 v240, 16, v170
	v_and_b32_e32 v241, 0xffff0000, v170
	v_pk_add_f32 v[48:49], v[48:49], v[240:241]
	v_lshlrev_b32_e32 v240, 16, v171
	v_and_b32_e32 v241, 0xffff0000, v171
	v_pk_add_f32 v[50:51], v[50:51], v[240:241]
	s_add_u32 s98, s62, 0x23400
	s_addc_u32 s99, s63, 0
	global_load_dwordx4 v[168:171], v205, s[98:99] sc0 sc1
	s_waitcnt vmcnt(16)
	v_lshlrev_b32_e32 v240, 16, v172
	v_and_b32_e32 v241, 0xffff0000, v172
	v_pk_add_f32 v[20:21], v[20:21], v[240:241]
	v_lshlrev_b32_e32 v240, 16, v173
	v_and_b32_e32 v241, 0xffff0000, v173
	v_pk_add_f32 v[22:23], v[22:23], v[240:241]
	v_lshlrev_b32_e32 v240, 16, v174
	v_and_b32_e32 v241, 0xffff0000, v174
	v_pk_add_f32 v[16:17], v[16:17], v[240:241]
	v_lshlrev_b32_e32 v240, 16, v175
	v_and_b32_e32 v241, 0xffff0000, v175
	v_pk_add_f32 v[18:19], v[18:19], v[240:241]
	s_add_u32 s42, s62, 0x22800
	s_addc_u32 s43, s63, 0
	global_load_dwordx4 v[172:175], v205, s[42:43] sc0 sc1
	s_waitcnt vmcnt(16)
	v_lshlrev_b32_e32 v240, 16, v176
	v_and_b32_e32 v241, 0xffff0000, v176
	v_pk_add_f32 v[44:45], v[44:45], v[240:241]
	v_lshlrev_b32_e32 v240, 16, v177
	v_and_b32_e32 v241, 0xffff0000, v177
	v_pk_add_f32 v[46:47], v[46:47], v[240:241]
	v_lshlrev_b32_e32 v240, 16, v178
	v_and_b32_e32 v241, 0xffff0000, v178
	v_pk_add_f32 v[40:41], v[40:41], v[240:241]
	v_lshlrev_b32_e32 v240, 16, v179
	v_and_b32_e32 v241, 0xffff0000, v179
	v_pk_add_f32 v[42:43], v[42:43], v[240:241]
	s_add_u32 s98, s62, 0x23800
	s_addc_u32 s99, s63, 0
	global_load_dwordx4 v[176:179], v205, s[98:99] sc0 sc1
	s_waitcnt vmcnt(16)
	v_lshlrev_b32_e32 v240, 16, v180
	v_and_b32_e32 v241, 0xffff0000, v180
	v_pk_add_f32 v[12:13], v[12:13], v[240:241]
	v_lshlrev_b32_e32 v240, 16, v181
	v_and_b32_e32 v241, 0xffff0000, v181
	v_pk_add_f32 v[14:15], v[14:15], v[240:241]
	v_lshlrev_b32_e32 v240, 16, v182
	v_and_b32_e32 v241, 0xffff0000, v182
	v_pk_add_f32 v[8:9], v[8:9], v[240:241]
	v_lshlrev_b32_e32 v240, 16, v183
	v_and_b32_e32 v241, 0xffff0000, v183
	v_pk_add_f32 v[10:11], v[10:11], v[240:241]
	s_add_u32 s42, s62, 0x22c00
	s_addc_u32 s43, s63, 0
	global_load_dwordx4 v[180:183], v205, s[42:43] sc0 sc1
	s_waitcnt vmcnt(16)
	v_lshlrev_b32_e32 v240, 16, v206
	v_and_b32_e32 v241, 0xffff0000, v206
	v_pk_add_f32 v[36:37], v[36:37], v[240:241]
	v_lshlrev_b32_e32 v240, 16, v207
	v_and_b32_e32 v241, 0xffff0000, v207
	v_pk_add_f32 v[38:39], v[38:39], v[240:241]
	v_lshlrev_b32_e32 v240, 16, v208
	v_and_b32_e32 v241, 0xffff0000, v208
	v_pk_add_f32 v[32:33], v[32:33], v[240:241]
	v_lshlrev_b32_e32 v240, 16, v209
	v_and_b32_e32 v241, 0xffff0000, v209
	v_pk_add_f32 v[34:35], v[34:35], v[240:241]
	s_add_u32 s98, s62, 0x23c00
	s_addc_u32 s99, s63, 0
	global_load_dwordx4 v[206:209], v205, s[98:99] sc0 sc1
	s_waitcnt vmcnt(16)
	v_lshlrev_b32_e32 v240, 16, v210
	v_and_b32_e32 v241, 0xffff0000, v210
	v_pk_add_f32 v[4:5], v[4:5], v[240:241]
	v_lshlrev_b32_e32 v240, 16, v211
	v_and_b32_e32 v241, 0xffff0000, v211
	v_pk_add_f32 v[6:7], v[6:7], v[240:241]
	v_lshlrev_b32_e32 v240, 16, v212
	v_and_b32_e32 v241, 0xffff0000, v212
	v_pk_add_f32 v[0:1], v[0:1], v[240:241]
	v_lshlrev_b32_e32 v240, 16, v213
	v_and_b32_e32 v241, 0xffff0000, v213
	v_pk_add_f32 v[2:3], v[2:3], v[240:241]
	s_add_u32 s42, s14, 0x0
	s_addc_u32 s43, s15, 0
	global_load_dwordx4 v[210:213], v235, s[42:43]
	s_waitcnt vmcnt(16)
	v_lshlrev_b32_e32 v240, 16, v236
	v_and_b32_e32 v241, 0xffff0000, v236
	v_pk_add_f32 v[124:125], v[124:125], v[240:241]
	v_lshlrev_b32_e32 v240, 16, v237
	v_and_b32_e32 v241, 0xffff0000, v237
	v_pk_add_f32 v[126:127], v[126:127], v[240:241]
	v_lshlrev_b32_e32 v240, 16, v238
	v_and_b32_e32 v241, 0xffff0000, v238
	v_pk_add_f32 v[120:121], v[120:121], v[240:241]
	v_lshlrev_b32_e32 v240, 16, v239
	v_and_b32_e32 v241, 0xffff0000, v239
	v_pk_add_f32 v[122:123], v[122:123], v[240:241]
	s_add_u32 s98, s10, 0x0
	s_addc_u32 s99, s11, 0
	global_load_dwordx4 v[236:239], v203, s[98:99]
	s_waitcnt vmcnt(16)
	v_lshlrev_b32_e32 v240, 16, v128
	v_and_b32_e32 v241, 0xffff0000, v128
	v_pk_add_f32 v[92:93], v[92:93], v[240:241]
	v_lshlrev_b32_e32 v240, 16, v129
	v_and_b32_e32 v241, 0xffff0000, v129
	v_pk_add_f32 v[94:95], v[94:95], v[240:241]
	v_lshlrev_b32_e32 v240, 16, v130
	v_and_b32_e32 v241, 0xffff0000, v130
	v_pk_add_f32 v[88:89], v[88:89], v[240:241]
	v_lshlrev_b32_e32 v240, 16, v131
	v_and_b32_e32 v241, 0xffff0000, v131
	v_pk_add_f32 v[90:91], v[90:91], v[240:241]
	s_add_u32 s42, s14, 0x0
	s_addc_u32 s43, s15, 0
	global_load_dwordx4 v[128:131], v235, s[42:43] offset:16
	s_waitcnt vmcnt(16)
	v_lshlrev_b32_e32 v240, 16, v132
	v_and_b32_e32 v241, 0xffff0000, v132
	v_pk_add_f32 v[116:117], v[116:117], v[240:241]
	v_lshlrev_b32_e32 v240, 16, v133
	v_and_b32_e32 v241, 0xffff0000, v133
	v_pk_add_f32 v[118:119], v[118:119], v[240:241]
	v_lshlrev_b32_e32 v240, 16, v134
	v_and_b32_e32 v241, 0xffff0000, v134
	v_pk_add_f32 v[112:113], v[112:113], v[240:241]
	v_lshlrev_b32_e32 v240, 16, v135
	v_and_b32_e32 v241, 0xffff0000, v135
	v_pk_add_f32 v[114:115], v[114:115], v[240:241]
	s_add_u32 s98, s10, 0x0
	s_addc_u32 s99, s11, 0
	global_load_dwordx4 v[132:135], v203, s[98:99] offset:16
	s_waitcnt vmcnt(16)
	v_lshlrev_b32_e32 v240, 16, v136
	v_and_b32_e32 v241, 0xffff0000, v136
	v_pk_add_f32 v[84:85], v[84:85], v[240:241]
	v_lshlrev_b32_e32 v240, 16, v137
	v_and_b32_e32 v241, 0xffff0000, v137
	v_pk_add_f32 v[86:87], v[86:87], v[240:241]
	v_lshlrev_b32_e32 v240, 16, v138
	v_and_b32_e32 v241, 0xffff0000, v138
	v_pk_add_f32 v[80:81], v[80:81], v[240:241]
	v_lshlrev_b32_e32 v240, 16, v139
	v_and_b32_e32 v241, 0xffff0000, v139
	v_pk_add_f32 v[82:83], v[82:83], v[240:241]
	s_add_u32 s42, s14, 0x200
	s_addc_u32 s43, s15, 0
	global_load_dwordx4 v[136:139], v235, s[42:43]
	s_waitcnt vmcnt(16)
	v_lshlrev_b32_e32 v240, 16, v140
	v_and_b32_e32 v241, 0xffff0000, v140
	v_pk_add_f32 v[108:109], v[108:109], v[240:241]
	v_lshlrev_b32_e32 v240, 16, v141
	v_and_b32_e32 v241, 0xffff0000, v141
	v_pk_add_f32 v[110:111], v[110:111], v[240:241]
	v_lshlrev_b32_e32 v240, 16, v142
	v_and_b32_e32 v241, 0xffff0000, v142
	v_pk_add_f32 v[104:105], v[104:105], v[240:241]
	v_lshlrev_b32_e32 v240, 16, v143
	v_and_b32_e32 v241, 0xffff0000, v143
	v_pk_add_f32 v[106:107], v[106:107], v[240:241]
	s_add_u32 s98, s10, 0x200
	s_addc_u32 s99, s11, 0
	global_load_dwordx4 v[140:143], v203, s[98:99]
	s_waitcnt vmcnt(16)
	v_lshlrev_b32_e32 v240, 16, v144
	v_and_b32_e32 v241, 0xffff0000, v144
	v_pk_add_f32 v[76:77], v[76:77], v[240:241]
	v_lshlrev_b32_e32 v240, 16, v145
	v_and_b32_e32 v241, 0xffff0000, v145
	v_pk_add_f32 v[78:79], v[78:79], v[240:241]
	v_lshlrev_b32_e32 v240, 16, v146
	v_and_b32_e32 v241, 0xffff0000, v146
	v_pk_add_f32 v[72:73], v[72:73], v[240:241]
	v_lshlrev_b32_e32 v240, 16, v147
	v_and_b32_e32 v241, 0xffff0000, v147
	v_pk_add_f32 v[74:75], v[74:75], v[240:241]
	s_add_u32 s42, s14, 0x200
	s_addc_u32 s43, s15, 0
	global_load_dwordx4 v[144:147], v235, s[42:43] offset:16
	s_waitcnt vmcnt(16)
	v_lshlrev_b32_e32 v240, 16, v148
	v_and_b32_e32 v241, 0xffff0000, v148
	v_pk_add_f32 v[100:101], v[100:101], v[240:241]
	v_lshlrev_b32_e32 v240, 16, v149
	v_and_b32_e32 v241, 0xffff0000, v149
	v_pk_add_f32 v[102:103], v[102:103], v[240:241]
	v_lshlrev_b32_e32 v240, 16, v150
	v_and_b32_e32 v241, 0xffff0000, v150
	v_pk_add_f32 v[96:97], v[96:97], v[240:241]
	v_lshlrev_b32_e32 v240, 16, v151
	v_and_b32_e32 v241, 0xffff0000, v151
	v_pk_add_f32 v[98:99], v[98:99], v[240:241]
	s_add_u32 s98, s10, 0x200
	s_addc_u32 s99, s11, 0
	global_load_dwordx4 v[148:151], v203, s[98:99] offset:16
	s_waitcnt vmcnt(16)
	v_lshlrev_b32_e32 v240, 16, v152
	v_and_b32_e32 v241, 0xffff0000, v152
	v_pk_add_f32 v[68:69], v[68:69], v[240:241]
	v_lshlrev_b32_e32 v240, 16, v153
	v_and_b32_e32 v241, 0xffff0000, v153
	v_pk_add_f32 v[70:71], v[70:71], v[240:241]
	v_lshlrev_b32_e32 v240, 16, v154
	v_and_b32_e32 v241, 0xffff0000, v154
	v_pk_add_f32 v[64:65], v[64:65], v[240:241]
	v_lshlrev_b32_e32 v240, 16, v155
	v_and_b32_e32 v241, 0xffff0000, v155
	v_pk_add_f32 v[66:67], v[66:67], v[240:241]
	s_add_u32 s42, s14, 0x18000
	s_addc_u32 s43, s15, 0
	global_load_dwordx4 v[152:155], v235, s[42:43]
	s_waitcnt vmcnt(16)
	v_lshlrev_b32_e32 v240, 16, v156
	v_and_b32_e32 v241, 0xffff0000, v156
	v_pk_add_f32 v[60:61], v[60:61], v[240:241]
	v_lshlrev_b32_e32 v240, 16, v157
	v_and_b32_e32 v241, 0xffff0000, v157
	v_pk_add_f32 v[62:63], v[62:63], v[240:241]
	v_lshlrev_b32_e32 v240, 16, v158
	v_and_b32_e32 v241, 0xffff0000, v158
	v_pk_add_f32 v[56:57], v[56:57], v[240:241]
	v_lshlrev_b32_e32 v240, 16, v159
	v_and_b32_e32 v241, 0xffff0000, v159
	v_pk_add_f32 v[58:59], v[58:59], v[240:241]
	s_add_u32 s98, s10, 0x10000
	s_addc_u32 s99, s11, 0
	global_load_dwordx4 v[156:159], v203, s[98:99]
	s_waitcnt vmcnt(16)
	v_lshlrev_b32_e32 v240, 16, v160
	v_and_b32_e32 v241, 0xffff0000, v160
	v_pk_add_f32 v[28:29], v[28:29], v[240:241]
	v_lshlrev_b32_e32 v240, 16, v161
	v_and_b32_e32 v241, 0xffff0000, v161
	v_pk_add_f32 v[30:31], v[30:31], v[240:241]
	v_lshlrev_b32_e32 v240, 16, v162
	v_and_b32_e32 v241, 0xffff0000, v162
	v_pk_add_f32 v[24:25], v[24:25], v[240:241]
	v_lshlrev_b32_e32 v240, 16, v163
	v_and_b32_e32 v241, 0xffff0000, v163
	v_pk_add_f32 v[26:27], v[26:27], v[240:241]
	s_add_u32 s42, s14, 0x18000
	s_addc_u32 s43, s15, 0
	global_load_dwordx4 v[160:163], v235, s[42:43] offset:16
	s_waitcnt vmcnt(16)
	v_lshlrev_b32_e32 v240, 16, v164
	v_and_b32_e32 v241, 0xffff0000, v164
	v_pk_add_f32 v[52:53], v[52:53], v[240:241]
	v_lshlrev_b32_e32 v240, 16, v165
	v_and_b32_e32 v241, 0xffff0000, v165
	v_pk_add_f32 v[54:55], v[54:55], v[240:241]
	v_lshlrev_b32_e32 v240, 16, v166
	v_and_b32_e32 v241, 0xffff0000, v166
	v_pk_add_f32 v[48:49], v[48:49], v[240:241]
	v_lshlrev_b32_e32 v240, 16, v167
	v_and_b32_e32 v241, 0xffff0000, v167
	v_pk_add_f32 v[50:51], v[50:51], v[240:241]
	s_add_u32 s98, s10, 0x10000
	s_addc_u32 s99, s11, 0
	global_load_dwordx4 v[164:167], v203, s[98:99] offset:16
	s_waitcnt vmcnt(16)
	v_lshlrev_b32_e32 v240, 16, v168
	v_and_b32_e32 v241, 0xffff0000, v168
	v_pk_add_f32 v[20:21], v[20:21], v[240:241]
	v_lshlrev_b32_e32 v240, 16, v169
	v_and_b32_e32 v241, 0xffff0000, v169
	v_pk_add_f32 v[22:23], v[22:23], v[240:241]
	v_lshlrev_b32_e32 v240, 16, v170
	v_and_b32_e32 v241, 0xffff0000, v170
	v_pk_add_f32 v[16:17], v[16:17], v[240:241]
	v_lshlrev_b32_e32 v240, 16, v171
	v_and_b32_e32 v241, 0xffff0000, v171
	v_pk_add_f32 v[18:19], v[18:19], v[240:241]
	s_add_u32 s42, s14, 0x18200
	s_addc_u32 s43, s15, 0
	global_load_dwordx4 v[168:171], v235, s[42:43]
	s_waitcnt vmcnt(16)
	v_lshlrev_b32_e32 v240, 16, v172
	v_and_b32_e32 v241, 0xffff0000, v172
	v_pk_add_f32 v[44:45], v[44:45], v[240:241]
	v_lshlrev_b32_e32 v240, 16, v173
	v_and_b32_e32 v241, 0xffff0000, v173
	v_pk_add_f32 v[46:47], v[46:47], v[240:241]
	v_lshlrev_b32_e32 v240, 16, v174
	v_and_b32_e32 v241, 0xffff0000, v174
	v_pk_add_f32 v[40:41], v[40:41], v[240:241]
	v_lshlrev_b32_e32 v240, 16, v175
	v_and_b32_e32 v241, 0xffff0000, v175
	v_pk_add_f32 v[42:43], v[42:43], v[240:241]
	s_add_u32 s98, s10, 0x10200
	s_addc_u32 s99, s11, 0
	global_load_dwordx4 v[172:175], v203, s[98:99]
	s_waitcnt vmcnt(16)
	v_lshlrev_b32_e32 v240, 16, v176
	v_and_b32_e32 v241, 0xffff0000, v176
	v_pk_add_f32 v[12:13], v[12:13], v[240:241]
	v_lshlrev_b32_e32 v240, 16, v177
	v_and_b32_e32 v241, 0xffff0000, v177
	v_pk_add_f32 v[14:15], v[14:15], v[240:241]
	v_lshlrev_b32_e32 v240, 16, v178
	v_and_b32_e32 v241, 0xffff0000, v178
	v_pk_add_f32 v[8:9], v[8:9], v[240:241]
	v_lshlrev_b32_e32 v240, 16, v179
	v_and_b32_e32 v241, 0xffff0000, v179
	v_pk_add_f32 v[10:11], v[10:11], v[240:241]
	s_add_u32 s42, s14, 0x18200
	s_addc_u32 s43, s15, 0
	global_load_dwordx4 v[176:179], v235, s[42:43] offset:16
	s_waitcnt vmcnt(16)
	v_lshlrev_b32_e32 v240, 16, v180
	v_and_b32_e32 v241, 0xffff0000, v180
	v_pk_add_f32 v[36:37], v[36:37], v[240:241]
	v_lshlrev_b32_e32 v240, 16, v181
	v_and_b32_e32 v241, 0xffff0000, v181
	v_pk_add_f32 v[38:39], v[38:39], v[240:241]
	v_lshlrev_b32_e32 v240, 16, v182
	v_and_b32_e32 v241, 0xffff0000, v182
	v_pk_add_f32 v[32:33], v[32:33], v[240:241]
	v_lshlrev_b32_e32 v240, 16, v183
	v_and_b32_e32 v241, 0xffff0000, v183
	v_pk_add_f32 v[34:35], v[34:35], v[240:241]
	s_add_u32 s98, s10, 0x10200
	s_addc_u32 s99, s11, 0
	global_load_dwordx4 v[180:183], v203, s[98:99] offset:16
	s_waitcnt vmcnt(16)
	v_lshlrev_b32_e32 v240, 16, v206
	v_and_b32_e32 v241, 0xffff0000, v206
	v_pk_add_f32 v[4:5], v[4:5], v[240:241]
	v_lshlrev_b32_e32 v240, 16, v207
	v_and_b32_e32 v241, 0xffff0000, v207
	v_pk_add_f32 v[6:7], v[6:7], v[240:241]
	v_lshlrev_b32_e32 v240, 16, v208
	v_and_b32_e32 v241, 0xffff0000, v208
	v_pk_add_f32 v[0:1], v[0:1], v[240:241]
	v_lshlrev_b32_e32 v240, 16, v209
	v_and_b32_e32 v241, 0xffff0000, v209
	v_pk_add_f32 v[2:3], v[2:3], v[240:241]
	s_add_u32 s42, s14, 0x30000
	s_addc_u32 s43, s15, 0
	global_load_dwordx4 v[206:209], v235, s[42:43]
	s_waitcnt vmcnt(15)
	v_pk_fma_f32 v[124:125], v[210:211], v[124:125], v[236:237]
	v_pk_fma_f32 v[126:127], v[212:213], v[126:127], v[238:239]
	s_add_u32 s98, s10, 0x0
	s_addc_u32 s99, s11, 0
	global_store_dwordx4 v203, v[124:127], s[98:99] nt
	s_add_u32 s42, s10, 0x20000
	s_addc_u32 s43, s11, 0
	global_load_dwordx4 v[210:213], v203, s[42:43]
	s_add_u32 s98, s14, 0x30000
	s_addc_u32 s99, s15, 0
	global_load_dwordx4 v[236:239], v235, s[98:99] offset:16
	s_waitcnt vmcnt(16)
	v_pk_fma_f32 v[120:121], v[128:129], v[120:121], v[132:133]
	v_pk_fma_f32 v[122:123], v[130:131], v[122:123], v[134:135]
	s_add_u32 s42, s10, 0x0
	s_addc_u32 s43, s11, 0
	global_store_dwordx4 v203, v[120:123], s[42:43] offset:16 nt
	s_add_u32 s98, s10, 0x20000
	s_addc_u32 s99, s11, 0
	global_load_dwordx4 v[128:131], v203, s[98:99] offset:16
	s_add_u32 s42, s14, 0x30200
	s_addc_u32 s43, s15, 0
	global_load_dwordx4 v[132:135], v235, s[42:43]
	s_waitcnt vmcnt(17)
	v_pk_fma_f32 v[92:93], v[136:137], v[92:93], v[140:141]
	v_pk_fma_f32 v[94:95], v[138:139], v[94:95], v[142:143]
	s_add_u32 s98, s10, 0x200
	s_addc_u32 s99, s11, 0
	global_store_dwordx4 v203, v[92:95], s[98:99] nt
	s_add_u32 s42, s10, 0x20200
	s_addc_u32 s43, s11, 0
	global_load_dwordx4 v[136:139], v203, s[42:43]
	s_add_u32 s98, s14, 0x30200
	s_addc_u32 s99, s15, 0
	global_load_dwordx4 v[140:143], v235, s[98:99] offset:16
	s_waitcnt vmcnt(18)
	v_pk_fma_f32 v[88:89], v[144:145], v[88:89], v[148:149]
	v_pk_fma_f32 v[90:91], v[146:147], v[90:91], v[150:151]
	s_add_u32 s42, s10, 0x200
	s_addc_u32 s43, s11, 0
	global_store_dwordx4 v203, v[88:91], s[42:43] offset:16 nt
	s_add_u32 s98, s10, 0x20200
	s_addc_u32 s99, s11, 0
	global_load_dwordx4 v[144:147], v203, s[98:99] offset:16
	s_add_u32 s42, s14, 0x48000
	s_addc_u32 s43, s15, 0
	global_load_dwordx4 v[148:151], v235, s[42:43]
	s_waitcnt vmcnt(19)
	v_pk_fma_f32 v[116:117], v[152:153], v[116:117], v[156:157]
	v_pk_fma_f32 v[118:119], v[154:155], v[118:119], v[158:159]
	s_add_u32 s98, s10, 0x10000
	s_addc_u32 s99, s11, 0
	global_store_dwordx4 v203, v[116:119], s[98:99] nt
	s_add_u32 s42, s10, 0x30000
	s_addc_u32 s43, s11, 0
	global_load_dwordx4 v[152:155], v203, s[42:43]
	s_add_u32 s98, s14, 0x48000
	s_addc_u32 s99, s15, 0
	global_load_dwordx4 v[156:159], v235, s[98:99] offset:16
	s_waitcnt vmcnt(20)
	v_pk_fma_f32 v[112:113], v[160:161], v[112:113], v[164:165]
	v_pk_fma_f32 v[114:115], v[162:163], v[114:115], v[166:167]
	s_add_u32 s42, s10, 0x10000
	s_addc_u32 s43, s11, 0
	global_store_dwordx4 v203, v[112:115], s[42:43] offset:16 nt
	s_add_u32 s98, s10, 0x30000
	s_addc_u32 s99, s11, 0
	global_load_dwordx4 v[160:163], v203, s[98:99] offset:16
	s_add_u32 s42, s14, 0x48200
	s_addc_u32 s43, s15, 0
	global_load_dwordx4 v[164:167], v235, s[42:43]
	s_waitcnt vmcnt(21)
	v_pk_fma_f32 v[84:85], v[168:169], v[84:85], v[172:173]
	v_pk_fma_f32 v[86:87], v[170:171], v[86:87], v[174:175]
	s_add_u32 s98, s10, 0x10200
	s_addc_u32 s99, s11, 0
	global_store_dwordx4 v203, v[84:87], s[98:99] nt
	s_add_u32 s42, s10, 0x30200
	s_addc_u32 s43, s11, 0
	global_load_dwordx4 v[168:171], v203, s[42:43]
	s_add_u32 s98, s14, 0x48200
	s_addc_u32 s99, s15, 0
	global_load_dwordx4 v[172:175], v235, s[98:99] offset:16
	s_waitcnt vmcnt(22)
	v_pk_fma_f32 v[80:81], v[176:177], v[80:81], v[180:181]
	v_pk_fma_f32 v[82:83], v[178:179], v[82:83], v[182:183]
	s_add_u32 s42, s10, 0x10200
	s_addc_u32 s43, s11, 0
	global_store_dwordx4 v203, v[80:83], s[42:43] offset:16 nt
	s_add_u32 s98, s10, 0x30200
	s_addc_u32 s99, s11, 0
	global_load_dwordx4 v[176:179], v203, s[98:99] offset:16
	s_add_u32 s42, s14, 0xc0000
	s_addc_u32 s43, s15, 0
	global_load_dwordx4 v[180:183], v235, s[42:43]
	s_waitcnt vmcnt(22)
	v_pk_fma_f32 v[108:109], v[206:207], v[108:109], v[210:211]
	v_pk_fma_f32 v[110:111], v[208:209], v[110:111], v[212:213]
	s_add_u32 s98, s10, 0x20000
	s_addc_u32 s99, s11, 0
	global_store_dwordx4 v203, v[108:111], s[98:99] nt
	s_add_u32 s42, s10, 0x80000
	s_addc_u32 s43, s11, 0
	global_load_dwordx4 v[206:209], v203, s[42:43]
	s_add_u32 s98, s14, 0xc0000
	s_addc_u32 s99, s15, 0
	global_load_dwordx4 v[210:213], v235, s[98:99] offset:16
	s_waitcnt vmcnt(22)
	v_pk_fma_f32 v[104:105], v[236:237], v[104:105], v[128:129]
	v_pk_fma_f32 v[106:107], v[238:239], v[106:107], v[130:131]
	s_add_u32 s42, s10, 0x20000
	s_addc_u32 s43, s11, 0
	global_store_dwordx4 v203, v[104:107], s[42:43] offset:16 nt
	s_add_u32 s98, s10, 0x80000
	s_addc_u32 s99, s11, 0
	global_load_dwordx4 v[236:239], v203, s[98:99] offset:16
	s_add_u32 s42, s14, 0xc0200
	s_addc_u32 s43, s15, 0
	global_load_dwordx4 v[128:131], v235, s[42:43]
	s_waitcnt vmcnt(22)
	v_pk_fma_f32 v[76:77], v[132:133], v[76:77], v[136:137]
	v_pk_fma_f32 v[78:79], v[134:135], v[78:79], v[138:139]
	s_add_u32 s98, s10, 0x20200
	s_addc_u32 s99, s11, 0
	global_store_dwordx4 v203, v[76:79], s[98:99] nt
	s_add_u32 s42, s10, 0x80200
	s_addc_u32 s43, s11, 0
	global_load_dwordx4 v[132:135], v203, s[42:43]
	s_add_u32 s98, s14, 0xc0200
	s_addc_u32 s99, s15, 0
	global_load_dwordx4 v[136:139], v235, s[98:99] offset:16
	s_waitcnt vmcnt(22)
	v_pk_fma_f32 v[72:73], v[140:141], v[72:73], v[144:145]
	v_pk_fma_f32 v[74:75], v[142:143], v[74:75], v[146:147]
	s_add_u32 s42, s10, 0x20200
	s_addc_u32 s43, s11, 0
	global_store_dwordx4 v203, v[72:75], s[42:43] offset:16 nt
	s_add_u32 s98, s10, 0x80200
	s_addc_u32 s99, s11, 0
	global_load_dwordx4 v[140:143], v203, s[98:99] offset:16
	s_add_u32 s42, s14, 0xd8000
	s_addc_u32 s43, s15, 0
	global_load_dwordx4 v[144:147], v235, s[42:43]
	s_waitcnt vmcnt(22)
	v_pk_fma_f32 v[100:101], v[148:149], v[100:101], v[152:153]
	v_pk_fma_f32 v[102:103], v[150:151], v[102:103], v[154:155]
	s_add_u32 s98, s10, 0x30000
	s_addc_u32 s99, s11, 0
	global_store_dwordx4 v203, v[100:103], s[98:99] nt
	s_add_u32 s42, s10, 0x90000
	s_addc_u32 s43, s11, 0
	global_load_dwordx4 v[148:151], v203, s[42:43]
	s_add_u32 s98, s14, 0xd8000
	s_addc_u32 s99, s15, 0
	global_load_dwordx4 v[152:155], v235, s[98:99] offset:16
	s_waitcnt vmcnt(22)
	v_pk_fma_f32 v[96:97], v[156:157], v[96:97], v[160:161]
	v_pk_fma_f32 v[98:99], v[158:159], v[98:99], v[162:163]
	s_add_u32 s42, s10, 0x30000
	s_addc_u32 s43, s11, 0
	global_store_dwordx4 v203, v[96:99], s[42:43] offset:16 nt
	s_add_u32 s98, s10, 0x90000
	s_addc_u32 s99, s11, 0
	global_load_dwordx4 v[156:159], v203, s[98:99] offset:16
	s_add_u32 s42, s14, 0xd8200
	s_addc_u32 s43, s15, 0
	global_load_dwordx4 v[160:163], v235, s[42:43]
	s_waitcnt vmcnt(22)
	v_pk_fma_f32 v[68:69], v[164:165], v[68:69], v[168:169]
	v_pk_fma_f32 v[70:71], v[166:167], v[70:71], v[170:171]
	s_add_u32 s98, s10, 0x30200
	s_addc_u32 s99, s11, 0
	global_store_dwordx4 v203, v[68:71], s[98:99] nt
	s_add_u32 s42, s10, 0x90200
	s_addc_u32 s43, s11, 0
	global_load_dwordx4 v[164:167], v203, s[42:43]
	s_add_u32 s98, s14, 0xd8200
	s_addc_u32 s99, s15, 0
	global_load_dwordx4 v[168:171], v235, s[98:99] offset:16
	s_waitcnt vmcnt(22)
	v_pk_fma_f32 v[64:65], v[172:173], v[64:65], v[176:177]
	v_pk_fma_f32 v[66:67], v[174:175], v[66:67], v[178:179]
	s_add_u32 s42, s10, 0x30200
	s_addc_u32 s43, s11, 0
	global_store_dwordx4 v203, v[64:67], s[42:43] offset:16 nt
	s_add_u32 s98, s10, 0x90200
	s_addc_u32 s99, s11, 0
	global_load_dwordx4 v[172:175], v203, s[98:99] offset:16
	s_add_u32 s42, s14, 0xf0000
	s_addc_u32 s43, s15, 0
	global_load_dwordx4 v[176:179], v235, s[42:43]
	s_waitcnt vmcnt(22)
	v_pk_fma_f32 v[60:61], v[180:181], v[60:61], v[206:207]
	v_pk_fma_f32 v[62:63], v[182:183], v[62:63], v[208:209]
	s_add_u32 s98, s10, 0x80000
	s_addc_u32 s99, s11, 0
	global_store_dwordx4 v203, v[60:63], s[98:99] nt
	s_add_u32 s42, s10, 0xa0000
	s_addc_u32 s43, s11, 0
	global_load_dwordx4 v[180:183], v203, s[42:43]
	s_add_u32 s98, s14, 0xf0000
	s_addc_u32 s99, s15, 0
	global_load_dwordx4 v[206:209], v235, s[98:99] offset:16
	s_waitcnt vmcnt(22)
	v_pk_fma_f32 v[56:57], v[210:211], v[56:57], v[236:237]
	v_pk_fma_f32 v[58:59], v[212:213], v[58:59], v[238:239]
	s_add_u32 s42, s10, 0x80000
	s_addc_u32 s43, s11, 0
	global_store_dwordx4 v203, v[56:59], s[42:43] offset:16 nt
	s_add_u32 s98, s10, 0xa0000
	s_addc_u32 s99, s11, 0
	global_load_dwordx4 v[210:213], v203, s[98:99] offset:16
	s_add_u32 s42, s14, 0xf0200
	s_addc_u32 s43, s15, 0
	global_load_dwordx4 v[236:239], v235, s[42:43]
	s_waitcnt vmcnt(22)
	v_pk_fma_f32 v[28:29], v[128:129], v[28:29], v[132:133]
	v_pk_fma_f32 v[30:31], v[130:131], v[30:31], v[134:135]
	s_add_u32 s98, s10, 0x80200
	s_addc_u32 s99, s11, 0
	global_store_dwordx4 v203, v[28:31], s[98:99] nt
	s_add_u32 s42, s10, 0xa0200
	s_addc_u32 s43, s11, 0
	global_load_dwordx4 v[128:131], v203, s[42:43]
	s_add_u32 s98, s14, 0xf0200
	s_addc_u32 s99, s15, 0
	global_load_dwordx4 v[132:135], v235, s[98:99] offset:16
	s_waitcnt vmcnt(22)
	v_pk_fma_f32 v[24:25], v[136:137], v[24:25], v[140:141]
	v_pk_fma_f32 v[26:27], v[138:139], v[26:27], v[142:143]
	s_add_u32 s42, s10, 0x80200
	s_addc_u32 s43, s11, 0
	global_store_dwordx4 v203, v[24:27], s[42:43] offset:16 nt
	s_add_u32 s98, s10, 0xa0200
	s_addc_u32 s99, s11, 0
	global_load_dwordx4 v[136:139], v203, s[98:99] offset:16
	s_add_u32 s42, s14, 0x108000
	s_addc_u32 s43, s15, 0
	global_load_dwordx4 v[140:143], v235, s[42:43]
	s_waitcnt vmcnt(22)
	v_pk_fma_f32 v[52:53], v[144:145], v[52:53], v[148:149]
	v_pk_fma_f32 v[54:55], v[146:147], v[54:55], v[150:151]
	s_add_u32 s98, s10, 0x90000
	s_addc_u32 s99, s11, 0
	global_store_dwordx4 v203, v[52:55], s[98:99] nt
	s_add_u32 s42, s10, 0xb0000
	s_addc_u32 s43, s11, 0
	global_load_dwordx4 v[144:147], v203, s[42:43]
	s_add_u32 s98, s14, 0x108000
	s_addc_u32 s99, s15, 0
	global_load_dwordx4 v[148:151], v235, s[98:99] offset:16
	s_waitcnt vmcnt(22)
	v_pk_fma_f32 v[48:49], v[152:153], v[48:49], v[156:157]
	v_pk_fma_f32 v[50:51], v[154:155], v[50:51], v[158:159]
	s_add_u32 s42, s10, 0x90000
	s_addc_u32 s43, s11, 0
	global_store_dwordx4 v203, v[48:51], s[42:43] offset:16 nt
	s_add_u32 s98, s10, 0xb0000
	s_addc_u32 s99, s11, 0
	global_load_dwordx4 v[152:155], v203, s[98:99] offset:16
	s_add_u32 s42, s14, 0x108200
	s_addc_u32 s43, s15, 0
	global_load_dwordx4 v[156:159], v235, s[42:43]
	s_waitcnt vmcnt(22)
	v_pk_fma_f32 v[20:21], v[160:161], v[20:21], v[164:165]
	v_pk_fma_f32 v[22:23], v[162:163], v[22:23], v[166:167]
	s_add_u32 s98, s10, 0x90200
	s_addc_u32 s99, s11, 0
	global_store_dwordx4 v203, v[20:23], s[98:99] nt
	s_add_u32 s42, s10, 0xb0200
	s_addc_u32 s43, s11, 0
	global_load_dwordx4 v[160:163], v203, s[42:43]
	s_add_u32 s98, s14, 0x108200
	s_addc_u32 s99, s15, 0
	global_load_dwordx4 v[164:167], v235, s[98:99] offset:16
	s_waitcnt vmcnt(22)
	v_pk_fma_f32 v[16:17], v[168:169], v[16:17], v[172:173]
	v_pk_fma_f32 v[18:19], v[170:171], v[18:19], v[174:175]
	s_add_u32 s42, s10, 0x90200
	s_addc_u32 s43, s11, 0
	global_store_dwordx4 v203, v[16:19], s[42:43] offset:16 nt
	s_add_u32 s98, s10, 0xb0200
	s_addc_u32 s99, s11, 0
	global_load_dwordx4 v[168:171], v203, s[98:99] offset:16
	s_waitcnt vmcnt(21)
	v_pk_fma_f32 v[44:45], v[176:177], v[44:45], v[180:181]
	v_pk_fma_f32 v[46:47], v[178:179], v[46:47], v[182:183]
	s_add_u32 s42, s10, 0xa0000
	s_addc_u32 s43, s11, 0
	global_store_dwordx4 v203, v[44:47], s[42:43] nt
	s_waitcnt vmcnt(19)
	v_pk_fma_f32 v[40:41], v[206:207], v[40:41], v[210:211]
	v_pk_fma_f32 v[42:43], v[208:209], v[42:43], v[212:213]
	s_add_u32 s98, s10, 0xa0000
	s_addc_u32 s99, s11, 0
	global_store_dwordx4 v203, v[40:43], s[98:99] offset:16 nt
	s_waitcnt vmcnt(17)
	v_pk_fma_f32 v[12:13], v[236:237], v[12:13], v[128:129]
	v_pk_fma_f32 v[14:15], v[238:239], v[14:15], v[130:131]
	s_add_u32 s42, s10, 0xa0200
	s_addc_u32 s43, s11, 0
	global_store_dwordx4 v203, v[12:15], s[42:43] nt
	s_waitcnt vmcnt(15)
	v_pk_fma_f32 v[8:9], v[132:133], v[8:9], v[136:137]
	v_pk_fma_f32 v[10:11], v[134:135], v[10:11], v[138:139]
	s_add_u32 s98, s10, 0xa0200
	s_addc_u32 s99, s11, 0
	global_store_dwordx4 v203, v[8:11], s[98:99] offset:16 nt
	s_waitcnt vmcnt(13)
	v_pk_fma_f32 v[36:37], v[140:141], v[36:37], v[144:145]
	v_pk_fma_f32 v[38:39], v[142:143], v[38:39], v[146:147]
	s_add_u32 s42, s10, 0xb0000
	s_addc_u32 s43, s11, 0
	global_store_dwordx4 v203, v[36:39], s[42:43] nt
	s_waitcnt vmcnt(11)
	v_pk_fma_f32 v[32:33], v[148:149], v[32:33], v[152:153]
	v_pk_fma_f32 v[34:35], v[150:151], v[34:35], v[154:155]
	s_add_u32 s98, s10, 0xb0000
	s_addc_u32 s99, s11, 0
	global_store_dwordx4 v203, v[32:35], s[98:99] offset:16 nt
	s_waitcnt vmcnt(9)
	v_pk_fma_f32 v[4:5], v[156:157], v[4:5], v[160:161]
	v_pk_fma_f32 v[6:7], v[158:159], v[6:7], v[162:163]
	s_add_u32 s42, s10, 0xb0200
	s_addc_u32 s43, s11, 0
	global_store_dwordx4 v203, v[4:7], s[42:43] nt
	s_waitcnt vmcnt(7)
	v_pk_fma_f32 v[0:1], v[164:165], v[0:1], v[168:169]
	v_pk_fma_f32 v[2:3], v[166:167], v[2:3], v[170:171]
	s_add_u32 s98, s10, 0xb0200
	s_addc_u32 s99, s11, 0
	global_store_dwordx4 v203, v[0:3], s[98:99] offset:16 nt
	s_branch .Lfs_predone
.Lfs_np1:
	s_add_u32 s42, s62, 0x0
	s_addc_u32 s43, s63, 0
	global_load_dwordx4 v[128:131], v205, s[42:43] sc0 sc1
	s_add_u32 s98, s62, 0x1000
	s_addc_u32 s99, s63, 0
	global_load_dwordx4 v[132:135], v205, s[98:99] sc0 sc1
	s_add_u32 s42, s62, 0x400
	s_addc_u32 s43, s63, 0
	global_load_dwordx4 v[136:139], v205, s[42:43] sc0 sc1
	s_add_u32 s98, s62, 0x1400
	s_addc_u32 s99, s63, 0
	global_load_dwordx4 v[140:143], v205, s[98:99] sc0 sc1
	s_add_u32 s42, s62, 0x800
	s_addc_u32 s43, s63, 0
	global_load_dwordx4 v[144:147], v205, s[42:43] sc0 sc1
	s_add_u32 s98, s62, 0x1800
	s_addc_u32 s99, s63, 0
	global_load_dwordx4 v[148:151], v205, s[98:99] sc0 sc1
	s_add_u32 s42, s62, 0xc00
	s_addc_u32 s43, s63, 0
	global_load_dwordx4 v[152:155], v205, s[42:43] sc0 sc1
	s_add_u32 s98, s62, 0x1c00
	s_addc_u32 s99, s63, 0
	global_load_dwordx4 v[156:159], v205, s[98:99] sc0 sc1
	s_add_u32 s42, s62, 0x2000
	s_addc_u32 s43, s63, 0
	global_load_dwordx4 v[160:163], v205, s[42:43] sc0 sc1
	s_add_u32 s98, s62, 0x3000
	s_addc_u32 s99, s63, 0
	global_load_dwordx4 v[164:167], v205, s[98:99] sc0 sc1
	s_add_u32 s42, s62, 0x2400
	s_addc_u32 s43, s63, 0
	global_load_dwordx4 v[168:171], v205, s[42:43] sc0 sc1
	s_add_u32 s98, s62, 0x3400
	s_addc_u32 s99, s63, 0
	global_load_dwordx4 v[172:175], v205, s[98:99] sc0 sc1
	s_add_u32 s42, s62, 0x2800
	s_addc_u32 s43, s63, 0
	global_load_dwordx4 v[176:179], v205, s[42:43] sc0 sc1
	s_add_u32 s98, s62, 0x3800
	s_addc_u32 s99, s63, 0
	global_load_dwordx4 v[180:183], v205, s[98:99] sc0 sc1
	s_add_u32 s42, s62, 0x2c00
	s_addc_u32 s43, s63, 0
	global_load_dwordx4 v[206:209], v205, s[42:43] sc0 sc1
	s_add_u32 s98, s62, 0x3c00
	s_addc_u32 s99, s63, 0
	global_load_dwordx4 v[210:213], v205, s[98:99] sc0 sc1
	s_add_u32 s42, s14, 0x0
	s_addc_u32 s43, s15, 0
	global_load_dwordx4 v[236:239], v235, s[42:43]
	s_waitcnt vmcnt(16)
	v_lshlrev_b32_e32 v240, 16, v128
	v_and_b32_e32 v241, 0xffff0000, v128
	v_pk_add_f32 v[124:125], v[124:125], v[240:241]
	v_lshlrev_b32_e32 v240, 16, v129
	v_and_b32_e32 v241, 0xffff0000, v129
	v_pk_add_f32 v[126:127], v[126:127], v[240:241]
	v_lshlrev_b32_e32 v240, 16, v130
	v_and_b32_e32 v241, 0xffff0000, v130
	v_pk_add_f32 v[120:121], v[120:121], v[240:241]
	v_lshlrev_b32_e32 v240, 16, v131
	v_and_b32_e32 v241, 0xffff0000, v131
	v_pk_add_f32 v[122:123], v[122:123], v[240:241]
	s_add_u32 s98, s10, 0x0
	s_addc_u32 s99, s11, 0
	global_load_dwordx4 v[128:131], v203, s[98:99]
	s_waitcnt vmcnt(16)
	v_lshlrev_b32_e32 v240, 16, v132
	v_and_b32_e32 v241, 0xffff0000, v132
	v_pk_add_f32 v[92:93], v[92:93], v[240:241]
	v_lshlrev_b32_e32 v240, 16, v133
	v_and_b32_e32 v241, 0xffff0000, v133
	v_pk_add_f32 v[94:95], v[94:95], v[240:241]
	v_lshlrev_b32_e32 v240, 16, v134
	v_and_b32_e32 v241, 0xffff0000, v134
	v_pk_add_f32 v[88:89], v[88:89], v[240:241]
	v_lshlrev_b32_e32 v240, 16, v135
	v_and_b32_e32 v241, 0xffff0000, v135
	v_pk_add_f32 v[90:91], v[90:91], v[240:241]
	s_add_u32 s42, s14, 0x0
	s_addc_u32 s43, s15, 0
	global_load_dwordx4 v[132:135], v235, s[42:43] offset:16
	s_waitcnt vmcnt(16)
	v_lshlrev_b32_e32 v240, 16, v136
	v_and_b32_e32 v241, 0xffff0000, v136
	v_pk_add_f32 v[116:117], v[116:117], v[240:241]
	v_lshlrev_b32_e32 v240, 16, v137
	v_and_b32_e32 v241, 0xffff0000, v137
	v_pk_add_f32 v[118:119], v[118:119], v[240:241]
	v_lshlrev_b32_e32 v240, 16, v138
	v_and_b32_e32 v241, 0xffff0000, v138
	v_pk_add_f32 v[112:113], v[112:113], v[240:241]
	v_lshlrev_b32_e32 v240, 16, v139
	v_and_b32_e32 v241, 0xffff0000, v139
	v_pk_add_f32 v[114:115], v[114:115], v[240:241]
	s_add_u32 s98, s10, 0x0
	s_addc_u32 s99, s11, 0
	global_load_dwordx4 v[136:139], v203, s[98:99] offset:16
	s_waitcnt vmcnt(16)
	v_lshlrev_b32_e32 v240, 16, v140
	v_and_b32_e32 v241, 0xffff0000, v140
	v_pk_add_f32 v[84:85], v[84:85], v[240:241]
	v_lshlrev_b32_e32 v240, 16, v141
	v_and_b32_e32 v241, 0xffff0000, v141
	v_pk_add_f32 v[86:87], v[86:87], v[240:241]
	v_lshlrev_b32_e32 v240, 16, v142
	v_and_b32_e32 v241, 0xffff0000, v142
	v_pk_add_f32 v[80:81], v[80:81], v[240:241]
	v_lshlrev_b32_e32 v240, 16, v143
	v_and_b32_e32 v241, 0xffff0000, v143
	v_pk_add_f32 v[82:83], v[82:83], v[240:241]
	s_add_u32 s42, s14, 0x200
	s_addc_u32 s43, s15, 0
	global_load_dwordx4 v[140:143], v235, s[42:43]
	s_waitcnt vmcnt(16)
	v_lshlrev_b32_e32 v240, 16, v144
	v_and_b32_e32 v241, 0xffff0000, v144
	v_pk_add_f32 v[108:109], v[108:109], v[240:241]
	v_lshlrev_b32_e32 v240, 16, v145
	v_and_b32_e32 v241, 0xffff0000, v145
	v_pk_add_f32 v[110:111], v[110:111], v[240:241]
	v_lshlrev_b32_e32 v240, 16, v146
	v_and_b32_e32 v241, 0xffff0000, v146
	v_pk_add_f32 v[104:105], v[104:105], v[240:241]
	v_lshlrev_b32_e32 v240, 16, v147
	v_and_b32_e32 v241, 0xffff0000, v147
	v_pk_add_f32 v[106:107], v[106:107], v[240:241]
	s_add_u32 s98, s10, 0x200
	s_addc_u32 s99, s11, 0
	global_load_dwordx4 v[144:147], v203, s[98:99]
	s_waitcnt vmcnt(16)
	v_lshlrev_b32_e32 v240, 16, v148
	v_and_b32_e32 v241, 0xffff0000, v148
	v_pk_add_f32 v[76:77], v[76:77], v[240:241]
	v_lshlrev_b32_e32 v240, 16, v149
	v_and_b32_e32 v241, 0xffff0000, v149
	v_pk_add_f32 v[78:79], v[78:79], v[240:241]
	v_lshlrev_b32_e32 v240, 16, v150
	v_and_b32_e32 v241, 0xffff0000, v150
	v_pk_add_f32 v[72:73], v[72:73], v[240:241]
	v_lshlrev_b32_e32 v240, 16, v151
	v_and_b32_e32 v241, 0xffff0000, v151
	v_pk_add_f32 v[74:75], v[74:75], v[240:241]
	s_add_u32 s42, s14, 0x200
	s_addc_u32 s43, s15, 0
	global_load_dwordx4 v[148:151], v235, s[42:43] offset:16
	s_waitcnt vmcnt(16)
	v_lshlrev_b32_e32 v240, 16, v152
	v_and_b32_e32 v241, 0xffff0000, v152
	v_pk_add_f32 v[100:101], v[100:101], v[240:241]
	v_lshlrev_b32_e32 v240, 16, v153
	v_and_b32_e32 v241, 0xffff0000, v153
	v_pk_add_f32 v[102:103], v[102:103], v[240:241]
	v_lshlrev_b32_e32 v240, 16, v154
	v_and_b32_e32 v241, 0xffff0000, v154
	v_pk_add_f32 v[96:97], v[96:97], v[240:241]
	v_lshlrev_b32_e32 v240, 16, v155
	v_and_b32_e32 v241, 0xffff0000, v155
	v_pk_add_f32 v[98:99], v[98:99], v[240:241]
	s_add_u32 s98, s10, 0x200
	s_addc_u32 s99, s11, 0
	global_load_dwordx4 v[152:155], v203, s[98:99] offset:16
	s_waitcnt vmcnt(16)
	v_lshlrev_b32_e32 v240, 16, v156
	v_and_b32_e32 v241, 0xffff0000, v156
	v_pk_add_f32 v[68:69], v[68:69], v[240:241]
	v_lshlrev_b32_e32 v240, 16, v157
	v_and_b32_e32 v241, 0xffff0000, v157
	v_pk_add_f32 v[70:71], v[70:71], v[240:241]
	v_lshlrev_b32_e32 v240, 16, v158
	v_and_b32_e32 v241, 0xffff0000, v158
	v_pk_add_f32 v[64:65], v[64:65], v[240:241]
	v_lshlrev_b32_e32 v240, 16, v159
	v_and_b32_e32 v241, 0xffff0000, v159
	v_pk_add_f32 v[66:67], v[66:67], v[240:241]
	s_add_u32 s42, s14, 0x18000
	s_addc_u32 s43, s15, 0
	global_load_dwordx4 v[156:159], v235, s[42:43]
	s_waitcnt vmcnt(16)
	v_lshlrev_b32_e32 v240, 16, v160
	v_and_b32_e32 v241, 0xffff0000, v160
	v_pk_add_f32 v[60:61], v[60:61], v[240:241]
	v_lshlrev_b32_e32 v240, 16, v161
	v_and_b32_e32 v241, 0xffff0000, v161
	v_pk_add_f32 v[62:63], v[62:63], v[240:241]
	v_lshlrev_b32_e32 v240, 16, v162
	v_and_b32_e32 v241, 0xffff0000, v162
	v_pk_add_f32 v[56:57], v[56:57], v[240:241]
	v_lshlrev_b32_e32 v240, 16, v163
	v_and_b32_e32 v241, 0xffff0000, v163
	v_pk_add_f32 v[58:59], v[58:59], v[240:241]
	s_add_u32 s98, s10, 0x10000
	s_addc_u32 s99, s11, 0
	global_load_dwordx4 v[160:163], v203, s[98:99]
	s_waitcnt vmcnt(16)
	v_lshlrev_b32_e32 v240, 16, v164
	v_and_b32_e32 v241, 0xffff0000, v164
	v_pk_add_f32 v[28:29], v[28:29], v[240:241]
	v_lshlrev_b32_e32 v240, 16, v165
	v_and_b32_e32 v241, 0xffff0000, v165
	v_pk_add_f32 v[30:31], v[30:31], v[240:241]
	v_lshlrev_b32_e32 v240, 16, v166
	v_and_b32_e32 v241, 0xffff0000, v166
	v_pk_add_f32 v[24:25], v[24:25], v[240:241]
	v_lshlrev_b32_e32 v240, 16, v167
	v_and_b32_e32 v241, 0xffff0000, v167
	v_pk_add_f32 v[26:27], v[26:27], v[240:241]
	s_add_u32 s42, s14, 0x18000
	s_addc_u32 s43, s15, 0
	global_load_dwordx4 v[164:167], v235, s[42:43] offset:16
	s_waitcnt vmcnt(16)
	v_lshlrev_b32_e32 v240, 16, v168
	v_and_b32_e32 v241, 0xffff0000, v168
	v_pk_add_f32 v[52:53], v[52:53], v[240:241]
	v_lshlrev_b32_e32 v240, 16, v169
	v_and_b32_e32 v241, 0xffff0000, v169
	v_pk_add_f32 v[54:55], v[54:55], v[240:241]
	v_lshlrev_b32_e32 v240, 16, v170
	v_and_b32_e32 v241, 0xffff0000, v170
	v_pk_add_f32 v[48:49], v[48:49], v[240:241]
	v_lshlrev_b32_e32 v240, 16, v171
	v_and_b32_e32 v241, 0xffff0000, v171
	v_pk_add_f32 v[50:51], v[50:51], v[240:241]
	s_add_u32 s98, s10, 0x10000
	s_addc_u32 s99, s11, 0
	global_load_dwordx4 v[168:171], v203, s[98:99] offset:16
	s_waitcnt vmcnt(16)
	v_lshlrev_b32_e32 v240, 16, v172
	v_and_b32_e32 v241, 0xffff0000, v172
	v_pk_add_f32 v[20:21], v[20:21], v[240:241]
	v_lshlrev_b32_e32 v240, 16, v173
	v_and_b32_e32 v241, 0xffff0000, v173
	v_pk_add_f32 v[22:23], v[22:23], v[240:241]
	v_lshlrev_b32_e32 v240, 16, v174
	v_and_b32_e32 v241, 0xffff0000, v174
	v_pk_add_f32 v[16:17], v[16:17], v[240:241]
	v_lshlrev_b32_e32 v240, 16, v175
	v_and_b32_e32 v241, 0xffff0000, v175
	v_pk_add_f32 v[18:19], v[18:19], v[240:241]
	s_add_u32 s42, s14, 0x18200
	s_addc_u32 s43, s15, 0
	global_load_dwordx4 v[172:175], v235, s[42:43]
	s_waitcnt vmcnt(16)
	v_lshlrev_b32_e32 v240, 16, v176
	v_and_b32_e32 v241, 0xffff0000, v176
	v_pk_add_f32 v[44:45], v[44:45], v[240:241]
	v_lshlrev_b32_e32 v240, 16, v177
	v_and_b32_e32 v241, 0xffff0000, v177
	v_pk_add_f32 v[46:47], v[46:47], v[240:241]
	v_lshlrev_b32_e32 v240, 16, v178
	v_and_b32_e32 v241, 0xffff0000, v178
	v_pk_add_f32 v[40:41], v[40:41], v[240:241]
	v_lshlrev_b32_e32 v240, 16, v179
	v_and_b32_e32 v241, 0xffff0000, v179
	v_pk_add_f32 v[42:43], v[42:43], v[240:241]
	s_add_u32 s98, s10, 0x10200
	s_addc_u32 s99, s11, 0
	global_load_dwordx4 v[176:179], v203, s[98:99]
	s_waitcnt vmcnt(16)
	v_lshlrev_b32_e32 v240, 16, v180
	v_and_b32_e32 v241, 0xffff0000, v180
	v_pk_add_f32 v[12:13], v[12:13], v[240:241]
	v_lshlrev_b32_e32 v240, 16, v181
	v_and_b32_e32 v241, 0xffff0000, v181
	v_pk_add_f32 v[14:15], v[14:15], v[240:241]
	v_lshlrev_b32_e32 v240, 16, v182
	v_and_b32_e32 v241, 0xffff0000, v182
	v_pk_add_f32 v[8:9], v[8:9], v[240:241]
	v_lshlrev_b32_e32 v240, 16, v183
	v_and_b32_e32 v241, 0xffff0000, v183
	v_pk_add_f32 v[10:11], v[10:11], v[240:241]
	s_add_u32 s42, s14, 0x18200
	s_addc_u32 s43, s15, 0
	global_load_dwordx4 v[180:183], v235, s[42:43] offset:16
	s_waitcnt vmcnt(16)
	v_lshlrev_b32_e32 v240, 16, v206
	v_and_b32_e32 v241, 0xffff0000, v206
	v_pk_add_f32 v[36:37], v[36:37], v[240:241]
	v_lshlrev_b32_e32 v240, 16, v207
	v_and_b32_e32 v241, 0xffff0000, v207
	v_pk_add_f32 v[38:39], v[38:39], v[240:241]
	v_lshlrev_b32_e32 v240, 16, v208
	v_and_b32_e32 v241, 0xffff0000, v208
	v_pk_add_f32 v[32:33], v[32:33], v[240:241]
	v_lshlrev_b32_e32 v240, 16, v209
	v_and_b32_e32 v241, 0xffff0000, v209
	v_pk_add_f32 v[34:35], v[34:35], v[240:241]
	s_add_u32 s98, s10, 0x10200
	s_addc_u32 s99, s11, 0
	global_load_dwordx4 v[206:209], v203, s[98:99] offset:16
	s_waitcnt vmcnt(16)
	v_lshlrev_b32_e32 v240, 16, v210
	v_and_b32_e32 v241, 0xffff0000, v210
	v_pk_add_f32 v[4:5], v[4:5], v[240:241]
	v_lshlrev_b32_e32 v240, 16, v211
	v_and_b32_e32 v241, 0xffff0000, v211
	v_pk_add_f32 v[6:7], v[6:7], v[240:241]
	v_lshlrev_b32_e32 v240, 16, v212
	v_and_b32_e32 v241, 0xffff0000, v212
	v_pk_add_f32 v[0:1], v[0:1], v[240:241]
	v_lshlrev_b32_e32 v240, 16, v213
	v_and_b32_e32 v241, 0xffff0000, v213
	v_pk_add_f32 v[2:3], v[2:3], v[240:241]
	s_add_u32 s42, s14, 0x30000
	s_addc_u32 s43, s15, 0
	global_load_dwordx4 v[210:213], v235, s[42:43]
	s_waitcnt vmcnt(15)
	v_pk_fma_f32 v[124:125], v[236:237], v[124:125], v[128:129]
	v_pk_fma_f32 v[126:127], v[238:239], v[126:127], v[130:131]
	s_add_u32 s98, s10, 0x0
	s_addc_u32 s99, s11, 0
	global_store_dwordx4 v203, v[124:127], s[98:99] nt
	s_add_u32 s42, s10, 0x20000
	s_addc_u32 s43, s11, 0
	global_load_dwordx4 v[236:239], v203, s[42:43]
	s_add_u32 s98, s14, 0x30000
	s_addc_u32 s99, s15, 0
	global_load_dwordx4 v[128:131], v235, s[98:99] offset:16
	s_waitcnt vmcnt(16)
	v_pk_fma_f32 v[120:121], v[132:133], v[120:121], v[136:137]
	v_pk_fma_f32 v[122:123], v[134:135], v[122:123], v[138:139]
	s_add_u32 s42, s10, 0x0
	s_addc_u32 s43, s11, 0
	global_store_dwordx4 v203, v[120:123], s[42:43] offset:16 nt
	s_add_u32 s98, s10, 0x20000
	s_addc_u32 s99, s11, 0
	global_load_dwordx4 v[132:135], v203, s[98:99] offset:16
	s_add_u32 s42, s14, 0x30200
	s_addc_u32 s43, s15, 0
	global_load_dwordx4 v[136:139], v235, s[42:43]
	s_waitcnt vmcnt(17)
	v_pk_fma_f32 v[92:93], v[140:141], v[92:93], v[144:145]
	v_pk_fma_f32 v[94:95], v[142:143], v[94:95], v[146:147]
	s_add_u32 s98, s10, 0x200
	s_addc_u32 s99, s11, 0
	global_store_dwordx4 v203, v[92:95], s[98:99] nt
	s_add_u32 s42, s10, 0x20200
	s_addc_u32 s43, s11, 0
	global_load_dwordx4 v[140:143], v203, s[42:43]
	s_add_u32 s98, s14, 0x30200
	s_addc_u32 s99, s15, 0
	global_load_dwordx4 v[144:147], v235, s[98:99] offset:16
	s_waitcnt vmcnt(18)
	v_pk_fma_f32 v[88:89], v[148:149], v[88:89], v[152:153]
	v_pk_fma_f32 v[90:91], v[150:151], v[90:91], v[154:155]
	s_add_u32 s42, s10, 0x200
	s_addc_u32 s43, s11, 0
	global_store_dwordx4 v203, v[88:91], s[42:43] offset:16 nt
	s_add_u32 s98, s10, 0x20200
	s_addc_u32 s99, s11, 0
	global_load_dwordx4 v[148:151], v203, s[98:99] offset:16
	s_add_u32 s42, s14, 0x48000
	s_addc_u32 s43, s15, 0
	global_load_dwordx4 v[152:155], v235, s[42:43]
	s_waitcnt vmcnt(19)
	v_pk_fma_f32 v[116:117], v[156:157], v[116:117], v[160:161]
	v_pk_fma_f32 v[118:119], v[158:159], v[118:119], v[162:163]
	s_add_u32 s98, s10, 0x10000
	s_addc_u32 s99, s11, 0
	global_store_dwordx4 v203, v[116:119], s[98:99] nt
	s_add_u32 s42, s10, 0x30000
	s_addc_u32 s43, s11, 0
	global_load_dwordx4 v[156:159], v203, s[42:43]
	s_add_u32 s98, s14, 0x48000
	s_addc_u32 s99, s15, 0
	global_load_dwordx4 v[160:163], v235, s[98:99] offset:16
	s_waitcnt vmcnt(20)
	v_pk_fma_f32 v[112:113], v[164:165], v[112:113], v[168:169]
	v_pk_fma_f32 v[114:115], v[166:167], v[114:115], v[170:171]
	s_add_u32 s42, s10, 0x10000
	s_addc_u32 s43, s11, 0
	global_store_dwordx4 v203, v[112:115], s[42:43] offset:16 nt
	s_add_u32 s98, s10, 0x30000
	s_addc_u32 s99, s11, 0
	global_load_dwordx4 v[164:167], v203, s[98:99] offset:16
	s_add_u32 s42, s14, 0x48200
	s_addc_u32 s43, s15, 0
	global_load_dwordx4 v[168:171], v235, s[42:43]
	s_waitcnt vmcnt(21)
	v_pk_fma_f32 v[84:85], v[172:173], v[84:85], v[176:177]
	v_pk_fma_f32 v[86:87], v[174:175], v[86:87], v[178:179]
	s_add_u32 s98, s10, 0x10200
	s_addc_u32 s99, s11, 0
	global_store_dwordx4 v203, v[84:87], s[98:99] nt
	s_add_u32 s42, s10, 0x30200
	s_addc_u32 s43, s11, 0
	global_load_dwordx4 v[172:175], v203, s[42:43]
	s_add_u32 s98, s14, 0x48200
	s_addc_u32 s99, s15, 0
	global_load_dwordx4 v[176:179], v235, s[98:99] offset:16
	s_waitcnt vmcnt(22)
	v_pk_fma_f32 v[80:81], v[180:181], v[80:81], v[206:207]
	v_pk_fma_f32 v[82:83], v[182:183], v[82:83], v[208:209]
	s_add_u32 s42, s10, 0x10200
	s_addc_u32 s43, s11, 0
	global_store_dwordx4 v203, v[80:83], s[42:43] offset:16 nt
	s_add_u32 s98, s10, 0x30200
	s_addc_u32 s99, s11, 0
	global_load_dwordx4 v[180:183], v203, s[98:99] offset:16
	s_add_u32 s42, s14, 0xc0000
	s_addc_u32 s43, s15, 0
	global_load_dwordx4 v[206:209], v235, s[42:43]
	s_waitcnt vmcnt(22)
	v_pk_fma_f32 v[108:109], v[210:211], v[108:109], v[236:237]
	v_pk_fma_f32 v[110:111], v[212:213], v[110:111], v[238:239]
	s_add_u32 s98, s10, 0x20000
	s_addc_u32 s99, s11, 0
	global_store_dwordx4 v203, v[108:111], s[98:99] nt
	s_add_u32 s42, s10, 0x80000
	s_addc_u32 s43, s11, 0
	global_load_dwordx4 v[210:213], v203, s[42:43]
	s_add_u32 s98, s14, 0xc0000
	s_addc_u32 s99, s15, 0
	global_load_dwordx4 v[236:239], v235, s[98:99] offset:16
	s_waitcnt vmcnt(22)
	v_pk_fma_f32 v[104:105], v[128:129], v[104:105], v[132:133]
	v_pk_fma_f32 v[106:107], v[130:131], v[106:107], v[134:135]
	s_add_u32 s42, s10, 0x20000
	s_addc_u32 s43, s11, 0
	global_store_dwordx4 v203, v[104:107], s[42:43] offset:16 nt
	s_add_u32 s98, s10, 0x80000
	s_addc_u32 s99, s11, 0
	global_load_dwordx4 v[128:131], v203, s[98:99] offset:16
	s_add_u32 s42, s14, 0xc0200
	s_addc_u32 s43, s15, 0
	global_load_dwordx4 v[132:135], v235, s[42:43]
	s_waitcnt vmcnt(22)
	v_pk_fma_f32 v[76:77], v[136:137], v[76:77], v[140:141]
	v_pk_fma_f32 v[78:79], v[138:139], v[78:79], v[142:143]
	s_add_u32 s98, s10, 0x20200
	s_addc_u32 s99, s11, 0
	global_store_dwordx4 v203, v[76:79], s[98:99] nt
	s_add_u32 s42, s10, 0x80200
	s_addc_u32 s43, s11, 0
	global_load_dwordx4 v[136:139], v203, s[42:43]
	s_add_u32 s98, s14, 0xc0200
	s_addc_u32 s99, s15, 0
	global_load_dwordx4 v[140:143], v235, s[98:99] offset:16
	s_waitcnt vmcnt(22)
	v_pk_fma_f32 v[72:73], v[144:145], v[72:73], v[148:149]
	v_pk_fma_f32 v[74:75], v[146:147], v[74:75], v[150:151]
	s_add_u32 s42, s10, 0x20200
	s_addc_u32 s43, s11, 0
	global_store_dwordx4 v203, v[72:75], s[42:43] offset:16 nt
	s_add_u32 s98, s10, 0x80200
	s_addc_u32 s99, s11, 0
	global_load_dwordx4 v[144:147], v203, s[98:99] offset:16
	s_add_u32 s42, s14, 0xd8000
	s_addc_u32 s43, s15, 0
	global_load_dwordx4 v[148:151], v235, s[42:43]
	s_waitcnt vmcnt(22)
	v_pk_fma_f32 v[100:101], v[152:153], v[100:101], v[156:157]
	v_pk_fma_f32 v[102:103], v[154:155], v[102:103], v[158:159]
	s_add_u32 s98, s10, 0x30000
	s_addc_u32 s99, s11, 0
	global_store_dwordx4 v203, v[100:103], s[98:99] nt
	s_add_u32 s42, s10, 0x90000
	s_addc_u32 s43, s11, 0
	global_load_dwordx4 v[152:155], v203, s[42:43]
	s_add_u32 s98, s14, 0xd8000
	s_addc_u32 s99, s15, 0
	global_load_dwordx4 v[156:159], v235, s[98:99] offset:16
	s_waitcnt vmcnt(22)
	v_pk_fma_f32 v[96:97], v[160:161], v[96:97], v[164:165]
	v_pk_fma_f32 v[98:99], v[162:163], v[98:99], v[166:167]
	s_add_u32 s42, s10, 0x30000
	s_addc_u32 s43, s11, 0
	global_store_dwordx4 v203, v[96:99], s[42:43] offset:16 nt
	s_add_u32 s98, s10, 0x90000
	s_addc_u32 s99, s11, 0
	global_load_dwordx4 v[160:163], v203, s[98:99] offset:16
	s_add_u32 s42, s14, 0xd8200
	s_addc_u32 s43, s15, 0
	global_load_dwordx4 v[164:167], v235, s[42:43]
	s_waitcnt vmcnt(22)
	v_pk_fma_f32 v[68:69], v[168:169], v[68:69], v[172:173]
	v_pk_fma_f32 v[70:71], v[170:171], v[70:71], v[174:175]
	s_add_u32 s98, s10, 0x30200
	s_addc_u32 s99, s11, 0
	global_store_dwordx4 v203, v[68:71], s[98:99] nt
	s_add_u32 s42, s10, 0x90200
	s_addc_u32 s43, s11, 0
	global_load_dwordx4 v[168:171], v203, s[42:43]
	s_add_u32 s98, s14, 0xd8200
	s_addc_u32 s99, s15, 0
	global_load_dwordx4 v[172:175], v235, s[98:99] offset:16
	s_waitcnt vmcnt(22)
	v_pk_fma_f32 v[64:65], v[176:177], v[64:65], v[180:181]
	v_pk_fma_f32 v[66:67], v[178:179], v[66:67], v[182:183]
	s_add_u32 s42, s10, 0x30200
	s_addc_u32 s43, s11, 0
	global_store_dwordx4 v203, v[64:67], s[42:43] offset:16 nt
	s_add_u32 s98, s10, 0x90200
	s_addc_u32 s99, s11, 0
	global_load_dwordx4 v[176:179], v203, s[98:99] offset:16
	s_add_u32 s42, s14, 0xf0000
	s_addc_u32 s43, s15, 0
	global_load_dwordx4 v[180:183], v235, s[42:43]
	s_waitcnt vmcnt(22)
	v_pk_fma_f32 v[60:61], v[206:207], v[60:61], v[210:211]
	v_pk_fma_f32 v[62:63], v[208:209], v[62:63], v[212:213]
	s_add_u32 s98, s10, 0x80000
	s_addc_u32 s99, s11, 0
	global_store_dwordx4 v203, v[60:63], s[98:99] nt
	s_add_u32 s42, s10, 0xa0000
	s_addc_u32 s43, s11, 0
	global_load_dwordx4 v[206:209], v203, s[42:43]
	s_add_u32 s98, s14, 0xf0000
	s_addc_u32 s99, s15, 0
	global_load_dwordx4 v[210:213], v235, s[98:99] offset:16
	s_waitcnt vmcnt(22)
	v_pk_fma_f32 v[56:57], v[236:237], v[56:57], v[128:129]
	v_pk_fma_f32 v[58:59], v[238:239], v[58:59], v[130:131]
	s_add_u32 s42, s10, 0x80000
	s_addc_u32 s43, s11, 0
	global_store_dwordx4 v203, v[56:59], s[42:43] offset:16 nt
	s_add_u32 s98, s10, 0xa0000
	s_addc_u32 s99, s11, 0
	global_load_dwordx4 v[236:239], v203, s[98:99] offset:16
	s_add_u32 s42, s14, 0xf0200
	s_addc_u32 s43, s15, 0
	global_load_dwordx4 v[128:131], v235, s[42:43]
	s_waitcnt vmcnt(22)
	v_pk_fma_f32 v[28:29], v[132:133], v[28:29], v[136:137]
	v_pk_fma_f32 v[30:31], v[134:135], v[30:31], v[138:139]
	s_add_u32 s98, s10, 0x80200
	s_addc_u32 s99, s11, 0
	global_store_dwordx4 v203, v[28:31], s[98:99] nt
	s_add_u32 s42, s10, 0xa0200
	s_addc_u32 s43, s11, 0
	global_load_dwordx4 v[132:135], v203, s[42:43]
	s_add_u32 s98, s14, 0xf0200
	s_addc_u32 s99, s15, 0
	global_load_dwordx4 v[136:139], v235, s[98:99] offset:16
	s_waitcnt vmcnt(22)
	v_pk_fma_f32 v[24:25], v[140:141], v[24:25], v[144:145]
	v_pk_fma_f32 v[26:27], v[142:143], v[26:27], v[146:147]
	s_add_u32 s42, s10, 0x80200
	s_addc_u32 s43, s11, 0
	global_store_dwordx4 v203, v[24:27], s[42:43] offset:16 nt
	s_add_u32 s98, s10, 0xa0200
	s_addc_u32 s99, s11, 0
	global_load_dwordx4 v[140:143], v203, s[98:99] offset:16
	s_add_u32 s42, s14, 0x108000
	s_addc_u32 s43, s15, 0
	global_load_dwordx4 v[144:147], v235, s[42:43]
	s_waitcnt vmcnt(22)
	v_pk_fma_f32 v[52:53], v[148:149], v[52:53], v[152:153]
	v_pk_fma_f32 v[54:55], v[150:151], v[54:55], v[154:155]
	s_add_u32 s98, s10, 0x90000
	s_addc_u32 s99, s11, 0
	global_store_dwordx4 v203, v[52:55], s[98:99] nt
	s_add_u32 s42, s10, 0xb0000
	s_addc_u32 s43, s11, 0
	global_load_dwordx4 v[148:151], v203, s[42:43]
	s_add_u32 s98, s14, 0x108000
	s_addc_u32 s99, s15, 0
	global_load_dwordx4 v[152:155], v235, s[98:99] offset:16
	s_waitcnt vmcnt(22)
	v_pk_fma_f32 v[48:49], v[156:157], v[48:49], v[160:161]
	v_pk_fma_f32 v[50:51], v[158:159], v[50:51], v[162:163]
	s_add_u32 s42, s10, 0x90000
	s_addc_u32 s43, s11, 0
	global_store_dwordx4 v203, v[48:51], s[42:43] offset:16 nt
	s_add_u32 s98, s10, 0xb0000
	s_addc_u32 s99, s11, 0
	global_load_dwordx4 v[156:159], v203, s[98:99] offset:16
	s_add_u32 s42, s14, 0x108200
	s_addc_u32 s43, s15, 0
	global_load_dwordx4 v[160:163], v235, s[42:43]
	s_waitcnt vmcnt(22)
	v_pk_fma_f32 v[20:21], v[164:165], v[20:21], v[168:169]
	v_pk_fma_f32 v[22:23], v[166:167], v[22:23], v[170:171]
	s_add_u32 s98, s10, 0x90200
	s_addc_u32 s99, s11, 0
	global_store_dwordx4 v203, v[20:23], s[98:99] nt
	s_add_u32 s42, s10, 0xb0200
	s_addc_u32 s43, s11, 0
	global_load_dwordx4 v[164:167], v203, s[42:43]
	s_add_u32 s98, s14, 0x108200
	s_addc_u32 s99, s15, 0
	global_load_dwordx4 v[168:171], v235, s[98:99] offset:16
	s_waitcnt vmcnt(22)
	v_pk_fma_f32 v[16:17], v[172:173], v[16:17], v[176:177]
	v_pk_fma_f32 v[18:19], v[174:175], v[18:19], v[178:179]
	s_add_u32 s42, s10, 0x90200
	s_addc_u32 s43, s11, 0
	global_store_dwordx4 v203, v[16:19], s[42:43] offset:16 nt
	s_add_u32 s98, s10, 0xb0200
	s_addc_u32 s99, s11, 0
	global_load_dwordx4 v[172:175], v203, s[98:99] offset:16
	s_waitcnt vmcnt(21)
	v_pk_fma_f32 v[44:45], v[180:181], v[44:45], v[206:207]
	v_pk_fma_f32 v[46:47], v[182:183], v[46:47], v[208:209]
	s_add_u32 s42, s10, 0xa0000
	s_addc_u32 s43, s11, 0
	global_store_dwordx4 v203, v[44:47], s[42:43] nt
	s_waitcnt vmcnt(19)
	v_pk_fma_f32 v[40:41], v[210:211], v[40:41], v[236:237]
	v_pk_fma_f32 v[42:43], v[212:213], v[42:43], v[238:239]
	s_add_u32 s98, s10, 0xa0000
	s_addc_u32 s99, s11, 0
	global_store_dwordx4 v203, v[40:43], s[98:99] offset:16 nt
	s_waitcnt vmcnt(17)
	v_pk_fma_f32 v[12:13], v[128:129], v[12:13], v[132:133]
	v_pk_fma_f32 v[14:15], v[130:131], v[14:15], v[134:135]
	s_add_u32 s42, s10, 0xa0200
	s_addc_u32 s43, s11, 0
	global_store_dwordx4 v203, v[12:15], s[42:43] nt
	s_waitcnt vmcnt(15)
	v_pk_fma_f32 v[8:9], v[136:137], v[8:9], v[140:141]
	v_pk_fma_f32 v[10:11], v[138:139], v[10:11], v[142:143]
	s_add_u32 s98, s10, 0xa0200
	s_addc_u32 s99, s11, 0
	global_store_dwordx4 v203, v[8:11], s[98:99] offset:16 nt
	s_waitcnt vmcnt(13)
	v_pk_fma_f32 v[36:37], v[144:145], v[36:37], v[148:149]
	v_pk_fma_f32 v[38:39], v[146:147], v[38:39], v[150:151]
	s_add_u32 s42, s10, 0xb0000
	s_addc_u32 s43, s11, 0
	global_store_dwordx4 v203, v[36:39], s[42:43] nt
	s_waitcnt vmcnt(11)
	v_pk_fma_f32 v[32:33], v[152:153], v[32:33], v[156:157]
	v_pk_fma_f32 v[34:35], v[154:155], v[34:35], v[158:159]
	s_add_u32 s98, s10, 0xb0000
	s_addc_u32 s99, s11, 0
	global_store_dwordx4 v203, v[32:35], s[98:99] offset:16 nt
	s_waitcnt vmcnt(9)
	v_pk_fma_f32 v[4:5], v[160:161], v[4:5], v[164:165]
	v_pk_fma_f32 v[6:7], v[162:163], v[6:7], v[166:167]
	s_add_u32 s42, s10, 0xb0200
	s_addc_u32 s43, s11, 0
	global_store_dwordx4 v203, v[4:7], s[42:43] nt
	s_waitcnt vmcnt(7)
	v_pk_fma_f32 v[0:1], v[168:169], v[0:1], v[172:173]
	v_pk_fma_f32 v[2:3], v[170:171], v[2:3], v[174:175]
	s_add_u32 s98, s10, 0xb0200
	s_addc_u32 s99, s11, 0
	global_store_dwordx4 v203, v[0:3], s[98:99] offset:16 nt

.Lfs_LBB0_1428:
	v_ashrrev_i32_e32 v203, 31, v202
	v_lshlrev_b64 v[206:207], 10, v[202:203]
	s_waitcnt vmcnt(0)
	s_and_b64 vcc, exec, s[80:81]
	s_cbranch_vccnz .Lfs_LBB0_1430
	v_lshl_add_u64 v[172:173], v[206:207], 1, s[18:19]
	v_mul_f32_e32 v174, v140, v160
	v_mul_f32_e32 v175, v141, v161
	v_cvt_pk_bf16_f32 v168, v174, v175
	v_mul_f32_e32 v178, v142, v162
	v_mul_f32_e32 v179, v143, v163
	v_cvt_pk_bf16_f32 v169, v178, v179
	v_lshl_add_u64 v[172:173], v[200:201], 1, v[172:173]
	v_mul_f32_e32 v180, v136, v164
	v_mul_f32_e32 v181, v137, v165
	v_cvt_pk_bf16_f32 v170, v180, v181
	v_mul_f32_e32 v182, v138, v166
	v_mul_f32_e32 v183, v139, v167
	v_cvt_pk_bf16_f32 v171, v182, v183
	global_store_dwordx4 v[172:173], v[168:171], off nt
	s_nop 1
	v_mov_b32_e32 v168, v185
	v_mov_b32_e32 v169, v185
	v_cvt_pk_fp8_f32 v168, v174, v175
	v_cvt_pk_fp8_f32 v169, v180, v181
	v_lshl_add_u64 v[170:171], s[70:71], 0, v[206:207]
	v_lshl_add_u64 v[170:171], v[170:171], 0, v[200:201]
	v_cvt_pk_fp8_f32 v168, v178, v179 op_sel:[0,0,1]
	v_cvt_pk_fp8_f32 v169, v182, v183 op_sel:[0,0,1]
	global_store_dwordx2 v[170:171], v[168:169], off nt

.Lfs_LBB0_1561:
	v_ashrrev_i32_e32 v177, 31, v176
	v_lshlrev_b64 v[180:181], 10, v[176:177]
	s_waitcnt vmcnt(0)
	v_mov_b64_e32 v[150:151], v[38:39]
	v_mov_b64_e32 v[148:149], v[36:37]
	v_mov_b64_e32 v[146:147], v[34:35]
	v_mov_b64_e32 v[144:145], v[32:33]
	s_and_b64 vcc, exec, s[80:81]
	s_cbranch_vccnz .Lfs_LBB0_1563
	v_mul_f32_e32 v160, v140, v148
	v_mul_f32_e32 v161, v141, v149
	v_mul_f32_e32 v164, v136, v144
	v_mul_f32_e32 v165, v137, v145
	v_mov_b32_e32 v136, v185
	v_mov_b32_e32 v137, v185
	v_cvt_pk_fp8_f32 v136, v160, v161
	v_cvt_pk_fp8_f32 v137, v164, v165
	v_mul_f32_e32 v162, v142, v150
	v_mul_f32_e32 v163, v143, v151
	v_mul_f32_e32 v166, v138, v146
	v_mul_f32_e32 v167, v139, v147
	v_lshl_add_u64 v[138:139], v[180:181], 1, s[18:19]
	v_cvt_pk_fp8_f32 v136, v162, v163 op_sel:[0,0,1]
	v_cvt_pk_fp8_f32 v137, v166, v167 op_sel:[0,0,1]
	v_lshl_add_u64 v[138:139], v[200:201], 1, v[138:139]
	v_cvt_pk_bf16_f32 v140, v160, v161
	v_cvt_pk_bf16_f32 v141, v162, v163
	v_cvt_pk_bf16_f32 v142, v164, v165
	v_cvt_pk_bf16_f32 v143, v166, v167
	global_store_dwordx4 v[138:139], v[140:143], off nt
	v_lshl_add_u64 v[138:139], s[70:71], 0, v[180:181]
	v_lshl_add_u64 v[138:139], v[138:139], 0, v[200:201]
	global_store_dwordx2 v[138:139], v[136:137], off nt
